# GEMM k-loops: end-of-step LDS-release barrier moved up to right after the last fragment read lands, trailing 13 MFMAs run after it
# baseline (speedup 1.0000x reference)
.LBB0_276:
	s_waitcnt vmcnt(5)
	ds_write_b128 v158, v[80:83]
	s_waitcnt vmcnt(3)
	ds_write_b128 v158, v[116:119] offset:6144
	s_waitcnt vmcnt(3)
	ds_write_b128 v158, v[88:91] offset:12288
	s_waitcnt vmcnt(2)
	ds_write_b128 v158, v[124:127] offset:18432
	s_waitcnt vmcnt(1)
	ds_write_b128 v158, v[128:131] offset:24576
	s_waitcnt vmcnt(0)
	ds_write_b128 v158, v[132:135] offset:30720
	s_waitcnt lgkmcnt(0)
	s_barrier
	ds_read_b128 v[116:119], v179 offset:12288
	ds_read_b128 v[124:127], v179 offset:13824
	ds_read_b128 v[182:185], v159
	ds_read_b128 v[200:203], v159 offset:1536
	ds_read_b128 v[132:135], v179 offset:15360
	ds_read_b128 v[204:207], v179 offset:16896
	v_lshl_add_u64 v[88:89], v[168:169], 0, s[0:1]
	v_add_co_u32_e32 v130, vcc, s69, v88
	v_lshl_add_u64 v[128:129], v[170:171], 0, s[0:1]
	s_nop 0
	v_addc_co_u32_e32 v131, vcc, 0, v89, vcc
	ds_read_b128 v[208:211], v159 offset:3072
	ds_read_b128 v[212:215], v159 offset:4608
	v_add_co_u32_e32 v186, vcc, s69, v128
	s_waitcnt lgkmcnt(5)
	v_mfma_f32_16x16x32_bf16 v[148:151], v[116:119], v[182:185], v[148:151]
	v_addc_co_u32_e32 v187, vcc, 0, v129, vcc
	v_add_co_u32_e32 v216, vcc, s70, v128
	v_mfma_f32_16x16x32_bf16 v[144:147], v[124:127], v[182:185], v[144:147]
	s_nop 0
	v_addc_co_u32_e32 v217, vcc, 0, v129, vcc
	v_add_co_u32_e32 v218, vcc, s71, v128
	s_waitcnt lgkmcnt(4)
	v_mfma_f32_16x16x32_bf16 v[120:123], v[116:119], v[200:203], v[120:123]
	global_load_dwordx4 v[80:83], v[88:89], off offset:64
	v_addc_co_u32_e32 v219, vcc, 0, v129, vcc
	v_mfma_f32_16x16x32_bf16 v[112:115], v[124:127], v[200:203], v[112:115]
	global_load_dwordx4 v[88:91], v[128:129], off offset:64
	s_waitcnt lgkmcnt(1)
	v_mfma_f32_16x16x32_bf16 v[76:79], v[116:119], v[208:211], v[76:79]
	v_mfma_f32_16x16x32_bf16 v[72:75], v[124:127], v[208:211], v[72:75]
	s_waitcnt lgkmcnt(0)
	v_mfma_f32_16x16x32_bf16 v[44:47], v[116:119], v[212:215], v[44:47]
	v_mfma_f32_16x16x32_bf16 v[40:43], v[124:127], v[212:215], v[40:43]
	global_load_dwordx4 v[116:119], v[130:131], off offset:64
	global_load_dwordx4 v[124:127], v[186:187], off offset:64
	s_nop 0
	global_load_dwordx4 v[128:131], v[216:217], off offset:64
	v_mfma_f32_16x16x32_bf16 v[140:143], v[132:135], v[182:185], v[140:143]
	v_mfma_f32_16x16x32_bf16 v[104:107], v[132:135], v[200:203], v[104:107]
	v_mfma_f32_16x16x32_bf16 v[64:67], v[132:135], v[208:211], v[64:67]
	v_mfma_f32_16x16x32_bf16 v[32:35], v[132:135], v[212:215], v[32:35]
	global_load_dwordx4 v[132:135], v[218:219], off offset:64
	v_mfma_f32_16x16x32_bf16 v[136:139], v[204:207], v[182:185], v[136:139]
	v_mfma_f32_16x16x32_bf16 v[96:99], v[204:207], v[200:203], v[96:99]
	v_mfma_f32_16x16x32_bf16 v[56:59], v[204:207], v[208:211], v[56:59]
	v_mfma_f32_16x16x32_bf16 v[24:27], v[204:207], v[212:215], v[24:27]
	ds_read_b128 v[204:207], v179 offset:18432
	ds_read_b128 v[216:219], v179 offset:19968
	ds_read_b128 v[220:223], v179 offset:21504
	ds_read_b128 v[224:227], v179 offset:23040
	s_waitcnt lgkmcnt(3)
	v_mfma_f32_16x16x32_bf16 v[108:111], v[204:207], v[182:185], v[108:111]
	s_waitcnt lgkmcnt(2)
	v_mfma_f32_16x16x32_bf16 v[100:103], v[216:219], v[182:185], v[100:103]
	s_waitcnt lgkmcnt(1)
	v_mfma_f32_16x16x32_bf16 v[92:95], v[220:223], v[182:185], v[92:95]
	s_waitcnt lgkmcnt(0)
	s_barrier
	v_mfma_f32_16x16x32_bf16 v[84:87], v[224:227], v[182:185], v[84:87]
	v_mfma_f32_16x16x32_bf16 v[68:71], v[204:207], v[200:203], v[68:71]
	v_mfma_f32_16x16x32_bf16 v[60:63], v[216:219], v[200:203], v[60:63]
	v_mfma_f32_16x16x32_bf16 v[52:55], v[220:223], v[200:203], v[52:55]
	v_mfma_f32_16x16x32_bf16 v[48:51], v[224:227], v[200:203], v[48:51]
	v_mfma_f32_16x16x32_bf16 v[36:39], v[204:207], v[208:211], v[36:39]
	v_mfma_f32_16x16x32_bf16 v[28:31], v[216:219], v[208:211], v[28:31]
	v_mfma_f32_16x16x32_bf16 v[20:23], v[220:223], v[208:211], v[20:23]
	v_mfma_f32_16x16x32_bf16 v[16:19], v[224:227], v[208:211], v[16:19]
	v_mfma_f32_16x16x32_bf16 v[12:15], v[204:207], v[212:215], v[12:15]
	v_mfma_f32_16x16x32_bf16 v[8:11], v[216:219], v[212:215], v[8:11]
	v_mfma_f32_16x16x32_bf16 v[4:7], v[220:223], v[212:215], v[4:7]
	v_mfma_f32_16x16x32_bf16 v[0:3], v[224:227], v[212:215], v[0:3]
	s_add_u32 s0, s0, 64
	s_addc_u32 s1, s1, 0
	s_cmpk_lg_i32 s0, 0xfc0
	s_cbranch_scc1 .LBB0_276
	s_waitcnt vmcnt(5)
	ds_write_b128 v158, v[80:83]
	s_waitcnt vmcnt(3)
	ds_write_b128 v158, v[116:119] offset:6144
	ds_write_b128 v158, v[88:91] offset:12288
	s_waitcnt vmcnt(2)
	ds_write_b128 v158, v[124:127] offset:18432
	s_waitcnt vmcnt(1)
	ds_write_b128 v158, v[128:131] offset:24576
	s_waitcnt vmcnt(0)
	ds_write_b128 v158, v[132:135] offset:30720
	s_waitcnt lgkmcnt(0)
	s_barrier
	ds_read_b128 v[80:83], v179 offset:12288
	ds_read_b128 v[88:91], v179 offset:13824
	ds_read_b128 v[116:119], v159
	ds_read_b128 v[124:127], v159 offset:1536
	s_waitcnt lgkmcnt(1)
	v_mfma_f32_16x16x32_bf16 v[128:131], v[80:83], v[116:119], v[148:151]
	ds_read_b128 v[132:135], v179 offset:15360
	s_nop 1
	ds_read_b128 v[148:151], v179 offset:16896
	ds_read_b128 v[168:171], v159 offset:3072
	ds_read_b128 v[182:185], v159 offset:4608
	v_mfma_f32_16x16x32_bf16 v[144:147], v[88:91], v[116:119], v[144:147]
	s_waitcnt lgkmcnt(3)
	v_mfma_f32_16x16x32_bf16 v[140:143], v[132:135], v[116:119], v[140:143]
	s_waitcnt lgkmcnt(2)
	v_mfma_f32_16x16x32_bf16 v[136:139], v[148:151], v[116:119], v[136:139]
	v_mfma_f32_16x16x32_bf16 v[120:123], v[80:83], v[124:127], v[120:123]
	v_mfma_f32_16x16x32_bf16 v[112:115], v[88:91], v[124:127], v[112:115]
	v_mfma_f32_16x16x32_bf16 v[104:107], v[132:135], v[124:127], v[104:107]
	v_mfma_f32_16x16x32_bf16 v[96:99], v[148:151], v[124:127], v[96:99]
	s_waitcnt lgkmcnt(1)
	v_mfma_f32_16x16x32_bf16 v[76:79], v[80:83], v[168:171], v[76:79]
	v_mfma_f32_16x16x32_bf16 v[72:75], v[88:91], v[168:171], v[72:75]
	v_mfma_f32_16x16x32_bf16 v[64:67], v[132:135], v[168:171], v[64:67]
	v_mfma_f32_16x16x32_bf16 v[56:59], v[148:151], v[168:171], v[56:59]
	s_waitcnt lgkmcnt(0)
	v_mfma_f32_16x16x32_bf16 v[44:47], v[80:83], v[182:185], v[44:47]
	v_mfma_f32_16x16x32_bf16 v[40:43], v[88:91], v[182:185], v[40:43]
	v_mfma_f32_16x16x32_bf16 v[32:35], v[132:135], v[182:185], v[32:35]
	v_mfma_f32_16x16x32_bf16 v[24:27], v[148:151], v[182:185], v[24:27]
	ds_read_b128 v[80:83], v179 offset:18432
	ds_read_b128 v[88:91], v179 offset:19968
	ds_read_b128 v[132:135], v179 offset:21504
	ds_read_b128 v[148:151], v179 offset:23040
	s_waitcnt lgkmcnt(3)
	v_mfma_f32_16x16x32_bf16 v[108:111], v[80:83], v[116:119], v[108:111]
	v_mfma_f32_16x16x32_bf16 v[68:71], v[80:83], v[124:127], v[68:71]
	v_mfma_f32_16x16x32_bf16 v[36:39], v[80:83], v[168:171], v[36:39]
	v_mfma_f32_16x16x32_bf16 v[12:15], v[80:83], v[182:185], v[12:15]
	s_waitcnt lgkmcnt(2)
	v_mfma_f32_16x16x32_bf16 v[80:83], v[88:91], v[182:185], v[8:11]
	s_waitcnt lgkmcnt(0)
	v_mfma_f32_16x16x32_bf16 v[8:11], v[148:151], v[182:185], v[0:3]
	v_mfma_f32_16x16x32_bf16 v[100:103], v[88:91], v[116:119], v[100:103]
	v_mfma_f32_16x16x32_bf16 v[92:95], v[132:135], v[116:119], v[92:95]
	v_mfma_f32_16x16x32_bf16 v[84:87], v[148:151], v[116:119], v[84:87]
	v_mfma_f32_16x16x32_bf16 v[60:63], v[88:91], v[124:127], v[60:63]
	v_mfma_f32_16x16x32_bf16 v[52:55], v[132:135], v[124:127], v[52:55]
	v_mfma_f32_16x16x32_bf16 v[48:51], v[148:151], v[124:127], v[48:51]
	v_mfma_f32_16x16x32_bf16 v[28:31], v[88:91], v[168:171], v[28:31]
	v_mfma_f32_16x16x32_bf16 v[20:23], v[132:135], v[168:171], v[20:23]
	v_mfma_f32_16x16x32_bf16 v[16:19], v[148:151], v[168:171], v[16:19]
	v_mfma_f32_16x16x32_bf16 v[4:7], v[132:135], v[182:185], v[4:7]
	v_or_b32_e32 v0, s4, v174
	v_add_u32_e32 v0, v0, v177
	v_ashrrev_i32_e32 v1, 31, v0
	v_or_b32_e32 v88, s5, v180
	v_lshlrev_b64 v[2:3], 13, v[0:1]
	v_lshl_add_u64 v[2:3], s[64:65], 0, v[2:3]
	v_lshlrev_b32_e32 v152, 1, v88
	v_lshl_add_u64 v[2:3], v[2:3], 0, v[152:153]
	v_cvt_pk_bf16_f32 v88, v128, v129
	v_cvt_pk_bf16_f32 v89, v130, v131
	s_barrier
	global_store_dwordx2 v[2:3], v[88:89], off
	v_cvt_pk_bf16_f32 v88, v144, v145
	v_cvt_pk_bf16_f32 v89, v146, v147
	global_store_dwordx2 v[2:3], v[88:89], off offset:32
	v_cvt_pk_bf16_f32 v88, v140, v141
	v_cvt_pk_bf16_f32 v89, v142, v143
	global_store_dwordx2 v[2:3], v[88:89], off offset:64
	v_cvt_pk_bf16_f32 v88, v136, v137
	v_cvt_pk_bf16_f32 v89, v138, v139
	global_store_dwordx2 v[2:3], v[88:89], off offset:96
	v_cvt_pk_bf16_f32 v88, v108, v109
	v_cvt_pk_bf16_f32 v89, v110, v111
	global_store_dwordx2 v[2:3], v[88:89], off offset:128
	v_cvt_pk_bf16_f32 v88, v100, v101
	v_cvt_pk_bf16_f32 v89, v102, v103
	global_store_dwordx2 v[2:3], v[88:89], off offset:160
	v_cvt_pk_bf16_f32 v88, v92, v93
	v_cvt_pk_bf16_f32 v89, v94, v95
	v_cvt_pk_bf16_f32 v84, v84, v85
	v_cvt_pk_bf16_f32 v85, v86, v87
	global_store_dwordx2 v[2:3], v[88:89], off offset:192
	global_store_dwordx2 v[2:3], v[84:85], off offset:224
	v_or_b32_e32 v2, 16, v0
	v_ashrrev_i32_e32 v3, 31, v2
	v_lshlrev_b64 v[2:3], 13, v[2:3]
	v_lshl_add_u64 v[2:3], s[64:65], 0, v[2:3]
	v_lshl_add_u64 v[2:3], v[2:3], 0, v[152:153]
	v_cvt_pk_bf16_f32 v84, v120, v121
	v_cvt_pk_bf16_f32 v85, v122, v123
	global_store_dwordx2 v[2:3], v[84:85], off
	v_cvt_pk_bf16_f32 v84, v112, v113
	v_cvt_pk_bf16_f32 v85, v114, v115
	global_store_dwordx2 v[2:3], v[84:85], off offset:32
	v_cvt_pk_bf16_f32 v84, v104, v105
	v_cvt_pk_bf16_f32 v85, v106, v107
	global_store_dwordx2 v[2:3], v[84:85], off offset:64
	v_cvt_pk_bf16_f32 v84, v96, v97
	v_cvt_pk_bf16_f32 v85, v98, v99
	v_cvt_pk_bf16_f32 v68, v68, v69
	v_cvt_pk_bf16_f32 v69, v70, v71
	v_cvt_pk_bf16_f32 v60, v60, v61
	v_cvt_pk_bf16_f32 v61, v62, v63
	v_cvt_pk_bf16_f32 v52, v52, v53
	v_cvt_pk_bf16_f32 v53, v54, v55
	v_cvt_pk_bf16_f32 v48, v48, v49
	v_cvt_pk_bf16_f32 v49, v50, v51
	global_store_dwordx2 v[2:3], v[84:85], off offset:96
	global_store_dwordx2 v[2:3], v[68:69], off offset:128
	global_store_dwordx2 v[2:3], v[60:61], off offset:160
	global_store_dwordx2 v[2:3], v[52:53], off offset:192
	global_store_dwordx2 v[2:3], v[48:49], off offset:224
	v_or_b32_e32 v2, 32, v0
	v_ashrrev_i32_e32 v3, 31, v2
	v_lshlrev_b64 v[2:3], 13, v[2:3]
	v_lshl_add_u64 v[2:3], s[64:65], 0, v[2:3]
	v_lshl_add_u64 v[2:3], v[2:3], 0, v[152:153]
	v_cvt_pk_bf16_f32 v48, v76, v77
	v_cvt_pk_bf16_f32 v49, v78, v79
	v_or_b32_e32 v0, 48, v0
	global_store_dwordx2 v[2:3], v[48:49], off
	v_cvt_pk_bf16_f32 v48, v72, v73
	v_cvt_pk_bf16_f32 v49, v74, v75
	v_ashrrev_i32_e32 v1, 31, v0
	global_store_dwordx2 v[2:3], v[48:49], off offset:32
	v_cvt_pk_bf16_f32 v48, v64, v65
	v_cvt_pk_bf16_f32 v49, v66, v67
	v_lshlrev_b64 v[0:1], 13, v[0:1]
	global_store_dwordx2 v[2:3], v[48:49], off offset:64
	v_cvt_pk_bf16_f32 v48, v56, v57
	v_cvt_pk_bf16_f32 v49, v58, v59
	v_cvt_pk_bf16_f32 v36, v36, v37
	v_cvt_pk_bf16_f32 v37, v38, v39
	v_cvt_pk_bf16_f32 v28, v28, v29
	v_cvt_pk_bf16_f32 v29, v30, v31
	v_cvt_pk_bf16_f32 v20, v20, v21
	v_cvt_pk_bf16_f32 v21, v22, v23
	v_cvt_pk_bf16_f32 v16, v16, v17
	v_cvt_pk_bf16_f32 v17, v18, v19
	v_lshl_add_u64 v[0:1], s[64:65], 0, v[0:1]
	global_store_dwordx2 v[2:3], v[48:49], off offset:96
	global_store_dwordx2 v[2:3], v[36:37], off offset:128
	global_store_dwordx2 v[2:3], v[28:29], off offset:160
	global_store_dwordx2 v[2:3], v[20:21], off offset:192
	global_store_dwordx2 v[2:3], v[16:17], off offset:224
	v_lshl_add_u64 v[2:3], v[0:1], 0, v[152:153]
	v_cvt_pk_bf16_f32 v0, v44, v45
	v_cvt_pk_bf16_f32 v1, v46, v47
	global_store_dwordx2 v[2:3], v[0:1], off
	v_cvt_pk_bf16_f32 v0, v40, v41
	v_cvt_pk_bf16_f32 v1, v42, v43
	global_store_dwordx2 v[2:3], v[0:1], off offset:32
	v_cvt_pk_bf16_f32 v0, v32, v33
	v_cvt_pk_bf16_f32 v1, v34, v35
	global_store_dwordx2 v[2:3], v[0:1], off offset:64
	v_cvt_pk_bf16_f32 v0, v24, v25
	v_cvt_pk_bf16_f32 v1, v26, v27
	global_store_dwordx2 v[2:3], v[0:1], off offset:96
	v_cvt_pk_bf16_f32 v0, v12, v13
	v_cvt_pk_bf16_f32 v1, v14, v15
	global_store_dwordx2 v[2:3], v[0:1], off offset:128
	v_cvt_pk_bf16_f32 v0, v80, v81
	v_cvt_pk_bf16_f32 v1, v82, v83
	global_store_dwordx2 v[2:3], v[0:1], off offset:160
	v_cvt_pk_bf16_f32 v0, v4, v5
	v_cvt_pk_bf16_f32 v1, v6, v7
	s_mov_b64 s[0:1], 0xe0
	v_cvt_pk_bf16_f32 v4, v8, v9
	global_store_dwordx2 v[2:3], v[0:1], off offset:192
	v_lshl_add_u64 v[0:1], v[2:3], 0, s[0:1]
	global_store_dword v[2:3], v4, off offset:224
	s_branch .LBB0_227

.LBB0_309:
	s_waitcnt vmcnt(5)
	ds_write_b128 v156, v[0:3]
	s_waitcnt vmcnt(3)
	ds_write_b128 v156, v[8:11] offset:6144
	s_waitcnt vmcnt(3)
	ds_write_b128 v156, v[4:7] offset:12288
	s_waitcnt vmcnt(2)
	ds_write_b128 v156, v[12:15] offset:18432
	s_waitcnt vmcnt(1)
	ds_write_b128 v156, v[16:19] offset:24576
	s_waitcnt vmcnt(0)
	ds_write_b128 v156, v[20:23] offset:30720
	s_waitcnt lgkmcnt(0)
	s_barrier
	ds_read_b128 v[8:11], v212 offset:12288
	ds_read_b128 v[12:15], v212 offset:13824
	ds_read_b128 v[216:219], v157
	ds_read_b128 v[220:223], v157 offset:1536
	ds_read_b128 v[20:23], v212 offset:15360
	ds_read_b128 v[224:227], v212 offset:16896
	v_lshl_add_u64 v[4:5], v[184:185], 0, s[0:1]
	v_add_co_u32_e32 v18, vcc, s69, v4
	v_lshl_add_u64 v[16:17], v[186:187], 0, s[0:1]
	s_nop 0
	v_addc_co_u32_e32 v19, vcc, 0, v5, vcc
	ds_read_b128 v[228:231], v157 offset:3072
	ds_read_b128 v[232:235], v157 offset:4608
	v_add_co_u32_e32 v236, vcc, s69, v16
	s_waitcnt lgkmcnt(5)
	v_mfma_f32_16x16x32_bf16 v[148:151], v[8:11], v[216:219], v[148:151]
	v_addc_co_u32_e32 v237, vcc, 0, v17, vcc
	v_add_co_u32_e32 v238, vcc, s70, v16
	v_mfma_f32_16x16x32_bf16 v[144:147], v[12:15], v[216:219], v[144:147]
	s_nop 0
	v_addc_co_u32_e32 v239, vcc, 0, v17, vcc
	v_add_co_u32_e32 v240, vcc, s71, v16
	s_waitcnt lgkmcnt(4)
	v_mfma_f32_16x16x32_bf16 v[96:99], v[8:11], v[220:223], v[96:99]
	global_load_dwordx4 v[0:3], v[4:5], off offset:64
	v_addc_co_u32_e32 v241, vcc, 0, v17, vcc
	v_mfma_f32_16x16x32_bf16 v[88:91], v[12:15], v[220:223], v[88:91]
	global_load_dwordx4 v[4:7], v[16:17], off offset:64
	s_waitcnt lgkmcnt(1)
	v_mfma_f32_16x16x32_bf16 v[60:63], v[8:11], v[228:231], v[60:63]
	v_mfma_f32_16x16x32_bf16 v[56:59], v[12:15], v[228:231], v[56:59]
	s_waitcnt lgkmcnt(0)
	v_mfma_f32_16x16x32_bf16 v[28:31], v[8:11], v[232:235], v[28:31]
	v_mfma_f32_16x16x32_bf16 v[24:27], v[12:15], v[232:235], v[24:27]
	global_load_dwordx4 v[8:11], v[18:19], off offset:64
	global_load_dwordx4 v[12:15], v[236:237], off offset:64
	s_nop 0
	global_load_dwordx4 v[16:19], v[238:239], off offset:64
	v_mfma_f32_16x16x32_bf16 v[140:143], v[20:23], v[216:219], v[140:143]
	v_mfma_f32_16x16x32_bf16 v[84:87], v[20:23], v[220:223], v[84:87]
	v_mfma_f32_16x16x32_bf16 v[52:55], v[20:23], v[228:231], v[52:55]
	v_mfma_f32_16x16x32_bf16 v[44:47], v[20:23], v[232:235], v[44:47]
	global_load_dwordx4 v[20:23], v[240:241], off offset:64
	v_mfma_f32_16x16x32_bf16 v[136:139], v[224:227], v[216:219], v[136:139]
	v_mfma_f32_16x16x32_bf16 v[80:83], v[224:227], v[220:223], v[80:83]
	v_mfma_f32_16x16x32_bf16 v[48:51], v[224:227], v[228:231], v[48:51]
	v_mfma_f32_16x16x32_bf16 v[40:43], v[224:227], v[232:235], v[40:43]
	ds_read_b128 v[224:227], v212 offset:18432
	ds_read_b128 v[236:239], v212 offset:19968
	ds_read_b128 v[240:243], v212 offset:21504
	ds_read_b128 v[244:247], v212 offset:23040
	s_waitcnt lgkmcnt(3)
	v_mfma_f32_16x16x32_bf16 v[132:135], v[224:227], v[216:219], v[132:135]
	s_waitcnt lgkmcnt(2)
	v_mfma_f32_16x16x32_bf16 v[128:131], v[236:239], v[216:219], v[128:131]
	s_waitcnt lgkmcnt(1)
	v_mfma_f32_16x16x32_bf16 v[124:127], v[240:243], v[216:219], v[124:127]
	s_waitcnt lgkmcnt(0)
	s_barrier
	v_mfma_f32_16x16x32_bf16 v[120:123], v[244:247], v[216:219], v[120:123]
	v_mfma_f32_16x16x32_bf16 v[76:79], v[224:227], v[220:223], v[76:79]
	v_mfma_f32_16x16x32_bf16 v[72:75], v[236:239], v[220:223], v[72:75]
	v_mfma_f32_16x16x32_bf16 v[68:71], v[240:243], v[220:223], v[68:71]
	v_mfma_f32_16x16x32_bf16 v[64:67], v[244:247], v[220:223], v[64:67]
	v_mfma_f32_16x16x32_bf16 v[116:119], v[224:227], v[228:231], v[116:119]
	v_mfma_f32_16x16x32_bf16 v[112:115], v[236:239], v[228:231], v[112:115]
	v_mfma_f32_16x16x32_bf16 v[36:39], v[240:243], v[228:231], v[36:39]
	v_mfma_f32_16x16x32_bf16 v[32:35], v[244:247], v[228:231], v[32:35]
	v_mfma_f32_16x16x32_bf16 v[108:111], v[224:227], v[232:235], v[108:111]
	v_mfma_f32_16x16x32_bf16 v[104:107], v[236:239], v[232:235], v[104:107]
	v_mfma_f32_16x16x32_bf16 v[100:103], v[240:243], v[232:235], v[100:103]
	v_mfma_f32_16x16x32_bf16 v[92:95], v[244:247], v[232:235], v[92:95]
	s_add_u32 s0, s0, 64
	s_addc_u32 s1, s1, 0
	s_cmpk_lg_i32 s0, 0xfc0
	s_cbranch_scc1 .LBB0_309
	s_waitcnt vmcnt(5)
	ds_write_b128 v156, v[0:3]
	s_waitcnt vmcnt(3)
	ds_write_b128 v156, v[8:11] offset:6144
	ds_write_b128 v156, v[4:7] offset:12288
	s_waitcnt vmcnt(2)
	ds_write_b128 v156, v[12:15] offset:18432
	s_waitcnt vmcnt(1)
	ds_write_b128 v156, v[16:19] offset:24576
	s_waitcnt vmcnt(0)
	ds_write_b128 v156, v[20:23] offset:30720
	s_waitcnt lgkmcnt(0)
	s_barrier
	ds_read_b128 v[0:3], v212 offset:12288
	ds_read_b128 v[4:7], v212 offset:13824
	ds_read_b128 v[8:11], v157
	ds_read_b128 v[12:15], v157 offset:1536
	ds_read_b128 v[16:19], v212 offset:15360
	ds_read_b128 v[184:187], v212 offset:16896
	ds_read_b128 v[216:219], v157 offset:3072
	ds_read_b128 v[220:223], v157 offset:4608
	s_waitcnt lgkmcnt(5)
	v_mfma_f32_16x16x32_bf16 v[148:151], v[0:3], v[8:11], v[148:151]
	v_mfma_f32_16x16x32_bf16 v[144:147], v[4:7], v[8:11], v[144:147]
	s_waitcnt lgkmcnt(3)
	v_mfma_f32_16x16x32_bf16 v[140:143], v[16:19], v[8:11], v[140:143]
	s_waitcnt lgkmcnt(2)
	v_mfma_f32_16x16x32_bf16 v[136:139], v[184:187], v[8:11], v[136:139]
	v_mfma_f32_16x16x32_bf16 v[96:99], v[0:3], v[12:15], v[96:99]
	v_mfma_f32_16x16x32_bf16 v[88:91], v[4:7], v[12:15], v[88:91]
	v_mfma_f32_16x16x32_bf16 v[84:87], v[16:19], v[12:15], v[84:87]
	v_mfma_f32_16x16x32_bf16 v[80:83], v[184:187], v[12:15], v[80:83]
	s_waitcnt lgkmcnt(1)
	v_mfma_f32_16x16x32_bf16 v[60:63], v[0:3], v[216:219], v[60:63]
	v_mfma_f32_16x16x32_bf16 v[56:59], v[4:7], v[216:219], v[56:59]
	v_mfma_f32_16x16x32_bf16 v[52:55], v[16:19], v[216:219], v[52:55]
	v_mfma_f32_16x16x32_bf16 v[48:51], v[184:187], v[216:219], v[48:51]
	s_waitcnt lgkmcnt(0)
	v_mfma_f32_16x16x32_bf16 v[28:31], v[0:3], v[220:223], v[28:31]
	v_mfma_f32_16x16x32_bf16 v[24:27], v[4:7], v[220:223], v[24:27]
	v_mfma_f32_16x16x32_bf16 v[20:23], v[16:19], v[220:223], v[44:47]
	v_mfma_f32_16x16x32_bf16 v[16:19], v[184:187], v[220:223], v[40:43]
	ds_read_b128 v[0:3], v212 offset:18432
	ds_read_b128 v[4:7], v212 offset:19968
	ds_read_b128 v[184:187], v212 offset:21504
	ds_read_b128 v[224:227], v212 offset:23040
	s_waitcnt lgkmcnt(3)
	v_mfma_f32_16x16x32_bf16 v[132:135], v[0:3], v[8:11], v[132:135]
	s_waitcnt lgkmcnt(2)
	v_mfma_f32_16x16x32_bf16 v[128:131], v[4:7], v[8:11], v[128:131]
	s_waitcnt lgkmcnt(1)
	v_mfma_f32_16x16x32_bf16 v[124:127], v[184:187], v[8:11], v[124:127]
	s_waitcnt lgkmcnt(0)
	v_mfma_f32_16x16x32_bf16 v[120:123], v[224:227], v[8:11], v[120:123]
	v_mfma_f32_16x16x32_bf16 v[76:79], v[0:3], v[12:15], v[76:79]
	v_mfma_f32_16x16x32_bf16 v[72:75], v[4:7], v[12:15], v[72:75]
	v_mfma_f32_16x16x32_bf16 v[68:71], v[184:187], v[12:15], v[68:71]
	v_mfma_f32_16x16x32_bf16 v[64:67], v[224:227], v[12:15], v[64:67]
	v_mfma_f32_16x16x32_bf16 v[44:47], v[0:3], v[216:219], v[116:119]
	v_mfma_f32_16x16x32_bf16 v[40:43], v[4:7], v[216:219], v[112:115]
	v_mfma_f32_16x16x32_bf16 v[36:39], v[184:187], v[216:219], v[36:39]
	v_mfma_f32_16x16x32_bf16 v[32:35], v[224:227], v[216:219], v[32:35]
	v_mfma_f32_16x16x32_bf16 v[12:15], v[0:3], v[220:223], v[108:111]
	v_mfma_f32_16x16x32_bf16 v[8:11], v[4:7], v[220:223], v[104:107]
	v_mfma_f32_16x16x32_bf16 v[4:7], v[184:187], v[220:223], v[100:103]
	v_mfma_f32_16x16x32_bf16 v[0:3], v[224:227], v[220:223], v[92:95]
	s_nop 2
	v_or_b32_e32 v94, v214, v213
	v_lshl_add_u64 v[92:93], s[64:65], 0, v[182:183]
	v_lshlrev_b32_e32 v152, 1, v94
	v_lshl_add_u64 v[92:93], v[92:93], 0, v[152:153]
	s_barrier
	global_load_dwordx2 v[94:95], v[92:93], off
	s_add_i32 s6, s6, s33
	s_cmpk_lt_i32 s6, 0xc00
	s_waitcnt vmcnt(0)
	v_lshlrev_b32_e32 v100, 16, v94
	v_and_b32_e32 v101, 0xffff0000, v94
	v_lshlrev_b32_e32 v102, 16, v95
	v_and_b32_e32 v103, 0xffff0000, v95
	v_lshl_add_u64 v[94:95], v[180:181], 0, v[152:153]
	global_load_dwordx2 v[104:105], v[94:95], off
	v_pk_add_f32 v[100:101], v[100:101], v[148:149] neg_lo:[0,1] neg_hi:[0,1]
	v_pk_add_f32 v[102:103], v[102:103], v[150:151] neg_lo:[0,1] neg_hi:[0,1]
	s_waitcnt vmcnt(0)
	v_lshlrev_b32_e32 v106, 16, v104
	v_and_b32_e32 v107, 0xffff0000, v104
	v_lshlrev_b32_e32 v104, 16, v105
	v_and_b32_e32 v105, 0xffff0000, v105
	v_pk_fma_f32 v[100:101], v[100:101], v[106:107], v[148:149]
	v_pk_fma_f32 v[102:103], v[102:103], v[104:105], v[150:151]
	v_cvt_pk_bf16_f32 v100, v100, v101
	v_cvt_pk_bf16_f32 v101, v102, v103
	global_store_dwordx2 v[92:93], v[100:101], off
	global_load_dwordx2 v[100:101], v[92:93], off offset:32
	s_waitcnt vmcnt(0)
	v_lshlrev_b32_e32 v102, 16, v100
	global_load_dwordx2 v[104:105], v[94:95], off offset:32
	v_and_b32_e32 v103, 0xffff0000, v100
	v_lshlrev_b32_e32 v100, 16, v101
	v_and_b32_e32 v101, 0xffff0000, v101
	v_pk_add_f32 v[102:103], v[102:103], v[144:145] neg_lo:[0,1] neg_hi:[0,1]
	v_pk_add_f32 v[100:101], v[100:101], v[146:147] neg_lo:[0,1] neg_hi:[0,1]
	s_waitcnt vmcnt(0)
	v_lshlrev_b32_e32 v106, 16, v104
	v_and_b32_e32 v107, 0xffff0000, v104
	v_lshlrev_b32_e32 v104, 16, v105
	v_and_b32_e32 v105, 0xffff0000, v105
	v_pk_fma_f32 v[102:103], v[102:103], v[106:107], v[144:145]
	v_pk_fma_f32 v[100:101], v[100:101], v[104:105], v[146:147]
	v_cvt_pk_bf16_f32 v102, v102, v103
	v_cvt_pk_bf16_f32 v103, v100, v101
	global_store_dwordx2 v[92:93], v[102:103], off offset:32
	global_load_dwordx2 v[100:101], v[92:93], off offset:64
	global_load_dwordx2 v[104:105], v[94:95], off offset:64
	s_waitcnt vmcnt(1)
	v_lshlrev_b32_e32 v102, 16, v100
	v_and_b32_e32 v103, 0xffff0000, v100
	v_lshlrev_b32_e32 v100, 16, v101
	v_and_b32_e32 v101, 0xffff0000, v101
	s_waitcnt vmcnt(0)
	v_lshlrev_b32_e32 v106, 16, v104
	v_and_b32_e32 v107, 0xffff0000, v104
	v_lshlrev_b32_e32 v104, 16, v105
	v_and_b32_e32 v105, 0xffff0000, v105
	v_pk_add_f32 v[102:103], v[102:103], v[140:141] neg_lo:[0,1] neg_hi:[0,1]
	v_pk_add_f32 v[100:101], v[100:101], v[142:143] neg_lo:[0,1] neg_hi:[0,1]
	v_pk_fma_f32 v[102:103], v[102:103], v[106:107], v[140:141]
	v_pk_fma_f32 v[100:101], v[100:101], v[104:105], v[142:143]
	v_cvt_pk_bf16_f32 v102, v102, v103
	v_cvt_pk_bf16_f32 v103, v100, v101
	global_store_dwordx2 v[92:93], v[102:103], off offset:64
	global_load_dwordx2 v[100:101], v[92:93], off offset:96
	global_load_dwordx2 v[104:105], v[94:95], off offset:96
	s_waitcnt vmcnt(1)
	v_lshlrev_b32_e32 v102, 16, v100
	v_and_b32_e32 v103, 0xffff0000, v100
	v_lshlrev_b32_e32 v100, 16, v101
	v_and_b32_e32 v101, 0xffff0000, v101
	s_waitcnt vmcnt(0)
	v_lshlrev_b32_e32 v106, 16, v104
	v_and_b32_e32 v107, 0xffff0000, v104
	v_lshlrev_b32_e32 v104, 16, v105
	v_and_b32_e32 v105, 0xffff0000, v105
	v_pk_add_f32 v[102:103], v[102:103], v[136:137] neg_lo:[0,1] neg_hi:[0,1]
	v_pk_add_f32 v[100:101], v[100:101], v[138:139] neg_lo:[0,1] neg_hi:[0,1]
	v_pk_fma_f32 v[102:103], v[102:103], v[106:107], v[136:137]
	v_pk_fma_f32 v[100:101], v[100:101], v[104:105], v[138:139]
	v_cvt_pk_bf16_f32 v102, v102, v103
	v_cvt_pk_bf16_f32 v103, v100, v101
	global_store_dwordx2 v[92:93], v[102:103], off offset:96
	global_load_dwordx2 v[100:101], v[92:93], off offset:128
	global_load_dwordx2 v[104:105], v[94:95], off offset:128
	s_waitcnt vmcnt(1)
	v_lshlrev_b32_e32 v102, 16, v100
	v_and_b32_e32 v103, 0xffff0000, v100
	v_lshlrev_b32_e32 v100, 16, v101
	v_and_b32_e32 v101, 0xffff0000, v101
	s_waitcnt vmcnt(0)
	v_lshlrev_b32_e32 v106, 16, v104
	v_and_b32_e32 v107, 0xffff0000, v104
	v_lshlrev_b32_e32 v104, 16, v105
	v_and_b32_e32 v105, 0xffff0000, v105
	v_pk_add_f32 v[102:103], v[102:103], v[132:133] neg_lo:[0,1] neg_hi:[0,1]
	v_pk_add_f32 v[100:101], v[100:101], v[134:135] neg_lo:[0,1] neg_hi:[0,1]
	v_pk_fma_f32 v[102:103], v[102:103], v[106:107], v[132:133]
	v_pk_fma_f32 v[100:101], v[100:101], v[104:105], v[134:135]
	v_cvt_pk_bf16_f32 v102, v102, v103
	v_cvt_pk_bf16_f32 v103, v100, v101
	global_store_dwordx2 v[92:93], v[102:103], off offset:128
	global_load_dwordx2 v[100:101], v[92:93], off offset:160
	global_load_dwordx2 v[104:105], v[94:95], off offset:160
	s_waitcnt vmcnt(1)
	v_lshlrev_b32_e32 v102, 16, v100
	v_and_b32_e32 v103, 0xffff0000, v100
	v_lshlrev_b32_e32 v100, 16, v101
	v_and_b32_e32 v101, 0xffff0000, v101
	s_waitcnt vmcnt(0)
	v_lshlrev_b32_e32 v106, 16, v104
	v_and_b32_e32 v107, 0xffff0000, v104
	v_lshlrev_b32_e32 v104, 16, v105
	v_and_b32_e32 v105, 0xffff0000, v105
	v_pk_add_f32 v[102:103], v[102:103], v[128:129] neg_lo:[0,1] neg_hi:[0,1]
	v_pk_add_f32 v[100:101], v[100:101], v[130:131] neg_lo:[0,1] neg_hi:[0,1]
	v_pk_fma_f32 v[102:103], v[102:103], v[106:107], v[128:129]
	v_pk_fma_f32 v[100:101], v[100:101], v[104:105], v[130:131]
	v_cvt_pk_bf16_f32 v102, v102, v103
	v_cvt_pk_bf16_f32 v103, v100, v101
	global_store_dwordx2 v[92:93], v[102:103], off offset:160
	global_load_dwordx2 v[100:101], v[92:93], off offset:192
	global_load_dwordx2 v[104:105], v[94:95], off offset:192
	s_waitcnt vmcnt(1)
	v_lshlrev_b32_e32 v102, 16, v100
	v_and_b32_e32 v103, 0xffff0000, v100
	v_lshlrev_b32_e32 v100, 16, v101
	v_and_b32_e32 v101, 0xffff0000, v101
	s_waitcnt vmcnt(0)
	v_lshlrev_b32_e32 v106, 16, v104
	v_and_b32_e32 v107, 0xffff0000, v104
	v_lshlrev_b32_e32 v104, 16, v105
	v_and_b32_e32 v105, 0xffff0000, v105
	v_pk_add_f32 v[102:103], v[102:103], v[124:125] neg_lo:[0,1] neg_hi:[0,1]
	v_pk_add_f32 v[100:101], v[100:101], v[126:127] neg_lo:[0,1] neg_hi:[0,1]
	v_pk_fma_f32 v[102:103], v[102:103], v[106:107], v[124:125]
	v_pk_fma_f32 v[100:101], v[100:101], v[104:105], v[126:127]
	v_cvt_pk_bf16_f32 v102, v102, v103
	v_cvt_pk_bf16_f32 v103, v100, v101
	global_store_dwordx2 v[92:93], v[102:103], off offset:192
	global_load_dwordx2 v[100:101], v[92:93], off offset:224
	s_waitcnt vmcnt(0)
	v_lshlrev_b32_e32 v102, 16, v100
	global_load_dwordx2 v[94:95], v[94:95], off offset:224
	v_and_b32_e32 v103, 0xffff0000, v100
	v_lshlrev_b32_e32 v100, 16, v101
	v_and_b32_e32 v101, 0xffff0000, v101
	v_pk_add_f32 v[102:103], v[102:103], v[120:121] neg_lo:[0,1] neg_hi:[0,1]
	v_pk_add_f32 v[100:101], v[100:101], v[122:123] neg_lo:[0,1] neg_hi:[0,1]
	s_waitcnt vmcnt(0)
	v_lshlrev_b32_e32 v104, 16, v94
	v_and_b32_e32 v105, 0xffff0000, v94
	v_lshlrev_b32_e32 v94, 16, v95
	v_and_b32_e32 v95, 0xffff0000, v95
	v_pk_fma_f32 v[102:103], v[102:103], v[104:105], v[120:121]
	v_pk_fma_f32 v[94:95], v[100:101], v[94:95], v[122:123]
	v_cvt_pk_bf16_f32 v100, v102, v103
	v_cvt_pk_bf16_f32 v101, v94, v95
	global_store_dwordx2 v[92:93], v[100:101], off offset:224
	v_lshl_add_u64 v[92:93], s[64:65], 0, v[178:179]
	v_lshl_add_u64 v[92:93], v[92:93], 0, v[152:153]
	global_load_dwordx2 v[94:95], v[92:93], off
	s_waitcnt vmcnt(0)
	v_lshlrev_b32_e32 v100, 16, v94
	v_and_b32_e32 v101, 0xffff0000, v94
	v_lshlrev_b32_e32 v102, 16, v95
	v_and_b32_e32 v103, 0xffff0000, v95
	v_lshl_add_u64 v[94:95], v[176:177], 0, v[152:153]
	global_load_dwordx2 v[104:105], v[94:95], off
	v_pk_add_f32 v[100:101], v[100:101], v[96:97] neg_lo:[0,1] neg_hi:[0,1]
	s_waitcnt vmcnt(0)
	v_lshlrev_b32_e32 v106, 16, v104
	v_and_b32_e32 v107, 0xffff0000, v104
	v_lshlrev_b32_e32 v104, 16, v105
	v_and_b32_e32 v105, 0xffff0000, v105
	v_pk_fma_f32 v[96:97], v[100:101], v[106:107], v[96:97]
	v_pk_add_f32 v[100:101], v[102:103], v[98:99] neg_lo:[0,1] neg_hi:[0,1]
	v_cvt_pk_bf16_f32 v96, v96, v97
	v_pk_fma_f32 v[98:99], v[100:101], v[104:105], v[98:99]
	s_nop 0
	v_cvt_pk_bf16_f32 v97, v98, v99
	global_store_dwordx2 v[92:93], v[96:97], off
	global_load_dwordx2 v[96:97], v[92:93], off offset:32
	s_waitcnt vmcnt(0)
	v_lshlrev_b32_e32 v98, 16, v96
	global_load_dwordx2 v[100:101], v[94:95], off offset:32
	v_and_b32_e32 v99, 0xffff0000, v96
	v_lshlrev_b32_e32 v96, 16, v97
	v_and_b32_e32 v97, 0xffff0000, v97
	v_pk_add_f32 v[98:99], v[98:99], v[88:89] neg_lo:[0,1] neg_hi:[0,1]
	v_pk_add_f32 v[96:97], v[96:97], v[90:91] neg_lo:[0,1] neg_hi:[0,1]
	s_waitcnt vmcnt(0)
	v_lshlrev_b32_e32 v102, 16, v100
	v_and_b32_e32 v103, 0xffff0000, v100
	v_lshlrev_b32_e32 v100, 16, v101
	v_and_b32_e32 v101, 0xffff0000, v101
	v_pk_fma_f32 v[88:89], v[98:99], v[102:103], v[88:89]
	v_pk_fma_f32 v[90:91], v[96:97], v[100:101], v[90:91]
	v_cvt_pk_bf16_f32 v88, v88, v89
	v_cvt_pk_bf16_f32 v89, v90, v91
	global_store_dwordx2 v[92:93], v[88:89], off offset:32
	global_load_dwordx2 v[88:89], v[92:93], off offset:64
	s_waitcnt vmcnt(0)
	v_lshlrev_b32_e32 v90, 16, v88
	global_load_dwordx2 v[96:97], v[94:95], off offset:64
	v_and_b32_e32 v91, 0xffff0000, v88
	v_lshlrev_b32_e32 v88, 16, v89
	v_and_b32_e32 v89, 0xffff0000, v89
	v_pk_add_f32 v[90:91], v[90:91], v[84:85] neg_lo:[0,1] neg_hi:[0,1]
	v_pk_add_f32 v[88:89], v[88:89], v[86:87] neg_lo:[0,1] neg_hi:[0,1]
	s_waitcnt vmcnt(0)
	v_lshlrev_b32_e32 v98, 16, v96
	v_and_b32_e32 v99, 0xffff0000, v96
	v_lshlrev_b32_e32 v96, 16, v97
	v_and_b32_e32 v97, 0xffff0000, v97
	v_pk_fma_f32 v[84:85], v[90:91], v[98:99], v[84:85]
	v_pk_fma_f32 v[86:87], v[88:89], v[96:97], v[86:87]
	v_cvt_pk_bf16_f32 v84, v84, v85
	v_cvt_pk_bf16_f32 v85, v86, v87
	global_store_dwordx2 v[92:93], v[84:85], off offset:64
	global_load_dwordx2 v[84:85], v[92:93], off offset:96
	s_waitcnt vmcnt(0)
	v_lshlrev_b32_e32 v86, 16, v84
	global_load_dwordx2 v[88:89], v[94:95], off offset:96
	v_and_b32_e32 v87, 0xffff0000, v84
	v_lshlrev_b32_e32 v84, 16, v85
	v_and_b32_e32 v85, 0xffff0000, v85
	v_pk_add_f32 v[86:87], v[86:87], v[80:81] neg_lo:[0,1] neg_hi:[0,1]
	v_pk_add_f32 v[84:85], v[84:85], v[82:83] neg_lo:[0,1] neg_hi:[0,1]
	s_waitcnt vmcnt(0)
	v_lshlrev_b32_e32 v90, 16, v88
	v_and_b32_e32 v91, 0xffff0000, v88
	v_lshlrev_b32_e32 v88, 16, v89
	v_and_b32_e32 v89, 0xffff0000, v89
	v_pk_fma_f32 v[80:81], v[86:87], v[90:91], v[80:81]
	v_pk_fma_f32 v[82:83], v[84:85], v[88:89], v[82:83]
	v_cvt_pk_bf16_f32 v80, v80, v81
	v_cvt_pk_bf16_f32 v81, v82, v83
	global_store_dwordx2 v[92:93], v[80:81], off offset:96
	global_load_dwordx2 v[80:81], v[92:93], off offset:128
	s_waitcnt vmcnt(0)
	v_lshlrev_b32_e32 v82, 16, v80
	global_load_dwordx2 v[84:85], v[94:95], off offset:128
	v_and_b32_e32 v83, 0xffff0000, v80
	v_lshlrev_b32_e32 v80, 16, v81
	v_and_b32_e32 v81, 0xffff0000, v81
	v_pk_add_f32 v[82:83], v[82:83], v[76:77] neg_lo:[0,1] neg_hi:[0,1]
	v_pk_add_f32 v[80:81], v[80:81], v[78:79] neg_lo:[0,1] neg_hi:[0,1]
	s_waitcnt vmcnt(0)
	v_lshlrev_b32_e32 v86, 16, v84
	v_and_b32_e32 v87, 0xffff0000, v84
	v_lshlrev_b32_e32 v84, 16, v85
	v_and_b32_e32 v85, 0xffff0000, v85
	v_pk_fma_f32 v[76:77], v[82:83], v[86:87], v[76:77]
	v_pk_fma_f32 v[78:79], v[80:81], v[84:85], v[78:79]
	v_cvt_pk_bf16_f32 v76, v76, v77
	v_cvt_pk_bf16_f32 v77, v78, v79
	global_store_dwordx2 v[92:93], v[76:77], off offset:128
	global_load_dwordx2 v[76:77], v[92:93], off offset:160
	s_waitcnt vmcnt(0)
	v_lshlrev_b32_e32 v78, 16, v76
	global_load_dwordx2 v[80:81], v[94:95], off offset:160
	v_and_b32_e32 v79, 0xffff0000, v76
	v_lshlrev_b32_e32 v76, 16, v77
	v_and_b32_e32 v77, 0xffff0000, v77
	v_pk_add_f32 v[78:79], v[78:79], v[72:73] neg_lo:[0,1] neg_hi:[0,1]
	v_pk_add_f32 v[76:77], v[76:77], v[74:75] neg_lo:[0,1] neg_hi:[0,1]
	s_waitcnt vmcnt(0)
	v_lshlrev_b32_e32 v82, 16, v80
	v_and_b32_e32 v83, 0xffff0000, v80
	v_lshlrev_b32_e32 v80, 16, v81
	v_and_b32_e32 v81, 0xffff0000, v81
	v_pk_fma_f32 v[72:73], v[78:79], v[82:83], v[72:73]
	v_pk_fma_f32 v[74:75], v[76:77], v[80:81], v[74:75]
	v_cvt_pk_bf16_f32 v72, v72, v73
	v_cvt_pk_bf16_f32 v73, v74, v75
	global_store_dwordx2 v[92:93], v[72:73], off offset:160
	global_load_dwordx2 v[72:73], v[92:93], off offset:192
	s_waitcnt vmcnt(0)
	v_lshlrev_b32_e32 v74, 16, v72
	global_load_dwordx2 v[76:77], v[94:95], off offset:192
	v_and_b32_e32 v75, 0xffff0000, v72
	v_lshlrev_b32_e32 v72, 16, v73
	v_and_b32_e32 v73, 0xffff0000, v73
	v_pk_add_f32 v[74:75], v[74:75], v[68:69] neg_lo:[0,1] neg_hi:[0,1]
	v_pk_add_f32 v[72:73], v[72:73], v[70:71] neg_lo:[0,1] neg_hi:[0,1]
	s_waitcnt vmcnt(0)
	v_lshlrev_b32_e32 v78, 16, v76
	v_and_b32_e32 v79, 0xffff0000, v76
	v_lshlrev_b32_e32 v76, 16, v77
	v_and_b32_e32 v77, 0xffff0000, v77
	v_pk_fma_f32 v[68:69], v[74:75], v[78:79], v[68:69]
	v_pk_fma_f32 v[70:71], v[72:73], v[76:77], v[70:71]
	v_cvt_pk_bf16_f32 v68, v68, v69
	v_cvt_pk_bf16_f32 v69, v70, v71
	global_store_dwordx2 v[92:93], v[68:69], off offset:192
	global_load_dwordx2 v[68:69], v[92:93], off offset:224
	s_waitcnt vmcnt(0)
	v_lshlrev_b32_e32 v70, 16, v68
	global_load_dwordx2 v[72:73], v[94:95], off offset:224
	v_and_b32_e32 v71, 0xffff0000, v68
	v_lshlrev_b32_e32 v68, 16, v69
	v_and_b32_e32 v69, 0xffff0000, v69
	v_pk_add_f32 v[70:71], v[70:71], v[64:65] neg_lo:[0,1] neg_hi:[0,1]
	v_pk_add_f32 v[68:69], v[68:69], v[66:67] neg_lo:[0,1] neg_hi:[0,1]
	s_waitcnt vmcnt(0)
	v_lshlrev_b32_e32 v74, 16, v72
	v_and_b32_e32 v75, 0xffff0000, v72
	v_lshlrev_b32_e32 v72, 16, v73
	v_and_b32_e32 v73, 0xffff0000, v73
	v_pk_fma_f32 v[64:65], v[70:71], v[74:75], v[64:65]
	v_pk_fma_f32 v[66:67], v[68:69], v[72:73], v[66:67]
	v_cvt_pk_bf16_f32 v64, v64, v65
	v_cvt_pk_bf16_f32 v65, v66, v67
	global_store_dwordx2 v[92:93], v[64:65], off offset:224
	v_lshl_add_u64 v[64:65], s[64:65], 0, v[174:175]
	v_lshl_add_u64 v[64:65], v[64:65], 0, v[152:153]
	global_load_dwordx2 v[66:67], v[64:65], off
	s_waitcnt vmcnt(0)
	v_lshlrev_b32_e32 v68, 16, v66
	v_and_b32_e32 v69, 0xffff0000, v66
	v_lshlrev_b32_e32 v70, 16, v67
	v_and_b32_e32 v71, 0xffff0000, v67
	v_lshl_add_u64 v[66:67], v[172:173], 0, v[152:153]
	global_load_dwordx2 v[72:73], v[66:67], off
	v_pk_add_f32 v[68:69], v[68:69], v[60:61] neg_lo:[0,1] neg_hi:[0,1]
	s_waitcnt vmcnt(0)
	v_lshlrev_b32_e32 v74, 16, v72
	v_and_b32_e32 v75, 0xffff0000, v72
	v_lshlrev_b32_e32 v72, 16, v73
	v_and_b32_e32 v73, 0xffff0000, v73
	v_pk_fma_f32 v[60:61], v[68:69], v[74:75], v[60:61]
	v_pk_add_f32 v[68:69], v[70:71], v[62:63] neg_lo:[0,1] neg_hi:[0,1]
	v_cvt_pk_bf16_f32 v60, v60, v61
	v_pk_fma_f32 v[62:63], v[68:69], v[72:73], v[62:63]
	s_nop 0
	v_cvt_pk_bf16_f32 v61, v62, v63
	global_store_dwordx2 v[64:65], v[60:61], off
	global_load_dwordx2 v[60:61], v[64:65], off offset:32
	s_waitcnt vmcnt(0)
	v_lshlrev_b32_e32 v62, 16, v60
	global_load_dwordx2 v[68:69], v[66:67], off offset:32
	v_and_b32_e32 v63, 0xffff0000, v60
	v_lshlrev_b32_e32 v60, 16, v61
	v_and_b32_e32 v61, 0xffff0000, v61
	v_pk_add_f32 v[62:63], v[62:63], v[56:57] neg_lo:[0,1] neg_hi:[0,1]
	v_pk_add_f32 v[60:61], v[60:61], v[58:59] neg_lo:[0,1] neg_hi:[0,1]
	s_waitcnt vmcnt(0)
	v_lshlrev_b32_e32 v70, 16, v68
	v_and_b32_e32 v71, 0xffff0000, v68
	v_lshlrev_b32_e32 v68, 16, v69
	v_and_b32_e32 v69, 0xffff0000, v69
	v_pk_fma_f32 v[56:57], v[62:63], v[70:71], v[56:57]
	v_pk_fma_f32 v[58:59], v[60:61], v[68:69], v[58:59]
	v_cvt_pk_bf16_f32 v56, v56, v57
	v_cvt_pk_bf16_f32 v57, v58, v59
	global_store_dwordx2 v[64:65], v[56:57], off offset:32
	global_load_dwordx2 v[56:57], v[64:65], off offset:64
	s_waitcnt vmcnt(0)
	v_lshlrev_b32_e32 v58, 16, v56
	global_load_dwordx2 v[60:61], v[66:67], off offset:64
	v_and_b32_e32 v59, 0xffff0000, v56
	v_lshlrev_b32_e32 v56, 16, v57
	v_and_b32_e32 v57, 0xffff0000, v57
	v_pk_add_f32 v[58:59], v[58:59], v[52:53] neg_lo:[0,1] neg_hi:[0,1]
	v_pk_add_f32 v[56:57], v[56:57], v[54:55] neg_lo:[0,1] neg_hi:[0,1]
	s_waitcnt vmcnt(0)
	v_lshlrev_b32_e32 v62, 16, v60
	v_and_b32_e32 v63, 0xffff0000, v60
	v_lshlrev_b32_e32 v60, 16, v61
	v_and_b32_e32 v61, 0xffff0000, v61
	v_pk_fma_f32 v[52:53], v[58:59], v[62:63], v[52:53]
	v_pk_fma_f32 v[54:55], v[56:57], v[60:61], v[54:55]
	v_cvt_pk_bf16_f32 v52, v52, v53
	v_cvt_pk_bf16_f32 v53, v54, v55
	global_store_dwordx2 v[64:65], v[52:53], off offset:64
	global_load_dwordx2 v[52:53], v[64:65], off offset:96
	s_waitcnt vmcnt(0)
	v_lshlrev_b32_e32 v54, 16, v52
	global_load_dwordx2 v[56:57], v[66:67], off offset:96
	v_and_b32_e32 v55, 0xffff0000, v52
	v_lshlrev_b32_e32 v52, 16, v53
	v_and_b32_e32 v53, 0xffff0000, v53
	v_pk_add_f32 v[54:55], v[54:55], v[48:49] neg_lo:[0,1] neg_hi:[0,1]
	v_pk_add_f32 v[52:53], v[52:53], v[50:51] neg_lo:[0,1] neg_hi:[0,1]
	s_waitcnt vmcnt(0)
	v_lshlrev_b32_e32 v58, 16, v56
	v_and_b32_e32 v59, 0xffff0000, v56
	v_lshlrev_b32_e32 v56, 16, v57
	v_and_b32_e32 v57, 0xffff0000, v57
	v_pk_fma_f32 v[48:49], v[54:55], v[58:59], v[48:49]
	v_pk_fma_f32 v[50:51], v[52:53], v[56:57], v[50:51]
	v_cvt_pk_bf16_f32 v48, v48, v49
	v_cvt_pk_bf16_f32 v49, v50, v51
	global_store_dwordx2 v[64:65], v[48:49], off offset:96
	global_load_dwordx2 v[48:49], v[64:65], off offset:128
	s_waitcnt vmcnt(0)
	v_lshlrev_b32_e32 v50, 16, v48
	global_load_dwordx2 v[52:53], v[66:67], off offset:128
	v_and_b32_e32 v51, 0xffff0000, v48
	v_lshlrev_b32_e32 v48, 16, v49
	v_and_b32_e32 v49, 0xffff0000, v49
	v_pk_add_f32 v[50:51], v[50:51], v[44:45] neg_lo:[0,1] neg_hi:[0,1]
	v_pk_add_f32 v[48:49], v[48:49], v[46:47] neg_lo:[0,1] neg_hi:[0,1]
	s_waitcnt vmcnt(0)
	v_lshlrev_b32_e32 v54, 16, v52
	v_and_b32_e32 v55, 0xffff0000, v52
	v_lshlrev_b32_e32 v52, 16, v53
	v_and_b32_e32 v53, 0xffff0000, v53
	v_pk_fma_f32 v[44:45], v[50:51], v[54:55], v[44:45]
	v_pk_fma_f32 v[46:47], v[48:49], v[52:53], v[46:47]
	v_cvt_pk_bf16_f32 v44, v44, v45
	v_cvt_pk_bf16_f32 v45, v46, v47
	global_store_dwordx2 v[64:65], v[44:45], off offset:128
	global_load_dwordx2 v[44:45], v[64:65], off offset:160
	s_waitcnt vmcnt(0)
	v_lshlrev_b32_e32 v46, 16, v44
	global_load_dwordx2 v[48:49], v[66:67], off offset:160
	v_and_b32_e32 v47, 0xffff0000, v44
	v_lshlrev_b32_e32 v44, 16, v45
	v_and_b32_e32 v45, 0xffff0000, v45
	v_pk_add_f32 v[46:47], v[46:47], v[40:41] neg_lo:[0,1] neg_hi:[0,1]
	v_pk_add_f32 v[44:45], v[44:45], v[42:43] neg_lo:[0,1] neg_hi:[0,1]
	s_waitcnt vmcnt(0)
	v_lshlrev_b32_e32 v50, 16, v48
	v_and_b32_e32 v51, 0xffff0000, v48
	v_lshlrev_b32_e32 v48, 16, v49
	v_and_b32_e32 v49, 0xffff0000, v49
	v_pk_fma_f32 v[40:41], v[46:47], v[50:51], v[40:41]
	v_pk_fma_f32 v[42:43], v[44:45], v[48:49], v[42:43]
	v_cvt_pk_bf16_f32 v40, v40, v41
	v_cvt_pk_bf16_f32 v41, v42, v43
	global_store_dwordx2 v[64:65], v[40:41], off offset:160
	global_load_dwordx2 v[40:41], v[64:65], off offset:192
	s_waitcnt vmcnt(0)
	v_lshlrev_b32_e32 v42, 16, v40
	global_load_dwordx2 v[44:45], v[66:67], off offset:192
	v_and_b32_e32 v43, 0xffff0000, v40
	v_lshlrev_b32_e32 v40, 16, v41
	v_and_b32_e32 v41, 0xffff0000, v41
	v_pk_add_f32 v[42:43], v[42:43], v[36:37] neg_lo:[0,1] neg_hi:[0,1]
	v_pk_add_f32 v[40:41], v[40:41], v[38:39] neg_lo:[0,1] neg_hi:[0,1]
	s_waitcnt vmcnt(0)
	v_lshlrev_b32_e32 v46, 16, v44
	v_and_b32_e32 v47, 0xffff0000, v44
	v_lshlrev_b32_e32 v44, 16, v45
	v_and_b32_e32 v45, 0xffff0000, v45
	v_pk_fma_f32 v[36:37], v[42:43], v[46:47], v[36:37]
	v_pk_fma_f32 v[38:39], v[40:41], v[44:45], v[38:39]
	v_cvt_pk_bf16_f32 v36, v36, v37
	v_cvt_pk_bf16_f32 v37, v38, v39
	global_store_dwordx2 v[64:65], v[36:37], off offset:192
	global_load_dwordx2 v[36:37], v[64:65], off offset:224
	s_waitcnt vmcnt(0)
	v_lshlrev_b32_e32 v38, 16, v36
	global_load_dwordx2 v[40:41], v[66:67], off offset:224
	v_and_b32_e32 v39, 0xffff0000, v36
	v_lshlrev_b32_e32 v36, 16, v37
	v_and_b32_e32 v37, 0xffff0000, v37
	v_pk_add_f32 v[38:39], v[38:39], v[32:33] neg_lo:[0,1] neg_hi:[0,1]
	v_pk_add_f32 v[36:37], v[36:37], v[34:35] neg_lo:[0,1] neg_hi:[0,1]
	s_waitcnt vmcnt(0)
	v_lshlrev_b32_e32 v42, 16, v40
	v_and_b32_e32 v43, 0xffff0000, v40
	v_lshlrev_b32_e32 v40, 16, v41
	v_and_b32_e32 v41, 0xffff0000, v41
	v_pk_fma_f32 v[32:33], v[38:39], v[42:43], v[32:33]
	v_pk_fma_f32 v[34:35], v[36:37], v[40:41], v[34:35]
	v_cvt_pk_bf16_f32 v32, v32, v33
	v_cvt_pk_bf16_f32 v33, v34, v35
	global_store_dwordx2 v[64:65], v[32:33], off offset:224
	v_lshl_add_u64 v[32:33], s[64:65], 0, v[170:171]
	v_lshl_add_u64 v[32:33], v[32:33], 0, v[152:153]
	global_load_dwordx2 v[34:35], v[32:33], off
	s_waitcnt vmcnt(0)
	v_lshlrev_b32_e32 v36, 16, v34
	v_and_b32_e32 v37, 0xffff0000, v34
	v_lshlrev_b32_e32 v38, 16, v35
	v_and_b32_e32 v39, 0xffff0000, v35
	v_lshl_add_u64 v[34:35], v[168:169], 0, v[152:153]
	global_load_dwordx2 v[40:41], v[34:35], off
	v_pk_add_f32 v[36:37], v[36:37], v[28:29] neg_lo:[0,1] neg_hi:[0,1]
	s_waitcnt vmcnt(0)
	v_lshlrev_b32_e32 v42, 16, v40
	v_and_b32_e32 v43, 0xffff0000, v40
	v_lshlrev_b32_e32 v40, 16, v41
	v_and_b32_e32 v41, 0xffff0000, v41
	v_pk_fma_f32 v[28:29], v[36:37], v[42:43], v[28:29]
	v_pk_add_f32 v[36:37], v[38:39], v[30:31] neg_lo:[0,1] neg_hi:[0,1]
	v_cvt_pk_bf16_f32 v28, v28, v29
	v_pk_fma_f32 v[30:31], v[36:37], v[40:41], v[30:31]
	s_nop 0
	v_cvt_pk_bf16_f32 v29, v30, v31
	global_store_dwordx2 v[32:33], v[28:29], off
	global_load_dwordx2 v[28:29], v[32:33], off offset:32
	s_waitcnt vmcnt(0)
	v_lshlrev_b32_e32 v30, 16, v28
	global_load_dwordx2 v[36:37], v[34:35], off offset:32
	v_and_b32_e32 v31, 0xffff0000, v28
	v_lshlrev_b32_e32 v28, 16, v29
	v_and_b32_e32 v29, 0xffff0000, v29
	v_pk_add_f32 v[30:31], v[30:31], v[24:25] neg_lo:[0,1] neg_hi:[0,1]
	v_pk_add_f32 v[28:29], v[28:29], v[26:27] neg_lo:[0,1] neg_hi:[0,1]
	s_waitcnt vmcnt(0)
	v_lshlrev_b32_e32 v38, 16, v36
	v_and_b32_e32 v39, 0xffff0000, v36
	v_lshlrev_b32_e32 v36, 16, v37
	v_and_b32_e32 v37, 0xffff0000, v37
	v_pk_fma_f32 v[24:25], v[30:31], v[38:39], v[24:25]
	v_pk_fma_f32 v[26:27], v[28:29], v[36:37], v[26:27]
	v_cvt_pk_bf16_f32 v24, v24, v25
	v_cvt_pk_bf16_f32 v25, v26, v27
	global_store_dwordx2 v[32:33], v[24:25], off offset:32
	global_load_dwordx2 v[24:25], v[32:33], off offset:64
	s_waitcnt vmcnt(0)
	v_lshlrev_b32_e32 v26, 16, v24
	global_load_dwordx2 v[28:29], v[34:35], off offset:64
	v_and_b32_e32 v27, 0xffff0000, v24
	v_lshlrev_b32_e32 v24, 16, v25
	v_and_b32_e32 v25, 0xffff0000, v25
	v_pk_add_f32 v[26:27], v[26:27], v[20:21] neg_lo:[0,1] neg_hi:[0,1]
	v_pk_add_f32 v[24:25], v[24:25], v[22:23] neg_lo:[0,1] neg_hi:[0,1]
	s_waitcnt vmcnt(0)
	v_lshlrev_b32_e32 v30, 16, v28
	v_and_b32_e32 v31, 0xffff0000, v28
	v_lshlrev_b32_e32 v28, 16, v29
	v_and_b32_e32 v29, 0xffff0000, v29
	v_pk_fma_f32 v[20:21], v[26:27], v[30:31], v[20:21]
	v_pk_fma_f32 v[22:23], v[24:25], v[28:29], v[22:23]
	v_cvt_pk_bf16_f32 v20, v20, v21
	v_cvt_pk_bf16_f32 v21, v22, v23
	global_store_dwordx2 v[32:33], v[20:21], off offset:64
	global_load_dwordx2 v[20:21], v[32:33], off offset:96
	s_waitcnt vmcnt(0)
	v_lshlrev_b32_e32 v22, 16, v20
	global_load_dwordx2 v[24:25], v[34:35], off offset:96
	v_and_b32_e32 v23, 0xffff0000, v20
	v_lshlrev_b32_e32 v20, 16, v21
	v_and_b32_e32 v21, 0xffff0000, v21
	v_pk_add_f32 v[22:23], v[22:23], v[16:17] neg_lo:[0,1] neg_hi:[0,1]
	v_pk_add_f32 v[20:21], v[20:21], v[18:19] neg_lo:[0,1] neg_hi:[0,1]
	s_waitcnt vmcnt(0)
	v_lshlrev_b32_e32 v26, 16, v24
	v_and_b32_e32 v27, 0xffff0000, v24
	v_lshlrev_b32_e32 v24, 16, v25
	v_and_b32_e32 v25, 0xffff0000, v25
	v_pk_fma_f32 v[16:17], v[22:23], v[26:27], v[16:17]
	v_pk_fma_f32 v[18:19], v[20:21], v[24:25], v[18:19]
	v_cvt_pk_bf16_f32 v16, v16, v17
	v_cvt_pk_bf16_f32 v17, v18, v19
	global_store_dwordx2 v[32:33], v[16:17], off offset:96
	global_load_dwordx2 v[16:17], v[32:33], off offset:128
	s_waitcnt vmcnt(0)
	v_lshlrev_b32_e32 v18, 16, v16
	global_load_dwordx2 v[20:21], v[34:35], off offset:128
	v_and_b32_e32 v19, 0xffff0000, v16
	v_lshlrev_b32_e32 v16, 16, v17
	v_and_b32_e32 v17, 0xffff0000, v17
	v_pk_add_f32 v[18:19], v[18:19], v[12:13] neg_lo:[0,1] neg_hi:[0,1]
	v_pk_add_f32 v[16:17], v[16:17], v[14:15] neg_lo:[0,1] neg_hi:[0,1]
	s_waitcnt vmcnt(0)
	v_lshlrev_b32_e32 v22, 16, v20
	v_and_b32_e32 v23, 0xffff0000, v20
	v_lshlrev_b32_e32 v20, 16, v21
	v_and_b32_e32 v21, 0xffff0000, v21
	v_pk_fma_f32 v[12:13], v[18:19], v[22:23], v[12:13]
	v_pk_fma_f32 v[14:15], v[16:17], v[20:21], v[14:15]
	v_cvt_pk_bf16_f32 v12, v12, v13
	v_cvt_pk_bf16_f32 v13, v14, v15
	global_store_dwordx2 v[32:33], v[12:13], off offset:128
	global_load_dwordx2 v[12:13], v[32:33], off offset:160
	s_waitcnt vmcnt(0)
	v_lshlrev_b32_e32 v14, 16, v12
	global_load_dwordx2 v[16:17], v[34:35], off offset:160
	v_and_b32_e32 v15, 0xffff0000, v12
	v_lshlrev_b32_e32 v12, 16, v13
	v_and_b32_e32 v13, 0xffff0000, v13
	v_pk_add_f32 v[14:15], v[14:15], v[8:9] neg_lo:[0,1] neg_hi:[0,1]
	v_pk_add_f32 v[12:13], v[12:13], v[10:11] neg_lo:[0,1] neg_hi:[0,1]
	s_waitcnt vmcnt(0)
	v_lshlrev_b32_e32 v18, 16, v16
	v_and_b32_e32 v19, 0xffff0000, v16
	v_lshlrev_b32_e32 v16, 16, v17
	v_and_b32_e32 v17, 0xffff0000, v17
	v_pk_fma_f32 v[8:9], v[14:15], v[18:19], v[8:9]
	v_pk_fma_f32 v[10:11], v[12:13], v[16:17], v[10:11]
	v_cvt_pk_bf16_f32 v8, v8, v9
	v_cvt_pk_bf16_f32 v9, v10, v11
	global_store_dwordx2 v[32:33], v[8:9], off offset:160
	global_load_dwordx2 v[8:9], v[32:33], off offset:192
	s_waitcnt vmcnt(0)
	v_lshlrev_b32_e32 v10, 16, v8
	global_load_dwordx2 v[12:13], v[34:35], off offset:192
	v_and_b32_e32 v11, 0xffff0000, v8
	v_lshlrev_b32_e32 v8, 16, v9
	v_and_b32_e32 v9, 0xffff0000, v9
	v_pk_add_f32 v[10:11], v[10:11], v[4:5] neg_lo:[0,1] neg_hi:[0,1]
	v_pk_add_f32 v[8:9], v[8:9], v[6:7] neg_lo:[0,1] neg_hi:[0,1]
	s_waitcnt vmcnt(0)
	v_lshlrev_b32_e32 v14, 16, v12
	v_and_b32_e32 v15, 0xffff0000, v12
	v_lshlrev_b32_e32 v12, 16, v13
	v_and_b32_e32 v13, 0xffff0000, v13
	v_pk_fma_f32 v[4:5], v[10:11], v[14:15], v[4:5]
	v_pk_fma_f32 v[6:7], v[8:9], v[12:13], v[6:7]
	v_cvt_pk_bf16_f32 v4, v4, v5
	v_cvt_pk_bf16_f32 v5, v6, v7
	global_store_dwordx2 v[32:33], v[4:5], off offset:192
	global_load_dwordx2 v[4:5], v[32:33], off offset:224
	s_waitcnt vmcnt(0)
	v_lshlrev_b32_e32 v6, 16, v4
	global_load_dwordx2 v[8:9], v[34:35], off offset:224
	v_and_b32_e32 v7, 0xffff0000, v4
	v_lshlrev_b32_e32 v4, 16, v5
	v_and_b32_e32 v5, 0xffff0000, v5
	v_pk_add_f32 v[6:7], v[6:7], v[0:1] neg_lo:[0,1] neg_hi:[0,1]
	v_pk_add_f32 v[4:5], v[4:5], v[2:3] neg_lo:[0,1] neg_hi:[0,1]
	s_waitcnt vmcnt(0)
	v_lshlrev_b32_e32 v10, 16, v8
	v_and_b32_e32 v11, 0xffff0000, v8
	v_lshlrev_b32_e32 v8, 16, v9
	v_and_b32_e32 v9, 0xffff0000, v9
	v_pk_fma_f32 v[0:1], v[6:7], v[10:11], v[0:1]
	v_pk_fma_f32 v[2:3], v[4:5], v[8:9], v[2:3]
	v_cvt_pk_bf16_f32 v0, v0, v1
	v_cvt_pk_bf16_f32 v1, v2, v3
	global_store_dwordx2 v[32:33], v[0:1], off offset:224
	s_cbranch_scc1 .LBB0_304

.LBB0_344:
	s_waitcnt vmcnt(5)
	ds_write_b128 v154, v[124:127]
	s_waitcnt vmcnt(4)
	ds_write_b128 v154, v[132:135] offset:6144
	s_waitcnt vmcnt(3)
	ds_write_b128 v154, v[136:139] offset:12288
	s_waitcnt vmcnt(2)
	ds_write_b128 v154, v[140:143] offset:18432
	s_waitcnt vmcnt(1)
	ds_write_b128 v154, v[144:147] offset:24576
	s_waitcnt vmcnt(0)
	ds_write_b128 v154, v[148:151] offset:30720
	v_lshl_add_u64 v[132:133], v[174:175], 0, s[0:1]
	s_mov_b32 s2, 0x6000000
	v_add_co_u32_e32 v140, vcc, s2, v132
	s_mov_b32 s2, 0x6040000
	s_nop 0
	v_addc_co_u32_e32 v141, vcc, 0, v133, vcc
	v_add_co_u32_e32 v132, vcc, s2, v132
	s_waitcnt lgkmcnt(0)
	s_barrier
	ds_read_b128 v[124:127], v180 offset:12288
	ds_read_b128 v[136:139], v180 offset:13824
	ds_read_b128 v[184:187], v179
	ds_read_b128 v[200:203], v179 offset:1536
	ds_read_b128 v[148:151], v180 offset:15360
	ds_read_b128 v[204:207], v180 offset:16896
	v_lshl_add_u64 v[134:135], v[176:177], 0, s[0:1]
	v_addc_co_u32_e32 v133, vcc, 0, v133, vcc
	s_brev_b32 s2, 64
	v_add_co_u32_e32 v142, vcc, s2, v134
	s_mov_b32 s2, 0x2040000
	s_nop 0
	v_addc_co_u32_e32 v143, vcc, 0, v135, vcc
	ds_read_b128 v[208:211], v179 offset:3072
	ds_read_b128 v[212:215], v179 offset:4608
	v_add_co_u32_e32 v144, vcc, s2, v134
	s_mov_b32 s2, 0x2080000
	s_nop 0
	v_addc_co_u32_e32 v145, vcc, 0, v135, vcc
	v_add_co_u32_e32 v146, vcc, s2, v134
	s_mov_b32 s2, 0x20c0000
	s_nop 0
	v_addc_co_u32_e32 v147, vcc, 0, v135, vcc
	v_add_co_u32_e32 v216, vcc, s2, v134
	s_waitcnt lgkmcnt(5)
	v_mfma_f32_16x16x32_bf16 v[128:131], v[124:127], v[184:187], v[128:131]
	v_addc_co_u32_e32 v217, vcc, 0, v135, vcc
	v_mfma_f32_16x16x32_bf16 v[120:123], v[136:139], v[184:187], v[120:123]
	s_waitcnt lgkmcnt(4)
	v_mfma_f32_16x16x32_bf16 v[108:111], v[124:127], v[200:203], v[108:111]
	v_mfma_f32_16x16x32_bf16 v[104:107], v[136:139], v[200:203], v[104:107]
	s_waitcnt lgkmcnt(1)
	v_mfma_f32_16x16x32_bf16 v[76:79], v[124:127], v[208:211], v[76:79]
	v_mfma_f32_16x16x32_bf16 v[72:75], v[136:139], v[208:211], v[72:75]
	s_waitcnt lgkmcnt(0)
	v_mfma_f32_16x16x32_bf16 v[44:47], v[124:127], v[212:215], v[44:47]
	global_load_dwordx4 v[124:127], v[140:141], off offset:64
	s_nop 0
	global_load_dwordx4 v[132:135], v[132:133], off offset:64
	v_mfma_f32_16x16x32_bf16 v[40:43], v[136:139], v[212:215], v[40:43]
	global_load_dwordx4 v[136:139], v[142:143], off offset:64
	s_nop 0
	global_load_dwordx4 v[140:143], v[144:145], off offset:64
	s_nop 0
	global_load_dwordx4 v[144:147], v[146:147], off offset:64
	v_mfma_f32_16x16x32_bf16 v[116:119], v[148:151], v[184:187], v[116:119]
	v_mfma_f32_16x16x32_bf16 v[96:99], v[148:151], v[200:203], v[96:99]
	v_mfma_f32_16x16x32_bf16 v[64:67], v[148:151], v[208:211], v[64:67]
	v_mfma_f32_16x16x32_bf16 v[32:35], v[148:151], v[212:215], v[32:35]
	global_load_dwordx4 v[148:151], v[216:217], off offset:64
	v_mfma_f32_16x16x32_bf16 v[112:115], v[204:207], v[184:187], v[112:115]
	v_mfma_f32_16x16x32_bf16 v[88:91], v[204:207], v[200:203], v[88:91]
	v_mfma_f32_16x16x32_bf16 v[56:59], v[204:207], v[208:211], v[56:59]
	v_mfma_f32_16x16x32_bf16 v[24:27], v[204:207], v[212:215], v[24:27]
	ds_read_b128 v[204:207], v180 offset:18432
	ds_read_b128 v[216:219], v180 offset:19968
	ds_read_b128 v[220:223], v180 offset:21504
	ds_read_b128 v[224:227], v180 offset:23040
	s_waitcnt lgkmcnt(3)
	v_mfma_f32_16x16x32_bf16 v[100:103], v[204:207], v[184:187], v[100:103]
	s_waitcnt lgkmcnt(2)
	v_mfma_f32_16x16x32_bf16 v[92:95], v[216:219], v[184:187], v[92:95]
	s_waitcnt lgkmcnt(1)
	v_mfma_f32_16x16x32_bf16 v[84:87], v[220:223], v[184:187], v[84:87]
	s_waitcnt lgkmcnt(0)
	s_barrier
	v_mfma_f32_16x16x32_bf16 v[80:83], v[224:227], v[184:187], v[80:83]
	v_mfma_f32_16x16x32_bf16 v[68:71], v[204:207], v[200:203], v[68:71]
	v_mfma_f32_16x16x32_bf16 v[60:63], v[216:219], v[200:203], v[60:63]
	v_mfma_f32_16x16x32_bf16 v[52:55], v[220:223], v[200:203], v[52:55]
	v_mfma_f32_16x16x32_bf16 v[48:51], v[224:227], v[200:203], v[48:51]
	v_mfma_f32_16x16x32_bf16 v[36:39], v[204:207], v[208:211], v[36:39]
	v_mfma_f32_16x16x32_bf16 v[28:31], v[216:219], v[208:211], v[28:31]
	v_mfma_f32_16x16x32_bf16 v[20:23], v[220:223], v[208:211], v[20:23]
	v_mfma_f32_16x16x32_bf16 v[16:19], v[224:227], v[208:211], v[16:19]
	v_mfma_f32_16x16x32_bf16 v[12:15], v[204:207], v[212:215], v[12:15]
	v_mfma_f32_16x16x32_bf16 v[8:11], v[216:219], v[212:215], v[8:11]
	v_mfma_f32_16x16x32_bf16 v[4:7], v[220:223], v[212:215], v[4:7]
	v_mfma_f32_16x16x32_bf16 v[0:3], v[224:227], v[212:215], v[0:3]
	s_add_u32 s0, s0, 64
	s_addc_u32 s1, s1, 0
	s_cmpk_lg_i32 s0, 0xfc0
	s_cbranch_scc1 .LBB0_344
	s_waitcnt vmcnt(5)
	ds_write_b128 v154, v[124:127]
	s_waitcnt vmcnt(4)
	ds_write_b128 v154, v[132:135] offset:6144
	s_waitcnt vmcnt(3)
	ds_write_b128 v154, v[136:139] offset:12288
	s_waitcnt vmcnt(2)
	ds_write_b128 v154, v[140:143] offset:18432
	s_waitcnt vmcnt(1)
	ds_write_b128 v154, v[144:147] offset:24576
	s_waitcnt vmcnt(0)
	ds_write_b128 v154, v[148:151] offset:30720
	s_waitcnt lgkmcnt(0)
	s_barrier
	ds_read_b128 v[136:139], v180 offset:12288
	ds_read_b128 v[140:143], v180 offset:13824
	ds_read_b128 v[144:147], v179
	ds_read_b128 v[148:151], v179 offset:1536
	s_waitcnt lgkmcnt(1)
	v_mfma_f32_16x16x32_bf16 v[124:127], v[136:139], v[144:147], v[128:131]
	s_nop 2
	ds_read_b128 v[128:131], v180 offset:15360
	ds_read_b128 v[174:177], v180 offset:16896
	v_mfma_f32_16x16x32_bf16 v[120:123], v[140:143], v[144:147], v[120:123]
	s_waitcnt lgkmcnt(1)
	v_mfma_f32_16x16x32_bf16 v[132:135], v[128:131], v[144:147], v[116:119]
	s_waitcnt lgkmcnt(0)
	v_mfma_f32_16x16x32_bf16 v[116:119], v[174:177], v[144:147], v[112:115]
	s_nop 2
	ds_read_b128 v[112:115], v179 offset:3072
	ds_read_b128 v[184:187], v179 offset:4608
	v_mfma_f32_16x16x32_bf16 v[108:111], v[136:139], v[148:151], v[108:111]
	v_mfma_f32_16x16x32_bf16 v[104:107], v[140:143], v[148:151], v[104:107]
	v_mfma_f32_16x16x32_bf16 v[96:99], v[128:131], v[148:151], v[96:99]
	v_mfma_f32_16x16x32_bf16 v[88:91], v[174:177], v[148:151], v[88:91]
	s_waitcnt lgkmcnt(1)
	v_mfma_f32_16x16x32_bf16 v[76:79], v[136:139], v[112:115], v[76:79]
	v_mfma_f32_16x16x32_bf16 v[72:75], v[140:143], v[112:115], v[72:75]
	v_mfma_f32_16x16x32_bf16 v[64:67], v[128:131], v[112:115], v[64:67]
	v_mfma_f32_16x16x32_bf16 v[56:59], v[174:177], v[112:115], v[56:59]
	s_waitcnt lgkmcnt(0)
	v_mfma_f32_16x16x32_bf16 v[44:47], v[136:139], v[184:187], v[44:47]
	v_mfma_f32_16x16x32_bf16 v[40:43], v[140:143], v[184:187], v[40:43]
	v_mfma_f32_16x16x32_bf16 v[32:35], v[128:131], v[184:187], v[32:35]
	v_mfma_f32_16x16x32_bf16 v[24:27], v[174:177], v[184:187], v[24:27]
	ds_read_b128 v[128:131], v180 offset:18432
	ds_read_b128 v[136:139], v180 offset:19968
	ds_read_b128 v[140:143], v180 offset:21504
	ds_read_b128 v[174:177], v180 offset:23040
	s_waitcnt lgkmcnt(3)
	v_mfma_f32_16x16x32_bf16 v[100:103], v[128:131], v[144:147], v[100:103]
	s_waitcnt lgkmcnt(2)
	v_mfma_f32_16x16x32_bf16 v[92:95], v[136:139], v[144:147], v[92:95]
	s_waitcnt lgkmcnt(1)
	v_mfma_f32_16x16x32_bf16 v[84:87], v[140:143], v[144:147], v[84:87]
	s_waitcnt lgkmcnt(0)
	v_mfma_f32_16x16x32_bf16 v[80:83], v[174:177], v[144:147], v[80:83]
	v_mfma_f32_16x16x32_bf16 v[68:71], v[128:131], v[148:151], v[68:71]
	v_mfma_f32_16x16x32_bf16 v[60:63], v[136:139], v[148:151], v[60:63]
	v_mfma_f32_16x16x32_bf16 v[52:55], v[140:143], v[148:151], v[52:55]
	v_mfma_f32_16x16x32_bf16 v[48:51], v[174:177], v[148:151], v[48:51]
	v_mfma_f32_16x16x32_bf16 v[36:39], v[128:131], v[112:115], v[36:39]
	v_mfma_f32_16x16x32_bf16 v[28:31], v[136:139], v[112:115], v[28:31]
	v_mfma_f32_16x16x32_bf16 v[20:23], v[140:143], v[112:115], v[20:23]
	v_mfma_f32_16x16x32_bf16 v[16:19], v[174:177], v[112:115], v[16:19]
	v_mfma_f32_16x16x32_bf16 v[12:15], v[128:131], v[184:187], v[12:15]
	v_mfma_f32_16x16x32_bf16 v[8:11], v[136:139], v[184:187], v[8:11]
	v_mfma_f32_16x16x32_bf16 v[4:7], v[140:143], v[184:187], v[4:7]
	v_mfma_f32_16x16x32_bf16 v[0:3], v[174:177], v[184:187], v[0:3]
	s_mov_b64 s[2:3], 0
	s_mov_b64 s[0:1], s[62:63]
	s_barrier

.LBB0_348:
	s_waitcnt vmcnt(5)
	ds_write_b128 v154, v[108:111]
	s_waitcnt vmcnt(4)
	ds_write_b128 v154, v[116:119] offset:6144
	s_waitcnt vmcnt(3)
	ds_write_b128 v154, v[120:123] offset:12288
	s_waitcnt vmcnt(2)
	ds_write_b128 v154, v[124:127] offset:18432
	s_waitcnt vmcnt(1)
	ds_write_b128 v154, v[136:139] offset:24576
	s_waitcnt vmcnt(0)
	ds_write_b128 v154, v[140:143] offset:30720
	v_lshl_add_u64 v[116:117], v[172:173], 0, s[0:1]
	v_add_co_u32_e32 v124, vcc, s69, v116
	s_waitcnt lgkmcnt(0)
	s_barrier
	ds_read_b128 v[108:111], v180 offset:12288
	ds_read_b128 v[120:123], v180 offset:13824
	ds_read_b128 v[174:177], v179
	ds_read_b128 v[184:187], v179 offset:1536
	ds_read_b128 v[140:143], v180 offset:15360
	ds_read_b128 v[200:203], v180 offset:16896
	v_lshl_add_u64 v[118:119], v[168:169], 0, s[0:1]
	v_addc_co_u32_e32 v125, vcc, 0, v117, vcc
	v_add_co_u32_e32 v126, vcc, s78, v118
	ds_read_b128 v[204:207], v179 offset:3072
	ds_read_b128 v[208:211], v179 offset:4608
	v_addc_co_u32_e32 v127, vcc, 0, v119, vcc
	v_add_co_u32_e32 v136, vcc, s79, v118
	s_waitcnt lgkmcnt(5)
	v_mfma_f32_16x16x32_bf16 v[148:151], v[108:111], v[174:177], v[148:151]
	v_addc_co_u32_e32 v137, vcc, 0, v119, vcc
	v_add_co_u32_e32 v138, vcc, s80, v118
	v_mfma_f32_16x16x32_bf16 v[144:147], v[120:123], v[174:177], v[144:147]
	s_nop 0
	v_addc_co_u32_e32 v139, vcc, 0, v119, vcc
	v_add_co_u32_e32 v170, vcc, s81, v118
	s_waitcnt lgkmcnt(4)
	v_mfma_f32_16x16x32_bf16 v[112:115], v[108:111], v[184:187], v[112:115]
	v_addc_co_u32_e32 v171, vcc, 0, v119, vcc
	v_mfma_f32_16x16x32_bf16 v[104:107], v[120:123], v[184:187], v[104:107]
	s_waitcnt lgkmcnt(1)
	v_mfma_f32_16x16x32_bf16 v[76:79], v[108:111], v[204:207], v[76:79]
	v_mfma_f32_16x16x32_bf16 v[72:75], v[120:123], v[204:207], v[72:75]
	s_waitcnt lgkmcnt(0)
	v_mfma_f32_16x16x32_bf16 v[44:47], v[108:111], v[208:211], v[44:47]
	global_load_dwordx4 v[108:111], v[116:117], off offset:64
	s_nop 0
	global_load_dwordx4 v[116:119], v[124:125], off offset:64
	v_mfma_f32_16x16x32_bf16 v[40:43], v[120:123], v[208:211], v[40:43]
	global_load_dwordx4 v[120:123], v[126:127], off offset:64
	s_nop 0
	global_load_dwordx4 v[124:127], v[136:137], off offset:64
	s_nop 0
	global_load_dwordx4 v[136:139], v[138:139], off offset:64
	v_mfma_f32_16x16x32_bf16 v[132:135], v[140:143], v[174:177], v[132:135]
	v_mfma_f32_16x16x32_bf16 v[96:99], v[140:143], v[184:187], v[96:99]
	v_mfma_f32_16x16x32_bf16 v[64:67], v[140:143], v[204:207], v[64:67]
	v_mfma_f32_16x16x32_bf16 v[32:35], v[140:143], v[208:211], v[32:35]
	global_load_dwordx4 v[140:143], v[170:171], off offset:64
	v_mfma_f32_16x16x32_bf16 v[128:131], v[200:203], v[174:177], v[128:131]
	v_mfma_f32_16x16x32_bf16 v[88:91], v[200:203], v[184:187], v[88:91]
	v_mfma_f32_16x16x32_bf16 v[56:59], v[200:203], v[204:207], v[56:59]
	v_mfma_f32_16x16x32_bf16 v[24:27], v[200:203], v[208:211], v[24:27]
	ds_read_b128 v[200:203], v180 offset:18432
	ds_read_b128 v[212:215], v180 offset:19968
	ds_read_b128 v[216:219], v180 offset:21504
	ds_read_b128 v[220:223], v180 offset:23040
	s_waitcnt lgkmcnt(3)
	v_mfma_f32_16x16x32_bf16 v[100:103], v[200:203], v[174:177], v[100:103]
	s_waitcnt lgkmcnt(2)
	v_mfma_f32_16x16x32_bf16 v[92:95], v[212:215], v[174:177], v[92:95]
	s_waitcnt lgkmcnt(1)
	v_mfma_f32_16x16x32_bf16 v[84:87], v[216:219], v[174:177], v[84:87]
	s_waitcnt lgkmcnt(0)
	s_barrier
	v_mfma_f32_16x16x32_bf16 v[80:83], v[220:223], v[174:177], v[80:83]
	v_mfma_f32_16x16x32_bf16 v[68:71], v[200:203], v[184:187], v[68:71]
	v_mfma_f32_16x16x32_bf16 v[60:63], v[212:215], v[184:187], v[60:63]
	v_mfma_f32_16x16x32_bf16 v[52:55], v[216:219], v[184:187], v[52:55]
	v_mfma_f32_16x16x32_bf16 v[48:51], v[220:223], v[184:187], v[48:51]
	v_mfma_f32_16x16x32_bf16 v[36:39], v[200:203], v[204:207], v[36:39]
	v_mfma_f32_16x16x32_bf16 v[28:31], v[212:215], v[204:207], v[28:31]
	v_mfma_f32_16x16x32_bf16 v[20:23], v[216:219], v[204:207], v[20:23]
	v_mfma_f32_16x16x32_bf16 v[16:19], v[220:223], v[204:207], v[16:19]
	v_mfma_f32_16x16x32_bf16 v[12:15], v[200:203], v[208:211], v[12:15]
	v_mfma_f32_16x16x32_bf16 v[8:11], v[212:215], v[208:211], v[8:11]
	v_mfma_f32_16x16x32_bf16 v[4:7], v[216:219], v[208:211], v[4:7]
	v_mfma_f32_16x16x32_bf16 v[0:3], v[220:223], v[208:211], v[0:3]
	s_add_u32 s0, s0, 64
	s_addc_u32 s1, s1, 0
	s_cmpk_lg_i32 s0, 0xfc0
	s_cbranch_scc1 .LBB0_348
	s_waitcnt vmcnt(5)
	ds_write_b128 v154, v[108:111]
	s_waitcnt vmcnt(4)
	ds_write_b128 v154, v[116:119] offset:6144
	s_waitcnt vmcnt(3)
	ds_write_b128 v154, v[120:123] offset:12288
	s_waitcnt vmcnt(2)
	ds_write_b128 v154, v[124:127] offset:18432
	s_waitcnt vmcnt(1)
	ds_write_b128 v154, v[136:139] offset:24576
	s_waitcnt vmcnt(0)
	ds_write_b128 v154, v[140:143] offset:30720
	s_waitcnt lgkmcnt(0)
	s_barrier
	ds_read_b128 v[136:139], v180 offset:12288
	ds_read_b128 v[140:143], v180 offset:13824
	ds_read_b128 v[168:171], v179
	ds_read_b128 v[172:175], v179 offset:1536
	s_waitcnt lgkmcnt(1)
	v_mfma_f32_16x16x32_bf16 v[124:127], v[136:139], v[168:171], v[148:151]
	s_nop 2
	ds_read_b128 v[148:151], v180 offset:15360
	v_mfma_f32_16x16x32_bf16 v[120:123], v[140:143], v[168:171], v[144:147]
	s_nop 2
	ds_read_b128 v[144:147], v180 offset:16896
	s_waitcnt lgkmcnt(0)
	v_mfma_f32_16x16x32_bf16 v[116:119], v[144:147], v[168:171], v[128:131]
	v_mfma_f32_16x16x32_bf16 v[108:111], v[136:139], v[172:175], v[112:115]
	s_nop 2
	ds_read_b128 v[112:115], v179 offset:3072
	ds_read_b128 v[128:131], v179 offset:4608
	v_mfma_f32_16x16x32_bf16 v[132:135], v[148:151], v[168:171], v[132:135]
	v_mfma_f32_16x16x32_bf16 v[104:107], v[140:143], v[172:175], v[104:107]
	v_mfma_f32_16x16x32_bf16 v[96:99], v[148:151], v[172:175], v[96:99]
	v_mfma_f32_16x16x32_bf16 v[88:91], v[144:147], v[172:175], v[88:91]
	s_waitcnt lgkmcnt(1)
	v_mfma_f32_16x16x32_bf16 v[76:79], v[136:139], v[112:115], v[76:79]
	v_mfma_f32_16x16x32_bf16 v[72:75], v[140:143], v[112:115], v[72:75]
	v_mfma_f32_16x16x32_bf16 v[64:67], v[148:151], v[112:115], v[64:67]
	v_mfma_f32_16x16x32_bf16 v[56:59], v[144:147], v[112:115], v[56:59]
	s_waitcnt lgkmcnt(0)
	v_mfma_f32_16x16x32_bf16 v[44:47], v[136:139], v[128:131], v[44:47]
	v_mfma_f32_16x16x32_bf16 v[40:43], v[140:143], v[128:131], v[40:43]
	v_mfma_f32_16x16x32_bf16 v[32:35], v[148:151], v[128:131], v[32:35]
	v_mfma_f32_16x16x32_bf16 v[24:27], v[144:147], v[128:131], v[24:27]
	ds_read_b128 v[136:139], v180 offset:18432
	ds_read_b128 v[140:143], v180 offset:19968
	ds_read_b128 v[144:147], v180 offset:21504
	ds_read_b128 v[148:151], v180 offset:23040
	s_waitcnt lgkmcnt(3)
	v_mfma_f32_16x16x32_bf16 v[100:103], v[136:139], v[168:171], v[100:103]
	s_waitcnt lgkmcnt(2)
	v_mfma_f32_16x16x32_bf16 v[92:95], v[140:143], v[168:171], v[92:95]
	s_waitcnt lgkmcnt(1)
	v_mfma_f32_16x16x32_bf16 v[84:87], v[144:147], v[168:171], v[84:87]
	s_waitcnt lgkmcnt(0)
	v_mfma_f32_16x16x32_bf16 v[80:83], v[148:151], v[168:171], v[80:83]
	v_mfma_f32_16x16x32_bf16 v[68:71], v[136:139], v[172:175], v[68:71]
	v_mfma_f32_16x16x32_bf16 v[60:63], v[140:143], v[172:175], v[60:63]
	v_mfma_f32_16x16x32_bf16 v[52:55], v[144:147], v[172:175], v[52:55]
	v_mfma_f32_16x16x32_bf16 v[48:51], v[148:151], v[172:175], v[48:51]
	v_mfma_f32_16x16x32_bf16 v[36:39], v[136:139], v[112:115], v[36:39]
	v_mfma_f32_16x16x32_bf16 v[28:31], v[140:143], v[112:115], v[28:31]
	v_mfma_f32_16x16x32_bf16 v[20:23], v[144:147], v[112:115], v[20:23]
	v_mfma_f32_16x16x32_bf16 v[16:19], v[148:151], v[112:115], v[16:19]
	v_mfma_f32_16x16x32_bf16 v[12:15], v[136:139], v[128:131], v[12:15]
	v_mfma_f32_16x16x32_bf16 v[8:11], v[140:143], v[128:131], v[8:11]
	v_mfma_f32_16x16x32_bf16 v[4:7], v[144:147], v[128:131], v[4:7]
	v_mfma_f32_16x16x32_bf16 v[0:3], v[148:151], v[128:131], v[0:3]
	s_mov_b64 s[0:1], s[60:61]
	s_barrier
	s_branch .LBB0_337

.LBB0_645:
	s_waitcnt vmcnt(5)
	ds_write_b128 v154, v[80:83]
	s_waitcnt vmcnt(3)
	ds_write_b128 v154, v[92:95] offset:6144
	s_waitcnt vmcnt(3)
	ds_write_b128 v154, v[84:87] offset:12288
	s_waitcnt vmcnt(2)
	ds_write_b128 v154, v[124:127] offset:18432
	s_waitcnt vmcnt(1)
	ds_write_b128 v154, v[128:131] offset:24576
	s_waitcnt vmcnt(0)
	ds_write_b128 v154, v[132:135] offset:30720
	s_waitcnt lgkmcnt(0)
	s_barrier
	ds_read_b128 v[92:95], v166 offset:12288
	ds_read_b128 v[124:127], v166 offset:13824
	ds_read_b128 v[170:173], v165
	ds_read_b128 v[174:177], v165 offset:1536
	ds_read_b128 v[132:135], v166 offset:15360
	ds_read_b128 v[178:181], v166 offset:16896
	v_lshl_add_u64 v[84:85], v[160:161], 0, s[0:1]
	v_add_co_u32_e32 v130, vcc, s69, v84
	v_lshl_add_u64 v[128:129], v[162:163], 0, s[0:1]
	s_nop 0
	v_addc_co_u32_e32 v131, vcc, 0, v85, vcc
	ds_read_b128 v[182:185], v165 offset:3072
	ds_read_b128 v[200:203], v165 offset:4608
	v_add_co_u32_e32 v186, vcc, s69, v128
	s_waitcnt lgkmcnt(5)
	v_mfma_f32_16x16x32_bf16 v[148:151], v[92:95], v[170:173], v[148:151]
	v_addc_co_u32_e32 v187, vcc, 0, v129, vcc
	v_add_co_u32_e32 v204, vcc, s70, v128
	v_mfma_f32_16x16x32_bf16 v[144:147], v[124:127], v[170:173], v[144:147]
	s_nop 0
	v_addc_co_u32_e32 v205, vcc, 0, v129, vcc
	v_add_co_u32_e32 v206, vcc, s71, v128
	s_waitcnt lgkmcnt(4)
	v_mfma_f32_16x16x32_bf16 v[120:123], v[92:95], v[174:177], v[120:123]
	global_load_dwordx4 v[80:83], v[84:85], off offset:64
	v_addc_co_u32_e32 v207, vcc, 0, v129, vcc
	v_mfma_f32_16x16x32_bf16 v[88:91], v[124:127], v[174:177], v[88:91]
	global_load_dwordx4 v[84:87], v[128:129], off offset:64
	s_waitcnt lgkmcnt(1)
	v_mfma_f32_16x16x32_bf16 v[60:63], v[92:95], v[182:185], v[60:63]
	v_mfma_f32_16x16x32_bf16 v[56:59], v[124:127], v[182:185], v[56:59]
	s_waitcnt lgkmcnt(0)
	v_mfma_f32_16x16x32_bf16 v[28:31], v[92:95], v[200:203], v[28:31]
	v_mfma_f32_16x16x32_bf16 v[24:27], v[124:127], v[200:203], v[24:27]
	global_load_dwordx4 v[92:95], v[130:131], off offset:64
	global_load_dwordx4 v[124:127], v[186:187], off offset:64
	s_nop 0
	global_load_dwordx4 v[128:131], v[204:205], off offset:64
	v_mfma_f32_16x16x32_bf16 v[140:143], v[132:135], v[170:173], v[140:143]
	v_mfma_f32_16x16x32_bf16 v[112:115], v[132:135], v[174:177], v[112:115]
	v_mfma_f32_16x16x32_bf16 v[52:55], v[132:135], v[182:185], v[52:55]
	v_mfma_f32_16x16x32_bf16 v[20:23], v[132:135], v[200:203], v[20:23]
	global_load_dwordx4 v[132:135], v[206:207], off offset:64
	v_mfma_f32_16x16x32_bf16 v[136:139], v[178:181], v[170:173], v[136:139]
	v_mfma_f32_16x16x32_bf16 v[104:107], v[178:181], v[174:177], v[104:107]
	v_mfma_f32_16x16x32_bf16 v[48:51], v[178:181], v[182:185], v[48:51]
	v_mfma_f32_16x16x32_bf16 v[16:19], v[178:181], v[200:203], v[16:19]
	ds_read_b128 v[178:181], v166 offset:18432
	ds_read_b128 v[204:207], v166 offset:19968
	ds_read_b128 v[208:211], v166 offset:21504
	ds_read_b128 v[212:215], v166 offset:23040
	s_waitcnt lgkmcnt(3)
	v_mfma_f32_16x16x32_bf16 v[116:119], v[178:181], v[170:173], v[116:119]
	s_waitcnt lgkmcnt(2)
	v_mfma_f32_16x16x32_bf16 v[108:111], v[204:207], v[170:173], v[108:111]
	s_waitcnt lgkmcnt(1)
	v_mfma_f32_16x16x32_bf16 v[100:103], v[208:211], v[170:173], v[100:103]
	s_waitcnt lgkmcnt(0)
	s_barrier
	v_mfma_f32_16x16x32_bf16 v[96:99], v[212:215], v[170:173], v[96:99]
	v_mfma_f32_16x16x32_bf16 v[76:79], v[178:181], v[174:177], v[76:79]
	v_mfma_f32_16x16x32_bf16 v[72:75], v[204:207], v[174:177], v[72:75]
	v_mfma_f32_16x16x32_bf16 v[68:71], v[208:211], v[174:177], v[68:71]
	v_mfma_f32_16x16x32_bf16 v[64:67], v[212:215], v[174:177], v[64:67]
	v_mfma_f32_16x16x32_bf16 v[44:47], v[178:181], v[182:185], v[44:47]
	v_mfma_f32_16x16x32_bf16 v[40:43], v[204:207], v[182:185], v[40:43]
	v_mfma_f32_16x16x32_bf16 v[36:39], v[208:211], v[182:185], v[36:39]
	v_mfma_f32_16x16x32_bf16 v[32:35], v[212:215], v[182:185], v[32:35]
	v_mfma_f32_16x16x32_bf16 v[12:15], v[178:181], v[200:203], v[12:15]
	v_mfma_f32_16x16x32_bf16 v[8:11], v[204:207], v[200:203], v[8:11]
	v_mfma_f32_16x16x32_bf16 v[4:7], v[208:211], v[200:203], v[4:7]
	v_mfma_f32_16x16x32_bf16 v[0:3], v[212:215], v[200:203], v[0:3]
	s_add_u32 s0, s0, 64
	s_addc_u32 s1, s1, 0
	s_cmpk_lg_i32 s0, 0xfc0
	s_cbranch_scc1 .LBB0_645
	s_waitcnt vmcnt(5)
	ds_write_b128 v154, v[80:83]
	s_waitcnt vmcnt(3)
	ds_write_b128 v154, v[92:95] offset:6144
	ds_write_b128 v154, v[84:87] offset:12288
	s_waitcnt vmcnt(2)
	ds_write_b128 v154, v[124:127] offset:18432
	s_waitcnt vmcnt(1)
	ds_write_b128 v154, v[128:131] offset:24576
	s_waitcnt vmcnt(0)
	ds_write_b128 v154, v[132:135] offset:30720
	s_waitcnt lgkmcnt(0)
	s_barrier
	ds_read_b128 v[132:135], v166 offset:12288
	ds_read_b128 v[160:163], v166 offset:13824
	ds_read_b128 v[170:173], v165
	ds_read_b128 v[174:177], v165 offset:1536
	ds_read_b128 v[178:181], v166 offset:15360
	ds_read_b128 v[182:185], v166 offset:16896
	s_waitcnt lgkmcnt(2)
	v_mfma_f32_16x16x32_bf16 v[92:95], v[132:135], v[174:177], v[120:123]
	s_waitcnt lgkmcnt(0)
	v_mfma_f32_16x16x32_bf16 v[124:127], v[182:185], v[170:173], v[136:139]
	s_nop 0
	ds_read_b128 v[120:123], v165 offset:3072
	s_nop 0
	ds_read_b128 v[136:139], v165 offset:4608
	v_mfma_f32_16x16x32_bf16 v[148:151], v[132:135], v[170:173], v[148:151]
	v_mfma_f32_16x16x32_bf16 v[144:147], v[160:163], v[170:173], v[144:147]
	v_mfma_f32_16x16x32_bf16 v[128:131], v[178:181], v[170:173], v[140:143]
	v_mfma_f32_16x16x32_bf16 v[88:91], v[160:163], v[174:177], v[88:91]
	v_mfma_f32_16x16x32_bf16 v[84:87], v[178:181], v[174:177], v[112:115]
	v_mfma_f32_16x16x32_bf16 v[80:83], v[182:185], v[174:177], v[104:107]
	s_waitcnt lgkmcnt(1)
	v_mfma_f32_16x16x32_bf16 v[60:63], v[132:135], v[120:123], v[60:63]
	v_mfma_f32_16x16x32_bf16 v[56:59], v[160:163], v[120:123], v[56:59]
	v_mfma_f32_16x16x32_bf16 v[52:55], v[178:181], v[120:123], v[52:55]
	v_mfma_f32_16x16x32_bf16 v[48:51], v[182:185], v[120:123], v[48:51]
	s_waitcnt lgkmcnt(0)
	v_mfma_f32_16x16x32_bf16 v[28:31], v[132:135], v[136:139], v[28:31]
	v_mfma_f32_16x16x32_bf16 v[24:27], v[160:163], v[136:139], v[24:27]
	v_mfma_f32_16x16x32_bf16 v[20:23], v[178:181], v[136:139], v[20:23]
	v_mfma_f32_16x16x32_bf16 v[16:19], v[182:185], v[136:139], v[16:19]
	ds_read_b128 v[132:135], v166 offset:18432
	ds_read_b128 v[140:143], v166 offset:19968
	s_waitcnt lgkmcnt(1)
	v_mfma_f32_16x16x32_bf16 v[112:115], v[132:135], v[170:173], v[116:119]
	s_nop 2
	ds_read_b128 v[116:119], v166 offset:21504
	s_waitcnt lgkmcnt(1)
	v_mfma_f32_16x16x32_bf16 v[104:107], v[140:143], v[170:173], v[108:111]
	s_nop 2
	ds_read_b128 v[108:111], v166 offset:23040
	s_waitcnt lgkmcnt(1)
	v_mfma_f32_16x16x32_bf16 v[100:103], v[116:119], v[170:173], v[100:103]
	s_waitcnt lgkmcnt(0)
	v_mfma_f32_16x16x32_bf16 v[96:99], v[108:111], v[170:173], v[96:99]
	v_mfma_f32_16x16x32_bf16 v[76:79], v[132:135], v[174:177], v[76:79]
	v_mfma_f32_16x16x32_bf16 v[72:75], v[140:143], v[174:177], v[72:75]
	v_mfma_f32_16x16x32_bf16 v[68:71], v[116:119], v[174:177], v[68:71]
	v_mfma_f32_16x16x32_bf16 v[64:67], v[108:111], v[174:177], v[64:67]
	v_mfma_f32_16x16x32_bf16 v[44:47], v[132:135], v[120:123], v[44:47]
	v_mfma_f32_16x16x32_bf16 v[40:43], v[140:143], v[120:123], v[40:43]
	v_mfma_f32_16x16x32_bf16 v[36:39], v[116:119], v[120:123], v[36:39]
	v_mfma_f32_16x16x32_bf16 v[32:35], v[108:111], v[120:123], v[32:35]
	v_mfma_f32_16x16x32_bf16 v[12:15], v[132:135], v[136:139], v[12:15]
	v_mfma_f32_16x16x32_bf16 v[8:11], v[140:143], v[136:139], v[8:11]
	v_mfma_f32_16x16x32_bf16 v[4:7], v[116:119], v[136:139], v[4:7]
	v_mfma_f32_16x16x32_bf16 v[0:3], v[108:111], v[136:139], v[0:3]
	v_or_b32_e32 v108, s4, v155
	v_add_u32_e32 v108, v108, v167
	v_ashrrev_i32_e32 v109, 31, v108
	v_or_b32_e32 v116, s3, v168
	v_lshlrev_b64 v[110:111], 13, v[108:109]
	v_lshl_add_u64 v[110:111], s[58:59], 0, v[110:111]
	v_lshlrev_b32_e32 v152, 1, v116
	v_lshl_add_u64 v[110:111], v[110:111], 0, v[152:153]
	s_barrier
	global_load_dwordx2 v[116:117], v[110:111], off
	v_mul_f32_e32 v109, 0xbfb8aa3b, v148
	v_exp_f32_e32 v109, v109
	s_add_i32 s2, s2, s33
	s_cmpk_lt_i32 s2, 0xc00
	v_add_f32_e32 v109, 1.0, v109
	v_rcp_f32_e32 v120, v109
	v_mul_f32_e32 v109, 0xbfb8aa3b, v149
	v_exp_f32_e32 v109, v109
	s_waitcnt vmcnt(0)
	v_lshlrev_b32_e32 v118, 16, v116
	v_add_f32_e32 v109, 1.0, v109
	v_rcp_f32_e32 v121, v109
	v_mul_f32_e32 v109, 0xbfb8aa3b, v150
	v_exp_f32_e32 v109, v109
	v_and_b32_e32 v119, 0xffff0000, v116
	v_pk_mul_f32 v[120:121], v[148:149], v[120:121]
	v_lshlrev_b32_e32 v116, 16, v117
	v_add_f32_e32 v109, 1.0, v109
	v_pk_mul_f32 v[118:119], v[120:121], v[118:119]
	v_rcp_f32_e32 v120, v109
	v_mul_f32_e32 v109, 0xbfb8aa3b, v151
	v_exp_f32_e32 v109, v109
	v_and_b32_e32 v117, 0xffff0000, v117
	v_cvt_pk_bf16_f32 v118, v118, v119
	v_add_f32_e32 v109, 1.0, v109
	v_rcp_f32_e32 v121, v109
	v_mul_f32_e32 v109, 0xbfb8aa3b, v144
	v_exp_f32_e32 v109, v109
	v_pk_mul_f32 v[120:121], v[150:151], v[120:121]
	s_nop 0
	v_pk_mul_f32 v[116:117], v[120:121], v[116:117]
	v_add_f32_e32 v109, 1.0, v109
	v_cvt_pk_bf16_f32 v119, v116, v117
	global_load_dwordx2 v[116:117], v[110:111], off offset:32
	v_rcp_f32_e32 v120, v109
	v_mul_f32_e32 v109, 0xbfb8aa3b, v145
	v_exp_f32_e32 v109, v109
	global_store_dwordx2 v[110:111], v[118:119], off
	v_add_f32_e32 v109, 1.0, v109
	v_rcp_f32_e32 v121, v109
	v_mul_f32_e32 v109, 0xbfb8aa3b, v146
	v_exp_f32_e32 v109, v109
	v_pk_mul_f32 v[120:121], v[144:145], v[120:121]
	v_add_f32_e32 v109, 1.0, v109
	s_waitcnt vmcnt(1)
	v_lshlrev_b32_e32 v118, 16, v116
	v_and_b32_e32 v119, 0xffff0000, v116
	v_pk_mul_f32 v[118:119], v[120:121], v[118:119]
	v_rcp_f32_e32 v120, v109
	v_mul_f32_e32 v109, 0xbfb8aa3b, v147
	v_exp_f32_e32 v109, v109
	v_lshlrev_b32_e32 v116, 16, v117
	v_and_b32_e32 v117, 0xffff0000, v117
	v_cvt_pk_bf16_f32 v118, v118, v119
	v_add_f32_e32 v109, 1.0, v109
	v_rcp_f32_e32 v121, v109
	v_mul_f32_e32 v109, 0xbfb8aa3b, v128
	v_exp_f32_e32 v109, v109
	v_pk_mul_f32 v[120:121], v[146:147], v[120:121]
	s_nop 0
	v_pk_mul_f32 v[116:117], v[120:121], v[116:117]
	v_add_f32_e32 v109, 1.0, v109
	v_cvt_pk_bf16_f32 v119, v116, v117
	global_load_dwordx2 v[116:117], v[110:111], off offset:64
	v_rcp_f32_e32 v120, v109
	v_mul_f32_e32 v109, 0xbfb8aa3b, v129
	v_exp_f32_e32 v109, v109
	global_store_dwordx2 v[110:111], v[118:119], off offset:32
	v_add_f32_e32 v109, 1.0, v109
	v_rcp_f32_e32 v121, v109
	v_mul_f32_e32 v109, 0xbfb8aa3b, v130
	v_exp_f32_e32 v109, v109
	v_pk_mul_f32 v[120:121], v[128:129], v[120:121]
	v_add_f32_e32 v109, 1.0, v109
	s_waitcnt vmcnt(1)
	v_lshlrev_b32_e32 v118, 16, v116
	v_and_b32_e32 v119, 0xffff0000, v116
	v_pk_mul_f32 v[118:119], v[120:121], v[118:119]
	v_rcp_f32_e32 v120, v109
	v_mul_f32_e32 v109, 0xbfb8aa3b, v131
	v_exp_f32_e32 v109, v109
	v_lshlrev_b32_e32 v116, 16, v117
	v_and_b32_e32 v117, 0xffff0000, v117
	v_cvt_pk_bf16_f32 v118, v118, v119
	v_add_f32_e32 v109, 1.0, v109
	v_rcp_f32_e32 v121, v109
	v_mul_f32_e32 v109, 0xbfb8aa3b, v124
	v_exp_f32_e32 v109, v109
	v_pk_mul_f32 v[120:121], v[130:131], v[120:121]
	s_nop 0
	v_pk_mul_f32 v[116:117], v[120:121], v[116:117]
	v_add_f32_e32 v109, 1.0, v109
	v_cvt_pk_bf16_f32 v119, v116, v117
	global_load_dwordx2 v[116:117], v[110:111], off offset:96
	v_rcp_f32_e32 v120, v109
	v_mul_f32_e32 v109, 0xbfb8aa3b, v125
	v_exp_f32_e32 v109, v109
	global_store_dwordx2 v[110:111], v[118:119], off offset:64
	v_add_f32_e32 v109, 1.0, v109
	v_rcp_f32_e32 v121, v109
	v_mul_f32_e32 v109, 0xbfb8aa3b, v126
	v_exp_f32_e32 v109, v109
	v_pk_mul_f32 v[120:121], v[124:125], v[120:121]
	v_add_f32_e32 v109, 1.0, v109
	s_waitcnt vmcnt(1)
	v_lshlrev_b32_e32 v118, 16, v116
	v_and_b32_e32 v119, 0xffff0000, v116
	v_pk_mul_f32 v[118:119], v[120:121], v[118:119]
	v_rcp_f32_e32 v120, v109
	v_mul_f32_e32 v109, 0xbfb8aa3b, v127
	v_exp_f32_e32 v109, v109
	v_lshlrev_b32_e32 v116, 16, v117
	v_and_b32_e32 v117, 0xffff0000, v117
	v_cvt_pk_bf16_f32 v118, v118, v119
	v_add_f32_e32 v109, 1.0, v109
	v_rcp_f32_e32 v121, v109
	v_mul_f32_e32 v109, 0xbfb8aa3b, v112
	v_exp_f32_e32 v109, v109
	v_pk_mul_f32 v[120:121], v[126:127], v[120:121]
	s_nop 0
	v_pk_mul_f32 v[116:117], v[120:121], v[116:117]
	v_add_f32_e32 v109, 1.0, v109
	v_cvt_pk_bf16_f32 v119, v116, v117
	global_load_dwordx2 v[116:117], v[110:111], off offset:128
	v_rcp_f32_e32 v120, v109
	v_mul_f32_e32 v109, 0xbfb8aa3b, v113
	v_exp_f32_e32 v109, v109
	global_store_dwordx2 v[110:111], v[118:119], off offset:96
	v_add_f32_e32 v109, 1.0, v109
	v_rcp_f32_e32 v121, v109
	v_mul_f32_e32 v109, 0xbfb8aa3b, v114
	v_exp_f32_e32 v109, v109
	v_pk_mul_f32 v[112:113], v[112:113], v[120:121]
	v_add_f32_e32 v109, 1.0, v109
	s_waitcnt vmcnt(1)
	v_lshlrev_b32_e32 v118, 16, v116
	v_and_b32_e32 v119, 0xffff0000, v116
	v_pk_mul_f32 v[112:113], v[112:113], v[118:119]
	v_rcp_f32_e32 v118, v109
	v_mul_f32_e32 v109, 0xbfb8aa3b, v115
	v_exp_f32_e32 v109, v109
	v_lshlrev_b32_e32 v116, 16, v117
	v_and_b32_e32 v117, 0xffff0000, v117
	v_cvt_pk_bf16_f32 v112, v112, v113
	v_add_f32_e32 v109, 1.0, v109
	v_rcp_f32_e32 v119, v109
	v_mul_f32_e32 v109, 0xbfb8aa3b, v104
	v_exp_f32_e32 v109, v109
	v_pk_mul_f32 v[114:115], v[114:115], v[118:119]
	s_nop 0
	v_pk_mul_f32 v[114:115], v[114:115], v[116:117]
	v_add_f32_e32 v109, 1.0, v109
	v_cvt_pk_bf16_f32 v113, v114, v115
	global_store_dwordx2 v[110:111], v[112:113], off offset:128
	global_load_dwordx2 v[112:113], v[110:111], off offset:160
	v_rcp_f32_e32 v116, v109
	v_mul_f32_e32 v109, 0xbfb8aa3b, v105
	v_exp_f32_e32 v109, v109
	s_waitcnt vmcnt(0)
	v_lshlrev_b32_e32 v114, 16, v112
	v_add_f32_e32 v109, 1.0, v109
	v_rcp_f32_e32 v117, v109
	v_mul_f32_e32 v109, 0xbfb8aa3b, v106
	v_exp_f32_e32 v109, v109
	v_and_b32_e32 v115, 0xffff0000, v112
	v_pk_mul_f32 v[104:105], v[104:105], v[116:117]
	v_lshlrev_b32_e32 v112, 16, v113
	v_add_f32_e32 v109, 1.0, v109
	v_pk_mul_f32 v[104:105], v[104:105], v[114:115]
	v_rcp_f32_e32 v114, v109
	v_mul_f32_e32 v109, 0xbfb8aa3b, v107
	v_exp_f32_e32 v109, v109
	v_and_b32_e32 v113, 0xffff0000, v113
	v_cvt_pk_bf16_f32 v104, v104, v105
	v_add_f32_e32 v109, 1.0, v109
	v_rcp_f32_e32 v115, v109
	v_mul_f32_e32 v109, 0xbfb8aa3b, v100
	v_exp_f32_e32 v109, v109
	v_pk_mul_f32 v[106:107], v[106:107], v[114:115]
	s_nop 0
	v_pk_mul_f32 v[106:107], v[106:107], v[112:113]
	v_add_f32_e32 v109, 1.0, v109
	v_cvt_pk_bf16_f32 v105, v106, v107
	global_store_dwordx2 v[110:111], v[104:105], off offset:160
	global_load_dwordx2 v[104:105], v[110:111], off offset:192
	v_rcp_f32_e32 v112, v109
	v_mul_f32_e32 v109, 0xbfb8aa3b, v101
	v_exp_f32_e32 v109, v109
	s_waitcnt vmcnt(0)
	v_lshlrev_b32_e32 v106, 16, v104
	v_add_f32_e32 v109, 1.0, v109
	v_rcp_f32_e32 v113, v109
	v_and_b32_e32 v107, 0xffff0000, v104
	v_lshlrev_b32_e32 v104, 16, v105
	v_and_b32_e32 v105, 0xffff0000, v105
	v_pk_mul_f32 v[100:101], v[100:101], v[112:113]
	s_nop 0
	v_pk_mul_f32 v[100:101], v[100:101], v[106:107]
	v_mul_f32_e32 v106, 0xbfb8aa3b, v102
	v_mul_f32_e32 v107, 0xbfb8aa3b, v103
	v_exp_f32_e32 v106, v106
	v_exp_f32_e32 v107, v107
	v_cvt_pk_bf16_f32 v100, v100, v101
	v_add_f32_e32 v106, 1.0, v106
	v_add_f32_e32 v107, 1.0, v107
	v_rcp_f32_e32 v106, v106
	v_rcp_f32_e32 v107, v107
	s_nop 0
	v_pk_mul_f32 v[102:103], v[102:103], v[106:107]
	s_nop 0
	v_pk_mul_f32 v[102:103], v[102:103], v[104:105]
	v_mul_f32_e32 v104, 0xbfb8aa3b, v96
	v_cvt_pk_bf16_f32 v101, v102, v103
	global_store_dwordx2 v[110:111], v[100:101], off offset:192
	global_load_dwordx2 v[100:101], v[110:111], off offset:224
	v_mul_f32_e32 v105, 0xbfb8aa3b, v97
	v_exp_f32_e32 v104, v104
	v_exp_f32_e32 v105, v105
	v_add_f32_e32 v104, 1.0, v104
	v_add_f32_e32 v105, 1.0, v105
	v_rcp_f32_e32 v104, v104
	v_rcp_f32_e32 v105, v105
	s_waitcnt vmcnt(0)
	v_lshlrev_b32_e32 v102, 16, v100
	v_and_b32_e32 v103, 0xffff0000, v100
	v_pk_mul_f32 v[96:97], v[96:97], v[104:105]
	v_lshlrev_b32_e32 v100, 16, v101
	v_pk_mul_f32 v[96:97], v[96:97], v[102:103]
	v_mul_f32_e32 v102, 0xbfb8aa3b, v98
	v_mul_f32_e32 v103, 0xbfb8aa3b, v99
	v_exp_f32_e32 v102, v102
	v_exp_f32_e32 v103, v103
	v_and_b32_e32 v101, 0xffff0000, v101
	v_cvt_pk_bf16_f32 v96, v96, v97
	v_add_f32_e32 v102, 1.0, v102
	v_add_f32_e32 v103, 1.0, v103
	v_rcp_f32_e32 v102, v102
	v_rcp_f32_e32 v103, v103
	s_nop 0
	v_pk_mul_f32 v[98:99], v[98:99], v[102:103]
	s_nop 0
	v_pk_mul_f32 v[98:99], v[98:99], v[100:101]
	v_mul_f32_e32 v102, 0xbfb8aa3b, v92
	v_cvt_pk_bf16_f32 v97, v98, v99
	global_store_dwordx2 v[110:111], v[96:97], off offset:224
	v_or_b32_e32 v96, 16, v108
	v_ashrrev_i32_e32 v97, 31, v96
	v_lshlrev_b64 v[96:97], 13, v[96:97]
	v_lshl_add_u64 v[96:97], s[58:59], 0, v[96:97]
	v_lshl_add_u64 v[96:97], v[96:97], 0, v[152:153]
	global_load_dwordx2 v[98:99], v[96:97], off
	v_mul_f32_e32 v103, 0xbfb8aa3b, v93
	v_exp_f32_e32 v102, v102
	v_exp_f32_e32 v103, v103
	v_add_f32_e32 v102, 1.0, v102
	v_add_f32_e32 v103, 1.0, v103
	v_rcp_f32_e32 v102, v102
	v_rcp_f32_e32 v103, v103
	s_waitcnt vmcnt(0)
	v_lshlrev_b32_e32 v100, 16, v98
	v_and_b32_e32 v101, 0xffff0000, v98
	v_pk_mul_f32 v[92:93], v[92:93], v[102:103]
	v_lshlrev_b32_e32 v98, 16, v99
	v_pk_mul_f32 v[92:93], v[92:93], v[100:101]
	v_mul_f32_e32 v100, 0xbfb8aa3b, v94
	v_mul_f32_e32 v101, 0xbfb8aa3b, v95
	v_exp_f32_e32 v100, v100
	v_exp_f32_e32 v101, v101
	v_and_b32_e32 v99, 0xffff0000, v99
	v_cvt_pk_bf16_f32 v92, v92, v93
	v_add_f32_e32 v100, 1.0, v100
	v_add_f32_e32 v101, 1.0, v101
	v_rcp_f32_e32 v100, v100
	v_rcp_f32_e32 v101, v101
	s_nop 0
	v_pk_mul_f32 v[94:95], v[94:95], v[100:101]
	s_nop 0
	v_pk_mul_f32 v[94:95], v[94:95], v[98:99]
	v_mul_f32_e32 v98, 0xbfb8aa3b, v88
	v_cvt_pk_bf16_f32 v93, v94, v95
	global_store_dwordx2 v[96:97], v[92:93], off
	global_load_dwordx2 v[92:93], v[96:97], off offset:32
	v_mul_f32_e32 v99, 0xbfb8aa3b, v89
	v_exp_f32_e32 v98, v98
	v_exp_f32_e32 v99, v99
	v_add_f32_e32 v98, 1.0, v98
	v_add_f32_e32 v99, 1.0, v99
	v_rcp_f32_e32 v98, v98
	v_rcp_f32_e32 v99, v99
	s_waitcnt vmcnt(0)
	v_lshlrev_b32_e32 v94, 16, v92
	v_and_b32_e32 v95, 0xffff0000, v92
	v_pk_mul_f32 v[88:89], v[88:89], v[98:99]
	v_lshlrev_b32_e32 v92, 16, v93
	v_pk_mul_f32 v[88:89], v[88:89], v[94:95]
	v_mul_f32_e32 v94, 0xbfb8aa3b, v90
	v_mul_f32_e32 v95, 0xbfb8aa3b, v91
	v_exp_f32_e32 v94, v94
	v_exp_f32_e32 v95, v95
	v_and_b32_e32 v93, 0xffff0000, v93
	v_cvt_pk_bf16_f32 v88, v88, v89
	v_add_f32_e32 v94, 1.0, v94
	v_add_f32_e32 v95, 1.0, v95
	v_rcp_f32_e32 v94, v94
	v_rcp_f32_e32 v95, v95
	s_nop 0
	v_pk_mul_f32 v[90:91], v[90:91], v[94:95]
	s_nop 0
	v_pk_mul_f32 v[90:91], v[90:91], v[92:93]
	v_mul_f32_e32 v92, 0xbfb8aa3b, v84
	v_cvt_pk_bf16_f32 v89, v90, v91
	global_store_dwordx2 v[96:97], v[88:89], off offset:32
	global_load_dwordx2 v[88:89], v[96:97], off offset:64
	v_mul_f32_e32 v93, 0xbfb8aa3b, v85
	v_exp_f32_e32 v92, v92
	v_exp_f32_e32 v93, v93
	v_add_f32_e32 v92, 1.0, v92
	v_add_f32_e32 v93, 1.0, v93
	v_rcp_f32_e32 v92, v92
	v_rcp_f32_e32 v93, v93
	s_waitcnt vmcnt(0)
	v_lshlrev_b32_e32 v90, 16, v88
	v_and_b32_e32 v91, 0xffff0000, v88
	v_pk_mul_f32 v[84:85], v[84:85], v[92:93]
	v_lshlrev_b32_e32 v88, 16, v89
	v_pk_mul_f32 v[84:85], v[84:85], v[90:91]
	v_mul_f32_e32 v90, 0xbfb8aa3b, v86
	v_mul_f32_e32 v91, 0xbfb8aa3b, v87
	v_exp_f32_e32 v90, v90
	v_exp_f32_e32 v91, v91
	v_and_b32_e32 v89, 0xffff0000, v89
	v_cvt_pk_bf16_f32 v84, v84, v85
	v_add_f32_e32 v90, 1.0, v90
	v_add_f32_e32 v91, 1.0, v91
	v_rcp_f32_e32 v90, v90
	v_rcp_f32_e32 v91, v91
	s_nop 0
	v_pk_mul_f32 v[86:87], v[86:87], v[90:91]
	s_nop 0
	v_pk_mul_f32 v[86:87], v[86:87], v[88:89]
	v_mul_f32_e32 v88, 0xbfb8aa3b, v80
	v_cvt_pk_bf16_f32 v85, v86, v87
	global_store_dwordx2 v[96:97], v[84:85], off offset:64
	global_load_dwordx2 v[84:85], v[96:97], off offset:96
	v_mul_f32_e32 v89, 0xbfb8aa3b, v81
	v_exp_f32_e32 v88, v88
	v_exp_f32_e32 v89, v89
	v_add_f32_e32 v88, 1.0, v88
	v_add_f32_e32 v89, 1.0, v89
	v_rcp_f32_e32 v88, v88
	v_rcp_f32_e32 v89, v89
	s_waitcnt vmcnt(0)
	v_lshlrev_b32_e32 v86, 16, v84
	v_and_b32_e32 v87, 0xffff0000, v84
	v_pk_mul_f32 v[80:81], v[80:81], v[88:89]
	v_lshlrev_b32_e32 v84, 16, v85
	v_pk_mul_f32 v[80:81], v[80:81], v[86:87]
	v_mul_f32_e32 v86, 0xbfb8aa3b, v82
	v_mul_f32_e32 v87, 0xbfb8aa3b, v83
	v_exp_f32_e32 v86, v86
	v_exp_f32_e32 v87, v87
	v_and_b32_e32 v85, 0xffff0000, v85
	v_cvt_pk_bf16_f32 v80, v80, v81
	v_add_f32_e32 v86, 1.0, v86
	v_add_f32_e32 v87, 1.0, v87
	v_rcp_f32_e32 v86, v86
	v_rcp_f32_e32 v87, v87
	s_nop 0
	v_pk_mul_f32 v[82:83], v[82:83], v[86:87]
	s_nop 0
	v_pk_mul_f32 v[82:83], v[82:83], v[84:85]
	v_mul_f32_e32 v84, 0xbfb8aa3b, v76
	v_cvt_pk_bf16_f32 v81, v82, v83
	global_store_dwordx2 v[96:97], v[80:81], off offset:96
	global_load_dwordx2 v[80:81], v[96:97], off offset:128
	v_mul_f32_e32 v85, 0xbfb8aa3b, v77
	v_exp_f32_e32 v84, v84
	v_exp_f32_e32 v85, v85
	v_add_f32_e32 v84, 1.0, v84
	v_add_f32_e32 v85, 1.0, v85
	v_rcp_f32_e32 v84, v84
	v_rcp_f32_e32 v85, v85
	s_waitcnt vmcnt(0)
	v_lshlrev_b32_e32 v82, 16, v80
	v_and_b32_e32 v83, 0xffff0000, v80
	v_pk_mul_f32 v[76:77], v[76:77], v[84:85]
	v_lshlrev_b32_e32 v80, 16, v81
	v_pk_mul_f32 v[76:77], v[76:77], v[82:83]
	v_mul_f32_e32 v82, 0xbfb8aa3b, v78
	v_mul_f32_e32 v83, 0xbfb8aa3b, v79
	v_exp_f32_e32 v82, v82
	v_exp_f32_e32 v83, v83
	v_and_b32_e32 v81, 0xffff0000, v81
	v_cvt_pk_bf16_f32 v76, v76, v77
	v_add_f32_e32 v82, 1.0, v82
	v_add_f32_e32 v83, 1.0, v83
	v_rcp_f32_e32 v82, v82
	v_rcp_f32_e32 v83, v83
	s_nop 0
	v_pk_mul_f32 v[78:79], v[78:79], v[82:83]
	s_nop 0
	v_pk_mul_f32 v[78:79], v[78:79], v[80:81]
	v_mul_f32_e32 v80, 0xbfb8aa3b, v72
	v_cvt_pk_bf16_f32 v77, v78, v79
	global_store_dwordx2 v[96:97], v[76:77], off offset:128
	global_load_dwordx2 v[76:77], v[96:97], off offset:160
	v_mul_f32_e32 v81, 0xbfb8aa3b, v73
	v_exp_f32_e32 v80, v80
	v_exp_f32_e32 v81, v81
	v_add_f32_e32 v80, 1.0, v80
	v_add_f32_e32 v81, 1.0, v81
	v_rcp_f32_e32 v80, v80
	v_rcp_f32_e32 v81, v81
	s_waitcnt vmcnt(0)
	v_lshlrev_b32_e32 v78, 16, v76
	v_and_b32_e32 v79, 0xffff0000, v76
	v_pk_mul_f32 v[72:73], v[72:73], v[80:81]
	v_lshlrev_b32_e32 v76, 16, v77
	v_pk_mul_f32 v[72:73], v[72:73], v[78:79]
	v_mul_f32_e32 v78, 0xbfb8aa3b, v74
	v_mul_f32_e32 v79, 0xbfb8aa3b, v75
	v_exp_f32_e32 v78, v78
	v_exp_f32_e32 v79, v79
	v_and_b32_e32 v77, 0xffff0000, v77
	v_cvt_pk_bf16_f32 v72, v72, v73
	v_add_f32_e32 v78, 1.0, v78
	v_add_f32_e32 v79, 1.0, v79
	v_rcp_f32_e32 v78, v78
	v_rcp_f32_e32 v79, v79
	s_nop 0
	v_pk_mul_f32 v[74:75], v[74:75], v[78:79]
	s_nop 0
	v_pk_mul_f32 v[74:75], v[74:75], v[76:77]
	v_mul_f32_e32 v76, 0xbfb8aa3b, v68
	v_cvt_pk_bf16_f32 v73, v74, v75
	global_store_dwordx2 v[96:97], v[72:73], off offset:160
	global_load_dwordx2 v[72:73], v[96:97], off offset:192
	v_mul_f32_e32 v77, 0xbfb8aa3b, v69
	v_exp_f32_e32 v76, v76
	v_exp_f32_e32 v77, v77
	v_add_f32_e32 v76, 1.0, v76
	v_add_f32_e32 v77, 1.0, v77
	v_rcp_f32_e32 v76, v76
	v_rcp_f32_e32 v77, v77
	s_waitcnt vmcnt(0)
	v_lshlrev_b32_e32 v74, 16, v72
	v_and_b32_e32 v75, 0xffff0000, v72
	v_pk_mul_f32 v[68:69], v[68:69], v[76:77]
	v_lshlrev_b32_e32 v72, 16, v73
	v_pk_mul_f32 v[68:69], v[68:69], v[74:75]
	v_mul_f32_e32 v74, 0xbfb8aa3b, v70
	v_mul_f32_e32 v75, 0xbfb8aa3b, v71
	v_exp_f32_e32 v74, v74
	v_exp_f32_e32 v75, v75
	v_and_b32_e32 v73, 0xffff0000, v73
	v_cvt_pk_bf16_f32 v68, v68, v69
	v_add_f32_e32 v74, 1.0, v74
	v_add_f32_e32 v75, 1.0, v75
	v_rcp_f32_e32 v74, v74
	v_rcp_f32_e32 v75, v75
	s_nop 0
	v_pk_mul_f32 v[70:71], v[70:71], v[74:75]
	s_nop 0
	v_pk_mul_f32 v[70:71], v[70:71], v[72:73]
	v_mul_f32_e32 v72, 0xbfb8aa3b, v64
	v_cvt_pk_bf16_f32 v69, v70, v71
	global_store_dwordx2 v[96:97], v[68:69], off offset:192
	global_load_dwordx2 v[68:69], v[96:97], off offset:224
	v_mul_f32_e32 v73, 0xbfb8aa3b, v65
	v_exp_f32_e32 v72, v72
	v_exp_f32_e32 v73, v73
	v_add_f32_e32 v72, 1.0, v72
	v_add_f32_e32 v73, 1.0, v73
	v_rcp_f32_e32 v72, v72
	v_rcp_f32_e32 v73, v73
	s_waitcnt vmcnt(0)
	v_lshlrev_b32_e32 v70, 16, v68
	v_and_b32_e32 v71, 0xffff0000, v68
	v_pk_mul_f32 v[64:65], v[64:65], v[72:73]
	v_lshlrev_b32_e32 v68, 16, v69
	v_pk_mul_f32 v[64:65], v[64:65], v[70:71]
	v_mul_f32_e32 v70, 0xbfb8aa3b, v66
	v_mul_f32_e32 v71, 0xbfb8aa3b, v67
	v_exp_f32_e32 v70, v70
	v_exp_f32_e32 v71, v71
	v_and_b32_e32 v69, 0xffff0000, v69
	v_cvt_pk_bf16_f32 v64, v64, v65
	v_add_f32_e32 v70, 1.0, v70
	v_add_f32_e32 v71, 1.0, v71
	v_rcp_f32_e32 v70, v70
	v_rcp_f32_e32 v71, v71
	s_nop 0
	v_pk_mul_f32 v[66:67], v[66:67], v[70:71]
	s_nop 0
	v_pk_mul_f32 v[66:67], v[66:67], v[68:69]
	v_mul_f32_e32 v70, 0xbfb8aa3b, v60
	v_cvt_pk_bf16_f32 v65, v66, v67
	global_store_dwordx2 v[96:97], v[64:65], off offset:224
	v_or_b32_e32 v64, 32, v108
	v_ashrrev_i32_e32 v65, 31, v64
	v_lshlrev_b64 v[64:65], 13, v[64:65]
	v_lshl_add_u64 v[64:65], s[58:59], 0, v[64:65]
	v_lshl_add_u64 v[64:65], v[64:65], 0, v[152:153]
	global_load_dwordx2 v[66:67], v[64:65], off
	v_mul_f32_e32 v71, 0xbfb8aa3b, v61
	v_exp_f32_e32 v70, v70
	v_exp_f32_e32 v71, v71
	v_add_f32_e32 v70, 1.0, v70
	v_add_f32_e32 v71, 1.0, v71
	v_rcp_f32_e32 v70, v70
	v_rcp_f32_e32 v71, v71
	s_waitcnt vmcnt(0)
	v_lshlrev_b32_e32 v68, 16, v66
	v_and_b32_e32 v69, 0xffff0000, v66
	v_pk_mul_f32 v[60:61], v[60:61], v[70:71]
	v_lshlrev_b32_e32 v66, 16, v67
	v_pk_mul_f32 v[60:61], v[60:61], v[68:69]
	v_mul_f32_e32 v68, 0xbfb8aa3b, v62
	v_mul_f32_e32 v69, 0xbfb8aa3b, v63
	v_exp_f32_e32 v68, v68
	v_exp_f32_e32 v69, v69
	v_and_b32_e32 v67, 0xffff0000, v67
	v_cvt_pk_bf16_f32 v60, v60, v61
	v_add_f32_e32 v68, 1.0, v68
	v_add_f32_e32 v69, 1.0, v69
	v_rcp_f32_e32 v68, v68
	v_rcp_f32_e32 v69, v69
	s_nop 0
	v_pk_mul_f32 v[62:63], v[62:63], v[68:69]
	s_nop 0
	v_pk_mul_f32 v[62:63], v[62:63], v[66:67]
	v_mul_f32_e32 v66, 0xbfb8aa3b, v56
	v_cvt_pk_bf16_f32 v61, v62, v63
	global_store_dwordx2 v[64:65], v[60:61], off
	global_load_dwordx2 v[60:61], v[64:65], off offset:32
	v_mul_f32_e32 v67, 0xbfb8aa3b, v57
	v_exp_f32_e32 v66, v66
	v_exp_f32_e32 v67, v67
	v_add_f32_e32 v66, 1.0, v66
	v_add_f32_e32 v67, 1.0, v67
	v_rcp_f32_e32 v66, v66
	v_rcp_f32_e32 v67, v67
	s_waitcnt vmcnt(0)
	v_lshlrev_b32_e32 v62, 16, v60
	v_and_b32_e32 v63, 0xffff0000, v60
	v_pk_mul_f32 v[56:57], v[56:57], v[66:67]
	v_lshlrev_b32_e32 v60, 16, v61
	v_pk_mul_f32 v[56:57], v[56:57], v[62:63]
	v_mul_f32_e32 v62, 0xbfb8aa3b, v58
	v_mul_f32_e32 v63, 0xbfb8aa3b, v59
	v_exp_f32_e32 v62, v62
	v_exp_f32_e32 v63, v63
	v_and_b32_e32 v61, 0xffff0000, v61
	v_cvt_pk_bf16_f32 v56, v56, v57
	v_add_f32_e32 v62, 1.0, v62
	v_add_f32_e32 v63, 1.0, v63
	v_rcp_f32_e32 v62, v62
	v_rcp_f32_e32 v63, v63
	s_nop 0
	v_pk_mul_f32 v[58:59], v[58:59], v[62:63]
	s_nop 0
	v_pk_mul_f32 v[58:59], v[58:59], v[60:61]
	v_mul_f32_e32 v60, 0xbfb8aa3b, v52
	v_cvt_pk_bf16_f32 v57, v58, v59
	global_store_dwordx2 v[64:65], v[56:57], off offset:32
	global_load_dwordx2 v[56:57], v[64:65], off offset:64
	v_mul_f32_e32 v61, 0xbfb8aa3b, v53
	v_exp_f32_e32 v60, v60
	v_exp_f32_e32 v61, v61
	v_add_f32_e32 v60, 1.0, v60
	v_add_f32_e32 v61, 1.0, v61
	v_rcp_f32_e32 v60, v60
	v_rcp_f32_e32 v61, v61
	s_waitcnt vmcnt(0)
	v_lshlrev_b32_e32 v58, 16, v56
	v_and_b32_e32 v59, 0xffff0000, v56
	v_pk_mul_f32 v[52:53], v[52:53], v[60:61]
	v_lshlrev_b32_e32 v56, 16, v57
	v_pk_mul_f32 v[52:53], v[52:53], v[58:59]
	v_mul_f32_e32 v58, 0xbfb8aa3b, v54
	v_mul_f32_e32 v59, 0xbfb8aa3b, v55
	v_exp_f32_e32 v58, v58
	v_exp_f32_e32 v59, v59
	v_and_b32_e32 v57, 0xffff0000, v57
	v_cvt_pk_bf16_f32 v52, v52, v53
	v_add_f32_e32 v58, 1.0, v58
	v_add_f32_e32 v59, 1.0, v59
	v_rcp_f32_e32 v58, v58
	v_rcp_f32_e32 v59, v59
	s_nop 0
	v_pk_mul_f32 v[54:55], v[54:55], v[58:59]
	s_nop 0
	v_pk_mul_f32 v[54:55], v[54:55], v[56:57]
	v_mul_f32_e32 v56, 0xbfb8aa3b, v48
	v_cvt_pk_bf16_f32 v53, v54, v55
	global_store_dwordx2 v[64:65], v[52:53], off offset:64
	global_load_dwordx2 v[52:53], v[64:65], off offset:96
	v_mul_f32_e32 v57, 0xbfb8aa3b, v49
	v_exp_f32_e32 v56, v56
	v_exp_f32_e32 v57, v57
	v_add_f32_e32 v56, 1.0, v56
	v_add_f32_e32 v57, 1.0, v57
	v_rcp_f32_e32 v56, v56
	v_rcp_f32_e32 v57, v57
	s_waitcnt vmcnt(0)
	v_lshlrev_b32_e32 v54, 16, v52
	v_and_b32_e32 v55, 0xffff0000, v52
	v_pk_mul_f32 v[48:49], v[48:49], v[56:57]
	v_lshlrev_b32_e32 v52, 16, v53
	v_pk_mul_f32 v[48:49], v[48:49], v[54:55]
	v_mul_f32_e32 v54, 0xbfb8aa3b, v50
	v_mul_f32_e32 v55, 0xbfb8aa3b, v51
	v_exp_f32_e32 v54, v54
	v_exp_f32_e32 v55, v55
	v_and_b32_e32 v53, 0xffff0000, v53
	v_cvt_pk_bf16_f32 v48, v48, v49
	v_add_f32_e32 v54, 1.0, v54
	v_add_f32_e32 v55, 1.0, v55
	v_rcp_f32_e32 v54, v54
	v_rcp_f32_e32 v55, v55
	s_nop 0
	v_pk_mul_f32 v[50:51], v[50:51], v[54:55]
	s_nop 0
	v_pk_mul_f32 v[50:51], v[50:51], v[52:53]
	v_mul_f32_e32 v52, 0xbfb8aa3b, v44
	v_cvt_pk_bf16_f32 v49, v50, v51
	global_store_dwordx2 v[64:65], v[48:49], off offset:96
	global_load_dwordx2 v[48:49], v[64:65], off offset:128
	v_mul_f32_e32 v53, 0xbfb8aa3b, v45
	v_exp_f32_e32 v52, v52
	v_exp_f32_e32 v53, v53
	v_add_f32_e32 v52, 1.0, v52
	v_add_f32_e32 v53, 1.0, v53
	v_rcp_f32_e32 v52, v52
	v_rcp_f32_e32 v53, v53
	s_waitcnt vmcnt(0)
	v_lshlrev_b32_e32 v50, 16, v48
	v_and_b32_e32 v51, 0xffff0000, v48
	v_pk_mul_f32 v[44:45], v[44:45], v[52:53]
	v_lshlrev_b32_e32 v48, 16, v49
	v_pk_mul_f32 v[44:45], v[44:45], v[50:51]
	v_mul_f32_e32 v50, 0xbfb8aa3b, v46
	v_mul_f32_e32 v51, 0xbfb8aa3b, v47
	v_exp_f32_e32 v50, v50
	v_exp_f32_e32 v51, v51
	v_and_b32_e32 v49, 0xffff0000, v49
	v_cvt_pk_bf16_f32 v44, v44, v45
	v_add_f32_e32 v50, 1.0, v50
	v_add_f32_e32 v51, 1.0, v51
	v_rcp_f32_e32 v50, v50
	v_rcp_f32_e32 v51, v51
	s_nop 0
	v_pk_mul_f32 v[46:47], v[46:47], v[50:51]
	s_nop 0
	v_pk_mul_f32 v[46:47], v[46:47], v[48:49]
	v_mul_f32_e32 v48, 0xbfb8aa3b, v40
	v_cvt_pk_bf16_f32 v45, v46, v47
	global_store_dwordx2 v[64:65], v[44:45], off offset:128
	global_load_dwordx2 v[44:45], v[64:65], off offset:160
	v_mul_f32_e32 v49, 0xbfb8aa3b, v41
	v_exp_f32_e32 v48, v48
	v_exp_f32_e32 v49, v49
	v_add_f32_e32 v48, 1.0, v48
	v_add_f32_e32 v49, 1.0, v49
	v_rcp_f32_e32 v48, v48
	v_rcp_f32_e32 v49, v49
	s_waitcnt vmcnt(0)
	v_lshlrev_b32_e32 v46, 16, v44
	v_and_b32_e32 v47, 0xffff0000, v44
	v_pk_mul_f32 v[40:41], v[40:41], v[48:49]
	v_lshlrev_b32_e32 v44, 16, v45
	v_pk_mul_f32 v[40:41], v[40:41], v[46:47]
	v_mul_f32_e32 v46, 0xbfb8aa3b, v42
	v_mul_f32_e32 v47, 0xbfb8aa3b, v43
	v_exp_f32_e32 v46, v46
	v_exp_f32_e32 v47, v47
	v_and_b32_e32 v45, 0xffff0000, v45
	v_cvt_pk_bf16_f32 v40, v40, v41
	v_add_f32_e32 v46, 1.0, v46
	v_add_f32_e32 v47, 1.0, v47
	v_rcp_f32_e32 v46, v46
	v_rcp_f32_e32 v47, v47
	s_nop 0
	v_pk_mul_f32 v[42:43], v[42:43], v[46:47]
	s_nop 0
	v_pk_mul_f32 v[42:43], v[42:43], v[44:45]
	v_mul_f32_e32 v44, 0xbfb8aa3b, v36
	v_cvt_pk_bf16_f32 v41, v42, v43
	global_store_dwordx2 v[64:65], v[40:41], off offset:160
	global_load_dwordx2 v[40:41], v[64:65], off offset:192
	v_mul_f32_e32 v45, 0xbfb8aa3b, v37
	v_exp_f32_e32 v44, v44
	v_exp_f32_e32 v45, v45
	v_add_f32_e32 v44, 1.0, v44
	v_add_f32_e32 v45, 1.0, v45
	v_rcp_f32_e32 v44, v44
	v_rcp_f32_e32 v45, v45
	s_waitcnt vmcnt(0)
	v_lshlrev_b32_e32 v42, 16, v40
	v_and_b32_e32 v43, 0xffff0000, v40
	v_pk_mul_f32 v[36:37], v[36:37], v[44:45]
	v_lshlrev_b32_e32 v40, 16, v41
	v_pk_mul_f32 v[36:37], v[36:37], v[42:43]
	v_mul_f32_e32 v42, 0xbfb8aa3b, v38
	v_mul_f32_e32 v43, 0xbfb8aa3b, v39
	v_exp_f32_e32 v42, v42
	v_exp_f32_e32 v43, v43
	v_and_b32_e32 v41, 0xffff0000, v41
	v_cvt_pk_bf16_f32 v36, v36, v37
	v_add_f32_e32 v42, 1.0, v42
	v_add_f32_e32 v43, 1.0, v43
	v_rcp_f32_e32 v42, v42
	v_rcp_f32_e32 v43, v43
	s_nop 0
	v_pk_mul_f32 v[38:39], v[38:39], v[42:43]
	s_nop 0
	v_pk_mul_f32 v[38:39], v[38:39], v[40:41]
	v_mul_f32_e32 v40, 0xbfb8aa3b, v32
	v_cvt_pk_bf16_f32 v37, v38, v39
	global_store_dwordx2 v[64:65], v[36:37], off offset:192
	global_load_dwordx2 v[36:37], v[64:65], off offset:224
	v_mul_f32_e32 v41, 0xbfb8aa3b, v33
	v_exp_f32_e32 v40, v40
	v_exp_f32_e32 v41, v41
	v_add_f32_e32 v40, 1.0, v40
	v_add_f32_e32 v41, 1.0, v41
	v_rcp_f32_e32 v40, v40
	v_rcp_f32_e32 v41, v41
	s_waitcnt vmcnt(0)
	v_lshlrev_b32_e32 v38, 16, v36
	v_and_b32_e32 v39, 0xffff0000, v36
	v_pk_mul_f32 v[32:33], v[32:33], v[40:41]
	v_lshlrev_b32_e32 v36, 16, v37
	v_pk_mul_f32 v[32:33], v[32:33], v[38:39]
	v_mul_f32_e32 v38, 0xbfb8aa3b, v34
	v_mul_f32_e32 v39, 0xbfb8aa3b, v35
	v_exp_f32_e32 v38, v38
	v_exp_f32_e32 v39, v39
	v_and_b32_e32 v37, 0xffff0000, v37
	v_cvt_pk_bf16_f32 v32, v32, v33
	v_add_f32_e32 v38, 1.0, v38
	v_add_f32_e32 v39, 1.0, v39
	v_rcp_f32_e32 v38, v38
	v_rcp_f32_e32 v39, v39
	s_nop 0
	v_pk_mul_f32 v[34:35], v[34:35], v[38:39]
	s_nop 0
	v_pk_mul_f32 v[34:35], v[34:35], v[36:37]
	v_mul_f32_e32 v38, 0xbfb8aa3b, v28
	v_cvt_pk_bf16_f32 v33, v34, v35
	global_store_dwordx2 v[64:65], v[32:33], off offset:224
	v_or_b32_e32 v32, 48, v108
	v_ashrrev_i32_e32 v33, 31, v32
	v_lshlrev_b64 v[32:33], 13, v[32:33]
	v_lshl_add_u64 v[32:33], s[58:59], 0, v[32:33]
	v_lshl_add_u64 v[32:33], v[32:33], 0, v[152:153]
	global_load_dwordx2 v[34:35], v[32:33], off
	v_mul_f32_e32 v39, 0xbfb8aa3b, v29
	v_exp_f32_e32 v38, v38
	v_exp_f32_e32 v39, v39
	v_add_f32_e32 v38, 1.0, v38
	v_add_f32_e32 v39, 1.0, v39
	v_rcp_f32_e32 v38, v38
	v_rcp_f32_e32 v39, v39
	s_waitcnt vmcnt(0)
	v_lshlrev_b32_e32 v36, 16, v34
	v_and_b32_e32 v37, 0xffff0000, v34
	v_pk_mul_f32 v[28:29], v[28:29], v[38:39]
	v_lshlrev_b32_e32 v34, 16, v35
	v_pk_mul_f32 v[28:29], v[28:29], v[36:37]
	v_mul_f32_e32 v36, 0xbfb8aa3b, v30
	v_mul_f32_e32 v37, 0xbfb8aa3b, v31
	v_exp_f32_e32 v36, v36
	v_exp_f32_e32 v37, v37
	v_and_b32_e32 v35, 0xffff0000, v35
	v_cvt_pk_bf16_f32 v28, v28, v29
	v_add_f32_e32 v36, 1.0, v36
	v_add_f32_e32 v37, 1.0, v37
	v_rcp_f32_e32 v36, v36
	v_rcp_f32_e32 v37, v37
	s_nop 0
	v_pk_mul_f32 v[30:31], v[30:31], v[36:37]
	s_nop 0
	v_pk_mul_f32 v[30:31], v[30:31], v[34:35]
	v_mul_f32_e32 v34, 0xbfb8aa3b, v24
	v_cvt_pk_bf16_f32 v29, v30, v31
	global_store_dwordx2 v[32:33], v[28:29], off
	global_load_dwordx2 v[28:29], v[32:33], off offset:32
	v_mul_f32_e32 v35, 0xbfb8aa3b, v25
	v_exp_f32_e32 v34, v34
	v_exp_f32_e32 v35, v35
	v_add_f32_e32 v34, 1.0, v34
	v_add_f32_e32 v35, 1.0, v35
	v_rcp_f32_e32 v34, v34
	v_rcp_f32_e32 v35, v35
	s_waitcnt vmcnt(0)
	v_lshlrev_b32_e32 v30, 16, v28
	v_and_b32_e32 v31, 0xffff0000, v28
	v_pk_mul_f32 v[24:25], v[24:25], v[34:35]
	v_lshlrev_b32_e32 v28, 16, v29
	v_pk_mul_f32 v[24:25], v[24:25], v[30:31]
	v_mul_f32_e32 v30, 0xbfb8aa3b, v26
	v_mul_f32_e32 v31, 0xbfb8aa3b, v27
	v_exp_f32_e32 v30, v30
	v_exp_f32_e32 v31, v31
	v_and_b32_e32 v29, 0xffff0000, v29
	v_cvt_pk_bf16_f32 v24, v24, v25
	v_add_f32_e32 v30, 1.0, v30
	v_add_f32_e32 v31, 1.0, v31
	v_rcp_f32_e32 v30, v30
	v_rcp_f32_e32 v31, v31
	s_nop 0
	v_pk_mul_f32 v[26:27], v[26:27], v[30:31]
	s_nop 0
	v_pk_mul_f32 v[26:27], v[26:27], v[28:29]
	v_mul_f32_e32 v28, 0xbfb8aa3b, v20
	v_cvt_pk_bf16_f32 v25, v26, v27
	global_store_dwordx2 v[32:33], v[24:25], off offset:32
	global_load_dwordx2 v[24:25], v[32:33], off offset:64
	v_mul_f32_e32 v29, 0xbfb8aa3b, v21
	v_exp_f32_e32 v28, v28
	v_exp_f32_e32 v29, v29
	v_add_f32_e32 v28, 1.0, v28
	v_add_f32_e32 v29, 1.0, v29
	v_rcp_f32_e32 v28, v28
	v_rcp_f32_e32 v29, v29
	s_waitcnt vmcnt(0)
	v_lshlrev_b32_e32 v26, 16, v24
	v_and_b32_e32 v27, 0xffff0000, v24
	v_pk_mul_f32 v[20:21], v[20:21], v[28:29]
	v_lshlrev_b32_e32 v24, 16, v25
	v_pk_mul_f32 v[20:21], v[20:21], v[26:27]
	v_mul_f32_e32 v26, 0xbfb8aa3b, v22
	v_mul_f32_e32 v27, 0xbfb8aa3b, v23
	v_exp_f32_e32 v26, v26
	v_exp_f32_e32 v27, v27
	v_and_b32_e32 v25, 0xffff0000, v25
	v_cvt_pk_bf16_f32 v20, v20, v21
	v_add_f32_e32 v26, 1.0, v26
	v_add_f32_e32 v27, 1.0, v27
	v_rcp_f32_e32 v26, v26
	v_rcp_f32_e32 v27, v27
	s_nop 0
	v_pk_mul_f32 v[22:23], v[22:23], v[26:27]
	s_nop 0
	v_pk_mul_f32 v[22:23], v[22:23], v[24:25]
	v_mul_f32_e32 v24, 0xbfb8aa3b, v16
	v_cvt_pk_bf16_f32 v21, v22, v23
	global_store_dwordx2 v[32:33], v[20:21], off offset:64
	global_load_dwordx2 v[20:21], v[32:33], off offset:96
	v_mul_f32_e32 v25, 0xbfb8aa3b, v17
	v_exp_f32_e32 v24, v24
	v_exp_f32_e32 v25, v25
	v_add_f32_e32 v24, 1.0, v24
	v_add_f32_e32 v25, 1.0, v25
	v_rcp_f32_e32 v24, v24
	v_rcp_f32_e32 v25, v25
	s_waitcnt vmcnt(0)
	v_lshlrev_b32_e32 v22, 16, v20
	v_and_b32_e32 v23, 0xffff0000, v20
	v_pk_mul_f32 v[16:17], v[16:17], v[24:25]
	v_lshlrev_b32_e32 v20, 16, v21
	v_pk_mul_f32 v[16:17], v[16:17], v[22:23]
	v_mul_f32_e32 v22, 0xbfb8aa3b, v18
	v_mul_f32_e32 v23, 0xbfb8aa3b, v19
	v_exp_f32_e32 v22, v22
	v_exp_f32_e32 v23, v23
	v_and_b32_e32 v21, 0xffff0000, v21
	v_cvt_pk_bf16_f32 v16, v16, v17
	v_add_f32_e32 v22, 1.0, v22
	v_add_f32_e32 v23, 1.0, v23
	v_rcp_f32_e32 v22, v22
	v_rcp_f32_e32 v23, v23
	s_nop 0
	v_pk_mul_f32 v[18:19], v[18:19], v[22:23]
	s_nop 0
	v_pk_mul_f32 v[18:19], v[18:19], v[20:21]
	v_mul_f32_e32 v20, 0xbfb8aa3b, v12
	v_cvt_pk_bf16_f32 v17, v18, v19
	global_store_dwordx2 v[32:33], v[16:17], off offset:96
	global_load_dwordx2 v[16:17], v[32:33], off offset:128
	v_mul_f32_e32 v21, 0xbfb8aa3b, v13
	v_exp_f32_e32 v20, v20
	v_exp_f32_e32 v21, v21
	v_add_f32_e32 v20, 1.0, v20
	v_add_f32_e32 v21, 1.0, v21
	v_rcp_f32_e32 v20, v20
	v_rcp_f32_e32 v21, v21
	s_waitcnt vmcnt(0)
	v_lshlrev_b32_e32 v18, 16, v16
	v_and_b32_e32 v19, 0xffff0000, v16
	v_pk_mul_f32 v[12:13], v[12:13], v[20:21]
	v_lshlrev_b32_e32 v16, 16, v17
	v_pk_mul_f32 v[12:13], v[12:13], v[18:19]
	v_mul_f32_e32 v18, 0xbfb8aa3b, v14
	v_mul_f32_e32 v19, 0xbfb8aa3b, v15
	v_exp_f32_e32 v18, v18
	v_exp_f32_e32 v19, v19
	v_and_b32_e32 v17, 0xffff0000, v17
	v_cvt_pk_bf16_f32 v12, v12, v13
	v_add_f32_e32 v18, 1.0, v18
	v_add_f32_e32 v19, 1.0, v19
	v_rcp_f32_e32 v18, v18
	v_rcp_f32_e32 v19, v19
	s_nop 0
	v_pk_mul_f32 v[14:15], v[14:15], v[18:19]
	s_nop 0
	v_pk_mul_f32 v[14:15], v[14:15], v[16:17]
	v_mul_f32_e32 v16, 0xbfb8aa3b, v8
	v_cvt_pk_bf16_f32 v13, v14, v15
	global_store_dwordx2 v[32:33], v[12:13], off offset:128
	global_load_dwordx2 v[12:13], v[32:33], off offset:160
	v_mul_f32_e32 v17, 0xbfb8aa3b, v9
	v_exp_f32_e32 v16, v16
	v_exp_f32_e32 v17, v17
	v_add_f32_e32 v16, 1.0, v16
	v_add_f32_e32 v17, 1.0, v17
	v_rcp_f32_e32 v16, v16
	v_rcp_f32_e32 v17, v17
	s_waitcnt vmcnt(0)
	v_lshlrev_b32_e32 v14, 16, v12
	v_and_b32_e32 v15, 0xffff0000, v12
	v_pk_mul_f32 v[8:9], v[8:9], v[16:17]
	v_lshlrev_b32_e32 v12, 16, v13
	v_pk_mul_f32 v[8:9], v[8:9], v[14:15]
	v_mul_f32_e32 v14, 0xbfb8aa3b, v10
	v_mul_f32_e32 v15, 0xbfb8aa3b, v11
	v_exp_f32_e32 v14, v14
	v_exp_f32_e32 v15, v15
	v_and_b32_e32 v13, 0xffff0000, v13
	v_cvt_pk_bf16_f32 v8, v8, v9
	v_add_f32_e32 v14, 1.0, v14
	v_add_f32_e32 v15, 1.0, v15
	v_rcp_f32_e32 v14, v14
	v_rcp_f32_e32 v15, v15
	s_nop 0
	v_pk_mul_f32 v[10:11], v[10:11], v[14:15]
	s_nop 0
	v_pk_mul_f32 v[10:11], v[10:11], v[12:13]
	v_mul_f32_e32 v12, 0xbfb8aa3b, v4
	v_cvt_pk_bf16_f32 v9, v10, v11
	global_store_dwordx2 v[32:33], v[8:9], off offset:160
	global_load_dwordx2 v[8:9], v[32:33], off offset:192
	v_mul_f32_e32 v13, 0xbfb8aa3b, v5
	v_exp_f32_e32 v12, v12
	v_exp_f32_e32 v13, v13
	v_add_f32_e32 v12, 1.0, v12
	v_add_f32_e32 v13, 1.0, v13
	v_rcp_f32_e32 v12, v12
	v_rcp_f32_e32 v13, v13
	s_waitcnt vmcnt(0)
	v_lshlrev_b32_e32 v10, 16, v8
	v_and_b32_e32 v11, 0xffff0000, v8
	v_pk_mul_f32 v[4:5], v[4:5], v[12:13]
	v_lshlrev_b32_e32 v8, 16, v9
	v_pk_mul_f32 v[4:5], v[4:5], v[10:11]
	v_mul_f32_e32 v10, 0xbfb8aa3b, v6
	v_mul_f32_e32 v11, 0xbfb8aa3b, v7
	v_exp_f32_e32 v10, v10
	v_exp_f32_e32 v11, v11
	v_and_b32_e32 v9, 0xffff0000, v9
	v_cvt_pk_bf16_f32 v4, v4, v5
	v_add_f32_e32 v10, 1.0, v10
	v_add_f32_e32 v11, 1.0, v11
	v_rcp_f32_e32 v10, v10
	v_rcp_f32_e32 v11, v11
	s_nop 0
	v_pk_mul_f32 v[6:7], v[6:7], v[10:11]
	s_nop 0
	v_pk_mul_f32 v[6:7], v[6:7], v[8:9]
	v_mul_f32_e32 v8, 0xbfb8aa3b, v0
	v_cvt_pk_bf16_f32 v5, v6, v7
	global_store_dwordx2 v[32:33], v[4:5], off offset:192
	global_load_dwordx2 v[4:5], v[32:33], off offset:224
	v_mul_f32_e32 v9, 0xbfb8aa3b, v1
	v_exp_f32_e32 v8, v8
	v_exp_f32_e32 v9, v9
	v_add_f32_e32 v8, 1.0, v8
	v_add_f32_e32 v9, 1.0, v9
	v_rcp_f32_e32 v8, v8
	v_rcp_f32_e32 v9, v9
	s_waitcnt vmcnt(0)
	v_lshlrev_b32_e32 v6, 16, v4
	v_and_b32_e32 v7, 0xffff0000, v4
	v_pk_mul_f32 v[0:1], v[0:1], v[8:9]
	v_lshlrev_b32_e32 v4, 16, v5
	v_pk_mul_f32 v[0:1], v[0:1], v[6:7]
	v_mul_f32_e32 v6, 0xbfb8aa3b, v2
	v_mul_f32_e32 v7, 0xbfb8aa3b, v3
	v_exp_f32_e32 v6, v6
	v_exp_f32_e32 v7, v7
	v_and_b32_e32 v5, 0xffff0000, v5
	v_cvt_pk_bf16_f32 v0, v0, v1
	v_add_f32_e32 v6, 1.0, v6
	v_add_f32_e32 v7, 1.0, v7
	v_rcp_f32_e32 v6, v6
	v_rcp_f32_e32 v7, v7
	s_nop 0
	v_pk_mul_f32 v[2:3], v[2:3], v[6:7]
	s_nop 0
	v_pk_mul_f32 v[2:3], v[2:3], v[4:5]
	s_nop 0
	v_cvt_pk_bf16_f32 v1, v2, v3
	global_store_dwordx2 v[32:33], v[0:1], off offset:224
	s_cbranch_scc1 .LBB0_640

.LBB0_677:
	s_waitcnt vmcnt(5)
	ds_write_b128 v158, v[112:115]
	s_waitcnt vmcnt(4)
	ds_write_b128 v158, v[116:119] offset:6144
	s_waitcnt vmcnt(3)
	ds_write_b128 v158, v[120:123] offset:12288
	s_waitcnt vmcnt(2)
	ds_write_b128 v158, v[124:127] offset:18432
	s_waitcnt vmcnt(1)
	ds_write_b128 v158, v[136:139] offset:24576
	s_waitcnt vmcnt(0)
	ds_write_b128 v158, v[140:143] offset:30720
	v_lshl_add_u64 v[116:117], v[162:163], 0, s[0:1]
	v_add_co_u32_e32 v124, vcc, s70, v116
	s_waitcnt lgkmcnt(0)
	s_barrier
	ds_read_b128 v[112:115], v168 offset:12288
	ds_read_b128 v[120:123], v168 offset:13824
	ds_read_b128 v[172:175], v167
	ds_read_b128 v[176:179], v167 offset:1536
	ds_read_b128 v[140:143], v168 offset:15360
	ds_read_b128 v[180:183], v168 offset:16896
	v_lshl_add_u64 v[118:119], v[164:165], 0, s[0:1]
	v_addc_co_u32_e32 v125, vcc, 0, v117, vcc
	v_add_co_u32_e32 v126, vcc, s78, v118
	ds_read_b128 v[184:187], v167 offset:3072
	ds_read_b128 v[200:203], v167 offset:4608
	v_addc_co_u32_e32 v127, vcc, 0, v119, vcc
	v_add_co_u32_e32 v136, vcc, s80, v118
	s_waitcnt lgkmcnt(5)
	v_mfma_f32_16x16x32_bf16 v[148:151], v[112:115], v[172:175], v[148:151]
	v_addc_co_u32_e32 v137, vcc, 0, v119, vcc
	v_add_co_u32_e32 v138, vcc, s83, v118
	v_mfma_f32_16x16x32_bf16 v[144:147], v[120:123], v[172:175], v[144:147]
	s_nop 0
	v_addc_co_u32_e32 v139, vcc, 0, v119, vcc
	v_add_co_u32_e32 v204, vcc, s73, v118
	s_waitcnt lgkmcnt(4)
	v_mfma_f32_16x16x32_bf16 v[108:111], v[112:115], v[176:179], v[108:111]
	v_addc_co_u32_e32 v205, vcc, 0, v119, vcc
	v_mfma_f32_16x16x32_bf16 v[104:107], v[120:123], v[176:179], v[104:107]
	s_waitcnt lgkmcnt(1)
	v_mfma_f32_16x16x32_bf16 v[76:79], v[112:115], v[184:187], v[76:79]
	v_mfma_f32_16x16x32_bf16 v[72:75], v[120:123], v[184:187], v[72:75]
	s_waitcnt lgkmcnt(0)
	v_mfma_f32_16x16x32_bf16 v[44:47], v[112:115], v[200:203], v[44:47]
	global_load_dwordx4 v[112:115], v[116:117], off offset:64
	s_nop 0
	global_load_dwordx4 v[116:119], v[124:125], off offset:64
	v_mfma_f32_16x16x32_bf16 v[40:43], v[120:123], v[200:203], v[40:43]
	global_load_dwordx4 v[120:123], v[126:127], off offset:64
	s_nop 0
	global_load_dwordx4 v[124:127], v[136:137], off offset:64
	s_nop 0
	global_load_dwordx4 v[136:139], v[138:139], off offset:64
	v_mfma_f32_16x16x32_bf16 v[132:135], v[140:143], v[172:175], v[132:135]
	v_mfma_f32_16x16x32_bf16 v[96:99], v[140:143], v[176:179], v[96:99]
	v_mfma_f32_16x16x32_bf16 v[64:67], v[140:143], v[184:187], v[64:67]
	v_mfma_f32_16x16x32_bf16 v[32:35], v[140:143], v[200:203], v[32:35]
	global_load_dwordx4 v[140:143], v[204:205], off offset:64
	v_mfma_f32_16x16x32_bf16 v[128:131], v[180:183], v[172:175], v[128:131]
	v_mfma_f32_16x16x32_bf16 v[88:91], v[180:183], v[176:179], v[88:91]
	v_mfma_f32_16x16x32_bf16 v[56:59], v[180:183], v[184:187], v[56:59]
	v_mfma_f32_16x16x32_bf16 v[24:27], v[180:183], v[200:203], v[24:27]
	ds_read_b128 v[180:183], v168 offset:18432
	ds_read_b128 v[204:207], v168 offset:19968
	ds_read_b128 v[208:211], v168 offset:21504
	ds_read_b128 v[212:215], v168 offset:23040
	s_waitcnt lgkmcnt(3)
	v_mfma_f32_16x16x32_bf16 v[100:103], v[180:183], v[172:175], v[100:103]
	s_waitcnt lgkmcnt(2)
	v_mfma_f32_16x16x32_bf16 v[92:95], v[204:207], v[172:175], v[92:95]
	s_waitcnt lgkmcnt(1)
	v_mfma_f32_16x16x32_bf16 v[84:87], v[208:211], v[172:175], v[84:87]
	s_waitcnt lgkmcnt(0)
	s_barrier
	v_mfma_f32_16x16x32_bf16 v[80:83], v[212:215], v[172:175], v[80:83]
	v_mfma_f32_16x16x32_bf16 v[68:71], v[180:183], v[176:179], v[68:71]
	v_mfma_f32_16x16x32_bf16 v[60:63], v[204:207], v[176:179], v[60:63]
	v_mfma_f32_16x16x32_bf16 v[52:55], v[208:211], v[176:179], v[52:55]
	v_mfma_f32_16x16x32_bf16 v[48:51], v[212:215], v[176:179], v[48:51]
	v_mfma_f32_16x16x32_bf16 v[36:39], v[180:183], v[184:187], v[36:39]
	v_mfma_f32_16x16x32_bf16 v[28:31], v[204:207], v[184:187], v[28:31]
	v_mfma_f32_16x16x32_bf16 v[20:23], v[208:211], v[184:187], v[20:23]
	v_mfma_f32_16x16x32_bf16 v[16:19], v[212:215], v[184:187], v[16:19]
	v_mfma_f32_16x16x32_bf16 v[12:15], v[180:183], v[200:203], v[12:15]
	v_mfma_f32_16x16x32_bf16 v[8:11], v[204:207], v[200:203], v[8:11]
	v_mfma_f32_16x16x32_bf16 v[4:7], v[208:211], v[200:203], v[4:7]
	v_mfma_f32_16x16x32_bf16 v[0:3], v[212:215], v[200:203], v[0:3]
	s_add_u32 s0, s0, 64
	s_addc_u32 s1, s1, 0
	s_cmpk_lg_i32 s0, 0x1fc0
	s_cbranch_scc1 .LBB0_677
	s_waitcnt vmcnt(5)
	ds_write_b128 v158, v[112:115]
	s_waitcnt vmcnt(4)
	ds_write_b128 v158, v[116:119] offset:6144
	s_waitcnt vmcnt(3)
	ds_write_b128 v158, v[120:123] offset:12288
	s_waitcnt vmcnt(2)
	ds_write_b128 v158, v[124:127] offset:18432
	s_waitcnt vmcnt(1)
	ds_write_b128 v158, v[136:139] offset:24576
	s_waitcnt vmcnt(0)
	ds_write_b128 v158, v[140:143] offset:30720
	s_waitcnt lgkmcnt(0)
	s_barrier
	ds_read_b128 v[112:115], v168 offset:12288
	ds_read_b128 v[116:119], v168 offset:13824
	ds_read_b128 v[120:123], v167
	ds_read_b128 v[124:127], v167 offset:1536
	s_waitcnt lgkmcnt(1)
	v_mfma_f32_16x16x32_bf16 v[136:139], v[112:115], v[120:123], v[148:151]
	ds_read_b128 v[140:143], v168 offset:15360
	s_nop 1
	ds_read_b128 v[148:151], v168 offset:16896
	ds_read_b128 v[162:165], v167 offset:3072
	ds_read_b128 v[172:175], v167 offset:4608
	v_mfma_f32_16x16x32_bf16 v[144:147], v[116:119], v[120:123], v[144:147]
	s_waitcnt lgkmcnt(3)
	v_mfma_f32_16x16x32_bf16 v[132:135], v[140:143], v[120:123], v[132:135]
	s_waitcnt lgkmcnt(2)
	v_mfma_f32_16x16x32_bf16 v[128:131], v[148:151], v[120:123], v[128:131]
	v_mfma_f32_16x16x32_bf16 v[108:111], v[112:115], v[124:127], v[108:111]
	v_mfma_f32_16x16x32_bf16 v[104:107], v[116:119], v[124:127], v[104:107]
	v_mfma_f32_16x16x32_bf16 v[96:99], v[140:143], v[124:127], v[96:99]
	v_mfma_f32_16x16x32_bf16 v[88:91], v[148:151], v[124:127], v[88:91]
	s_waitcnt lgkmcnt(1)
	v_mfma_f32_16x16x32_bf16 v[76:79], v[112:115], v[162:165], v[76:79]
	v_mfma_f32_16x16x32_bf16 v[72:75], v[116:119], v[162:165], v[72:75]
	v_mfma_f32_16x16x32_bf16 v[64:67], v[140:143], v[162:165], v[64:67]
	v_mfma_f32_16x16x32_bf16 v[56:59], v[148:151], v[162:165], v[56:59]
	s_waitcnt lgkmcnt(0)
	v_mfma_f32_16x16x32_bf16 v[44:47], v[112:115], v[172:175], v[44:47]
	v_mfma_f32_16x16x32_bf16 v[40:43], v[116:119], v[172:175], v[40:43]
	v_mfma_f32_16x16x32_bf16 v[32:35], v[140:143], v[172:175], v[32:35]
	v_mfma_f32_16x16x32_bf16 v[24:27], v[148:151], v[172:175], v[24:27]
	ds_read_b128 v[112:115], v168 offset:18432
	ds_read_b128 v[116:119], v168 offset:19968
	ds_read_b128 v[140:143], v168 offset:21504
	ds_read_b128 v[148:151], v168 offset:23040
	s_waitcnt lgkmcnt(3)
	v_mfma_f32_16x16x32_bf16 v[100:103], v[112:115], v[120:123], v[100:103]
	s_waitcnt lgkmcnt(2)
	v_mfma_f32_16x16x32_bf16 v[92:95], v[116:119], v[120:123], v[92:95]
	s_waitcnt lgkmcnt(1)
	v_mfma_f32_16x16x32_bf16 v[84:87], v[140:143], v[120:123], v[84:87]
	s_waitcnt lgkmcnt(0)
	v_mfma_f32_16x16x32_bf16 v[80:83], v[148:151], v[120:123], v[80:83]
	v_mfma_f32_16x16x32_bf16 v[68:71], v[112:115], v[124:127], v[68:71]
	v_mfma_f32_16x16x32_bf16 v[60:63], v[116:119], v[124:127], v[60:63]
	v_mfma_f32_16x16x32_bf16 v[52:55], v[140:143], v[124:127], v[52:55]
	v_mfma_f32_16x16x32_bf16 v[48:51], v[148:151], v[124:127], v[48:51]
	v_mfma_f32_16x16x32_bf16 v[36:39], v[112:115], v[162:165], v[36:39]
	v_mfma_f32_16x16x32_bf16 v[28:31], v[116:119], v[162:165], v[28:31]
	v_mfma_f32_16x16x32_bf16 v[20:23], v[140:143], v[162:165], v[20:23]
	v_mfma_f32_16x16x32_bf16 v[16:19], v[148:151], v[162:165], v[16:19]
	v_mfma_f32_16x16x32_bf16 v[12:15], v[112:115], v[172:175], v[12:15]
	v_mfma_f32_16x16x32_bf16 v[8:11], v[116:119], v[172:175], v[8:11]
	v_mfma_f32_16x16x32_bf16 v[4:7], v[140:143], v[172:175], v[4:7]
	v_mfma_f32_16x16x32_bf16 v[0:3], v[148:151], v[172:175], v[0:3]
	v_or_b32_e32 v112, s3, v159
	v_add_u32_e32 v112, v112, v169
	v_ashrrev_i32_e32 v113, 31, v112
	v_or_b32_e32 v116, s4, v170
	v_lshlrev_b64 v[114:115], 13, v[112:113]
	v_lshl_add_u64 v[114:115], s[60:61], 0, v[114:115]
	v_lshlrev_b32_e32 v152, 2, v116
	v_lshl_add_u64 v[114:115], v[114:115], 0, v[152:153]
	s_barrier
	global_store_dwordx4 v[114:115], v[136:139], off
	global_store_dwordx4 v[114:115], v[144:147], off offset:64
	global_store_dwordx4 v[114:115], v[132:135], off offset:128
	global_store_dwordx4 v[114:115], v[128:131], off offset:192
	global_store_dwordx4 v[114:115], v[100:103], off offset:256
	global_store_dwordx4 v[114:115], v[92:95], off offset:320
	global_store_dwordx4 v[114:115], v[84:87], off offset:384
	global_store_dwordx4 v[114:115], v[80:83], off offset:448
	s_add_i32 s2, s2, s33
	s_cmpk_lt_i32 s2, 0x600
	v_or_b32_e32 v80, 16, v112
	v_ashrrev_i32_e32 v81, 31, v80
	v_lshlrev_b64 v[80:81], 13, v[80:81]
	v_lshl_add_u64 v[80:81], s[60:61], 0, v[80:81]
	v_lshl_add_u64 v[80:81], v[80:81], 0, v[152:153]
	global_store_dwordx4 v[80:81], v[108:111], off
	global_store_dwordx4 v[80:81], v[104:107], off offset:64
	global_store_dwordx4 v[80:81], v[96:99], off offset:128
	global_store_dwordx4 v[80:81], v[88:91], off offset:192
	global_store_dwordx4 v[80:81], v[68:71], off offset:256
	global_store_dwordx4 v[80:81], v[60:63], off offset:320
	global_store_dwordx4 v[80:81], v[52:55], off offset:384
	global_store_dwordx4 v[80:81], v[48:51], off offset:448
	s_nop 1
	v_or_b32_e32 v48, 32, v112
	v_ashrrev_i32_e32 v49, 31, v48
	v_lshlrev_b64 v[48:49], 13, v[48:49]
	v_lshl_add_u64 v[48:49], s[60:61], 0, v[48:49]
	v_lshl_add_u64 v[48:49], v[48:49], 0, v[152:153]
	global_store_dwordx4 v[48:49], v[76:79], off
	global_store_dwordx4 v[48:49], v[72:75], off offset:64
	global_store_dwordx4 v[48:49], v[64:67], off offset:128
	global_store_dwordx4 v[48:49], v[56:59], off offset:192
	global_store_dwordx4 v[48:49], v[36:39], off offset:256
	global_store_dwordx4 v[48:49], v[28:31], off offset:320
	global_store_dwordx4 v[48:49], v[20:23], off offset:384
	global_store_dwordx4 v[48:49], v[16:19], off offset:448
	s_nop 1
	v_or_b32_e32 v16, 48, v112
	v_ashrrev_i32_e32 v17, 31, v16
	v_lshlrev_b64 v[16:17], 13, v[16:17]
	v_lshl_add_u64 v[16:17], s[60:61], 0, v[16:17]
	v_lshl_add_u64 v[16:17], v[16:17], 0, v[152:153]
	global_store_dwordx4 v[16:17], v[44:47], off
	global_store_dwordx4 v[16:17], v[40:43], off offset:64
	global_store_dwordx4 v[16:17], v[32:35], off offset:128
	global_store_dwordx4 v[16:17], v[24:27], off offset:192
	global_store_dwordx4 v[16:17], v[12:15], off offset:256
	global_store_dwordx4 v[16:17], v[8:11], off offset:320
	global_store_dwordx4 v[16:17], v[4:7], off offset:384
	global_store_dwordx4 v[16:17], v[0:3], off offset:448
	s_cbranch_scc1 .LBB0_672

.LBB0_712:
	s_waitcnt vmcnt(5)
	ds_write_b128 v156, v[112:115]
	s_waitcnt vmcnt(4)
	ds_write_b128 v156, v[116:119] offset:6144
	s_waitcnt vmcnt(3)
	ds_write_b128 v156, v[120:123] offset:12288
	s_waitcnt vmcnt(2)
	ds_write_b128 v156, v[124:127] offset:18432
	s_waitcnt vmcnt(1)
	ds_write_b128 v156, v[136:139] offset:24576
	s_waitcnt vmcnt(0)
	ds_write_b128 v156, v[140:143] offset:30720
	v_lshl_add_u64 v[116:117], v[162:163], 0, s[0:1]
	v_add_co_u32_e32 v124, vcc, s69, v116
	s_waitcnt lgkmcnt(0)
	s_barrier
	ds_read_b128 v[112:115], v168 offset:12288
	ds_read_b128 v[120:123], v168 offset:13824
	ds_read_b128 v[172:175], v167
	ds_read_b128 v[176:179], v167 offset:1536
	ds_read_b128 v[140:143], v168 offset:15360
	ds_read_b128 v[180:183], v168 offset:16896
	v_lshl_add_u64 v[118:119], v[164:165], 0, s[0:1]
	v_addc_co_u32_e32 v125, vcc, 0, v117, vcc
	v_add_co_u32_e32 v126, vcc, s78, v118
	ds_read_b128 v[184:187], v167 offset:3072
	ds_read_b128 v[200:203], v167 offset:4608
	ds_read_b128 v[216:219], v168 offset:18432
	ds_read_b128 v[220:223], v168 offset:19968
	ds_read_b128 v[224:227], v168 offset:21504
	ds_read_b128 v[228:231], v168 offset:23040
	v_addc_co_u32_e32 v127, vcc, 0, v119, vcc
	v_add_co_u32_e32 v136, vcc, s79, v118
	s_waitcnt lgkmcnt(9)
	v_mfma_f32_16x16x32_bf16 v[148:151], v[112:115], v[172:175], v[148:151]
	v_addc_co_u32_e32 v137, vcc, 0, v119, vcc
	v_add_co_u32_e32 v138, vcc, s80, v118
	v_mfma_f32_16x16x32_bf16 v[144:147], v[120:123], v[172:175], v[144:147]
	s_nop 0
	v_addc_co_u32_e32 v139, vcc, 0, v119, vcc
	v_add_co_u32_e32 v204, vcc, s81, v118
	s_waitcnt lgkmcnt(8)
	v_mfma_f32_16x16x32_bf16 v[108:111], v[112:115], v[176:179], v[108:111]
	v_addc_co_u32_e32 v205, vcc, 0, v119, vcc
	v_mfma_f32_16x16x32_bf16 v[100:103], v[120:123], v[176:179], v[100:103]
	s_waitcnt lgkmcnt(5)
	v_mfma_f32_16x16x32_bf16 v[60:63], v[112:115], v[184:187], v[60:63]
	v_mfma_f32_16x16x32_bf16 v[56:59], v[120:123], v[184:187], v[56:59]
	s_waitcnt lgkmcnt(4)
	v_mfma_f32_16x16x32_bf16 v[28:31], v[112:115], v[200:203], v[28:31]
	global_load_dwordx4 v[112:115], v[116:117], off offset:64
	s_nop 0
	global_load_dwordx4 v[116:119], v[124:125], off offset:64
	v_mfma_f32_16x16x32_bf16 v[24:27], v[120:123], v[200:203], v[24:27]
	global_load_dwordx4 v[120:123], v[126:127], off offset:64
	s_nop 0
	global_load_dwordx4 v[124:127], v[136:137], off offset:64
	s_nop 0
	global_load_dwordx4 v[136:139], v[138:139], off offset:64
	v_mfma_f32_16x16x32_bf16 v[132:135], v[140:143], v[172:175], v[132:135]
	v_mfma_f32_16x16x32_bf16 v[84:87], v[140:143], v[176:179], v[84:87]
	v_mfma_f32_16x16x32_bf16 v[52:55], v[140:143], v[184:187], v[52:55]
	v_mfma_f32_16x16x32_bf16 v[20:23], v[140:143], v[200:203], v[20:23]
	global_load_dwordx4 v[140:143], v[204:205], off offset:64
	v_mfma_f32_16x16x32_bf16 v[128:131], v[180:183], v[172:175], v[128:131]
	v_mfma_f32_16x16x32_bf16 v[80:83], v[180:183], v[176:179], v[80:83]
	v_mfma_f32_16x16x32_bf16 v[48:51], v[180:183], v[184:187], v[48:51]
	v_mfma_f32_16x16x32_bf16 v[16:19], v[180:183], v[200:203], v[16:19]
	s_waitcnt lgkmcnt(3)
	v_mfma_f32_16x16x32_bf16 v[104:107], v[216:219], v[172:175], v[104:107]
	s_waitcnt lgkmcnt(2)
	v_mfma_f32_16x16x32_bf16 v[96:99], v[220:223], v[172:175], v[96:99]
	s_waitcnt lgkmcnt(1)
	v_mfma_f32_16x16x32_bf16 v[92:95], v[224:227], v[172:175], v[92:95]
	s_waitcnt lgkmcnt(0)
	s_barrier
	v_mfma_f32_16x16x32_bf16 v[88:91], v[228:231], v[172:175], v[88:91]
	v_mfma_f32_16x16x32_bf16 v[76:79], v[216:219], v[176:179], v[76:79]
	v_mfma_f32_16x16x32_bf16 v[72:75], v[220:223], v[176:179], v[72:75]
	v_mfma_f32_16x16x32_bf16 v[68:71], v[224:227], v[176:179], v[68:71]
	v_mfma_f32_16x16x32_bf16 v[64:67], v[228:231], v[176:179], v[64:67]
	v_mfma_f32_16x16x32_bf16 v[44:47], v[216:219], v[184:187], v[44:47]
	v_mfma_f32_16x16x32_bf16 v[40:43], v[220:223], v[184:187], v[40:43]
	v_mfma_f32_16x16x32_bf16 v[36:39], v[224:227], v[184:187], v[36:39]
	v_mfma_f32_16x16x32_bf16 v[32:35], v[228:231], v[184:187], v[32:35]
	v_mfma_f32_16x16x32_bf16 v[12:15], v[216:219], v[200:203], v[12:15]
	v_mfma_f32_16x16x32_bf16 v[8:11], v[220:223], v[200:203], v[8:11]
	v_mfma_f32_16x16x32_bf16 v[4:7], v[224:227], v[200:203], v[4:7]
	v_mfma_f32_16x16x32_bf16 v[0:3], v[228:231], v[200:203], v[0:3]
	s_add_u32 s0, s0, 64
	s_addc_u32 s1, s1, 0
	s_cmpk_lg_i32 s0, 0xfc0
	s_cbranch_scc1 .LBB0_712
	s_waitcnt vmcnt(5)
	ds_write_b128 v156, v[112:115]
	s_waitcnt vmcnt(4)
	ds_write_b128 v156, v[116:119] offset:6144
	s_waitcnt vmcnt(3)
	ds_write_b128 v156, v[120:123] offset:12288
	s_waitcnt vmcnt(2)
	ds_write_b128 v156, v[124:127] offset:18432
	s_waitcnt vmcnt(1)
	ds_write_b128 v156, v[136:139] offset:24576
	s_waitcnt vmcnt(0)
	ds_write_b128 v156, v[140:143] offset:30720
	s_waitcnt lgkmcnt(0)
	s_barrier
	ds_read_b128 v[136:139], v168 offset:12288
	ds_read_b128 v[140:143], v168 offset:13824
	ds_read_b128 v[162:165], v167
	ds_read_b128 v[172:175], v167 offset:1536
	s_waitcnt lgkmcnt(1)
	v_mfma_f32_16x16x32_bf16 v[124:127], v[136:139], v[162:165], v[148:151]
	s_nop 2
	ds_read_b128 v[148:151], v168 offset:15360
	v_mfma_f32_16x16x32_bf16 v[120:123], v[140:143], v[162:165], v[144:147]
	s_nop 2
	ds_read_b128 v[144:147], v168 offset:16896
	s_waitcnt lgkmcnt(1)
	v_mfma_f32_16x16x32_bf16 v[116:119], v[148:151], v[162:165], v[132:135]
	s_waitcnt lgkmcnt(0)
	v_mfma_f32_16x16x32_bf16 v[112:115], v[144:147], v[162:165], v[128:131]
	s_nop 2
	ds_read_b128 v[128:131], v167 offset:3072
	ds_read_b128 v[132:135], v167 offset:4608
	v_mfma_f32_16x16x32_bf16 v[108:111], v[136:139], v[172:175], v[108:111]
	v_mfma_f32_16x16x32_bf16 v[100:103], v[140:143], v[172:175], v[100:103]
	v_mfma_f32_16x16x32_bf16 v[84:87], v[148:151], v[172:175], v[84:87]
	v_mfma_f32_16x16x32_bf16 v[80:83], v[144:147], v[172:175], v[80:83]
	s_waitcnt lgkmcnt(1)
	v_mfma_f32_16x16x32_bf16 v[60:63], v[136:139], v[128:131], v[60:63]
	v_mfma_f32_16x16x32_bf16 v[56:59], v[140:143], v[128:131], v[56:59]
	v_mfma_f32_16x16x32_bf16 v[52:55], v[148:151], v[128:131], v[52:55]
	v_mfma_f32_16x16x32_bf16 v[48:51], v[144:147], v[128:131], v[48:51]
	s_waitcnt lgkmcnt(0)
	v_mfma_f32_16x16x32_bf16 v[28:31], v[136:139], v[132:135], v[28:31]
	v_mfma_f32_16x16x32_bf16 v[24:27], v[140:143], v[132:135], v[24:27]
	v_mfma_f32_16x16x32_bf16 v[20:23], v[148:151], v[132:135], v[20:23]
	v_mfma_f32_16x16x32_bf16 v[16:19], v[144:147], v[132:135], v[16:19]
	ds_read_b128 v[136:139], v168 offset:18432
	ds_read_b128 v[140:143], v168 offset:19968
	ds_read_b128 v[144:147], v168 offset:21504
	ds_read_b128 v[148:151], v168 offset:23040
	s_waitcnt lgkmcnt(3)
	v_mfma_f32_16x16x32_bf16 v[104:107], v[136:139], v[162:165], v[104:107]
	s_waitcnt lgkmcnt(2)
	v_mfma_f32_16x16x32_bf16 v[96:99], v[140:143], v[162:165], v[96:99]
	s_waitcnt lgkmcnt(1)
	v_mfma_f32_16x16x32_bf16 v[92:95], v[144:147], v[162:165], v[92:95]
	s_waitcnt lgkmcnt(0)
	v_mfma_f32_16x16x32_bf16 v[88:91], v[148:151], v[162:165], v[88:91]
	v_mfma_f32_16x16x32_bf16 v[76:79], v[136:139], v[172:175], v[76:79]
	v_mfma_f32_16x16x32_bf16 v[72:75], v[140:143], v[172:175], v[72:75]
	v_mfma_f32_16x16x32_bf16 v[68:71], v[144:147], v[172:175], v[68:71]
	v_mfma_f32_16x16x32_bf16 v[64:67], v[148:151], v[172:175], v[64:67]
	v_mfma_f32_16x16x32_bf16 v[44:47], v[136:139], v[128:131], v[44:47]
	v_mfma_f32_16x16x32_bf16 v[40:43], v[140:143], v[128:131], v[40:43]
	v_mfma_f32_16x16x32_bf16 v[36:39], v[144:147], v[128:131], v[36:39]
	v_mfma_f32_16x16x32_bf16 v[32:35], v[148:151], v[128:131], v[32:35]
	v_mfma_f32_16x16x32_bf16 v[12:15], v[136:139], v[132:135], v[12:15]
	v_mfma_f32_16x16x32_bf16 v[8:11], v[140:143], v[132:135], v[8:11]
	v_mfma_f32_16x16x32_bf16 v[4:7], v[144:147], v[132:135], v[4:7]
	v_mfma_f32_16x16x32_bf16 v[0:3], v[148:151], v[132:135], v[0:3]
	v_or_b32_e32 v128, s3, v157
	v_add_u32_e32 v128, v128, v169
	v_ashrrev_i32_e32 v129, 31, v128
	v_or_b32_e32 v134, s2, v170
	v_lshlrev_b64 v[132:133], 13, v[128:129]
	s_cmp_gt_u32 s5, 15
	v_lshl_add_u64 v[130:131], s[60:61], 0, v[132:133]
	s_mov_b64 s[2:3], -1
	s_cselect_b64 s[0:1], -1, 0
	s_cmp_lt_u32 s5, 16
	v_lshlrev_b32_e32 v152, 1, v134
	s_barrier
	s_cbranch_scc1 .LBB0_715
	v_mul_f32_e32 v129, 0xbfb8aa3b, v124
	v_exp_f32_e32 v129, v129
	v_mul_f32_e32 v134, 0xbfb8aa3b, v125
	v_exp_f32_e32 v134, v134
	v_mul_f32_e32 v136, 0xbfb8aa3b, v127
	v_add_f32_e32 v129, 1.0, v129
	v_exp_f32_e32 v137, v136
	v_add_f32_e32 v135, 1.0, v134
	v_rcp_f32_e32 v134, v129
	v_mul_f32_e32 v129, 0xbfb8aa3b, v126
	v_exp_f32_e32 v129, v129
	v_rcp_f32_e32 v135, v135
	v_lshl_add_u64 v[138:139], v[130:131], 0, v[152:153]
	s_mov_b64 s[2:3], 0
	v_add_f32_e32 v129, 1.0, v129
	v_rcp_f32_e32 v136, v129
	v_add_f32_e32 v129, 1.0, v137
	v_rcp_f32_e32 v137, v129
	v_pk_mul_f32 v[134:135], v[124:125], v[134:135]
	v_pk_mul_f32 v[136:137], v[126:127], v[136:137]
	v_cvt_pk_bf16_f32 v134, v134, v135
	v_cvt_pk_bf16_f32 v135, v136, v137
	v_add_co_u32_e32 v136, vcc, 0xffffe000, v138
	s_nop 1
	v_addc_co_u32_e32 v137, vcc, -1, v139, vcc
	global_store_dwordx2 v[136:137], v[134:135], off

.LBB0_1113:
	s_waitcnt vmcnt(5)
	ds_write_b128 v158, v[112:115]
	s_waitcnt vmcnt(4)
	ds_write_b128 v158, v[116:119] offset:6144
	s_waitcnt vmcnt(3)
	ds_write_b128 v158, v[120:123] offset:12288
	s_waitcnt vmcnt(2)
	ds_write_b128 v158, v[124:127] offset:18432
	s_waitcnt vmcnt(1)
	ds_write_b128 v158, v[136:139] offset:24576
	s_waitcnt vmcnt(0)
	ds_write_b128 v158, v[140:143] offset:30720
	v_lshl_add_u64 v[116:117], v[162:163], 0, s[0:1]
	v_add_co_u32_e32 v124, vcc, s70, v116
	s_waitcnt lgkmcnt(0)
	s_barrier
	ds_read_b128 v[112:115], v168 offset:12288
	ds_read_b128 v[120:123], v168 offset:13824
	ds_read_b128 v[172:175], v167
	ds_read_b128 v[176:179], v167 offset:1536
	ds_read_b128 v[140:143], v168 offset:15360
	ds_read_b128 v[180:183], v168 offset:16896
	v_lshl_add_u64 v[118:119], v[164:165], 0, s[0:1]
	v_addc_co_u32_e32 v125, vcc, 0, v117, vcc
	v_add_co_u32_e32 v126, vcc, s78, v118
	ds_read_b128 v[184:187], v167 offset:3072
	ds_read_b128 v[200:203], v167 offset:4608
	v_addc_co_u32_e32 v127, vcc, 0, v119, vcc
	v_add_co_u32_e32 v136, vcc, s80, v118
	s_waitcnt lgkmcnt(5)
	v_mfma_f32_16x16x32_bf16 v[148:151], v[112:115], v[172:175], v[148:151]
	v_addc_co_u32_e32 v137, vcc, 0, v119, vcc
	v_add_co_u32_e32 v138, vcc, s83, v118
	v_mfma_f32_16x16x32_bf16 v[144:147], v[120:123], v[172:175], v[144:147]
	s_nop 0
	v_addc_co_u32_e32 v139, vcc, 0, v119, vcc
	v_add_co_u32_e32 v204, vcc, s73, v118
	s_waitcnt lgkmcnt(4)
	v_mfma_f32_16x16x32_bf16 v[108:111], v[112:115], v[176:179], v[108:111]
	v_addc_co_u32_e32 v205, vcc, 0, v119, vcc
	v_mfma_f32_16x16x32_bf16 v[104:107], v[120:123], v[176:179], v[104:107]
	s_waitcnt lgkmcnt(1)
	v_mfma_f32_16x16x32_bf16 v[76:79], v[112:115], v[184:187], v[76:79]
	v_mfma_f32_16x16x32_bf16 v[72:75], v[120:123], v[184:187], v[72:75]
	s_waitcnt lgkmcnt(0)
	v_mfma_f32_16x16x32_bf16 v[44:47], v[112:115], v[200:203], v[44:47]
	global_load_dwordx4 v[112:115], v[116:117], off offset:64
	s_nop 0
	global_load_dwordx4 v[116:119], v[124:125], off offset:64
	v_mfma_f32_16x16x32_bf16 v[40:43], v[120:123], v[200:203], v[40:43]
	global_load_dwordx4 v[120:123], v[126:127], off offset:64
	s_nop 0
	global_load_dwordx4 v[124:127], v[136:137], off offset:64
	s_nop 0
	global_load_dwordx4 v[136:139], v[138:139], off offset:64
	v_mfma_f32_16x16x32_bf16 v[132:135], v[140:143], v[172:175], v[132:135]
	v_mfma_f32_16x16x32_bf16 v[96:99], v[140:143], v[176:179], v[96:99]
	v_mfma_f32_16x16x32_bf16 v[64:67], v[140:143], v[184:187], v[64:67]
	v_mfma_f32_16x16x32_bf16 v[32:35], v[140:143], v[200:203], v[32:35]
	global_load_dwordx4 v[140:143], v[204:205], off offset:64
	v_mfma_f32_16x16x32_bf16 v[128:131], v[180:183], v[172:175], v[128:131]
	v_mfma_f32_16x16x32_bf16 v[88:91], v[180:183], v[176:179], v[88:91]
	v_mfma_f32_16x16x32_bf16 v[56:59], v[180:183], v[184:187], v[56:59]
	v_mfma_f32_16x16x32_bf16 v[24:27], v[180:183], v[200:203], v[24:27]
	ds_read_b128 v[180:183], v168 offset:18432
	ds_read_b128 v[204:207], v168 offset:19968
	ds_read_b128 v[208:211], v168 offset:21504
	ds_read_b128 v[212:215], v168 offset:23040
	s_waitcnt lgkmcnt(3)
	v_mfma_f32_16x16x32_bf16 v[100:103], v[180:183], v[172:175], v[100:103]
	s_waitcnt lgkmcnt(2)
	v_mfma_f32_16x16x32_bf16 v[92:95], v[204:207], v[172:175], v[92:95]
	s_waitcnt lgkmcnt(1)
	v_mfma_f32_16x16x32_bf16 v[84:87], v[208:211], v[172:175], v[84:87]
	s_waitcnt lgkmcnt(0)
	s_barrier
	v_mfma_f32_16x16x32_bf16 v[80:83], v[212:215], v[172:175], v[80:83]
	v_mfma_f32_16x16x32_bf16 v[68:71], v[180:183], v[176:179], v[68:71]
	v_mfma_f32_16x16x32_bf16 v[60:63], v[204:207], v[176:179], v[60:63]
	v_mfma_f32_16x16x32_bf16 v[52:55], v[208:211], v[176:179], v[52:55]
	v_mfma_f32_16x16x32_bf16 v[48:51], v[212:215], v[176:179], v[48:51]
	v_mfma_f32_16x16x32_bf16 v[36:39], v[180:183], v[184:187], v[36:39]
	v_mfma_f32_16x16x32_bf16 v[28:31], v[204:207], v[184:187], v[28:31]
	v_mfma_f32_16x16x32_bf16 v[20:23], v[208:211], v[184:187], v[20:23]
	v_mfma_f32_16x16x32_bf16 v[16:19], v[212:215], v[184:187], v[16:19]
	v_mfma_f32_16x16x32_bf16 v[12:15], v[180:183], v[200:203], v[12:15]
	v_mfma_f32_16x16x32_bf16 v[8:11], v[204:207], v[200:203], v[8:11]
	v_mfma_f32_16x16x32_bf16 v[4:7], v[208:211], v[200:203], v[4:7]
	v_mfma_f32_16x16x32_bf16 v[0:3], v[212:215], v[200:203], v[0:3]
	s_add_u32 s0, s0, 64
	s_addc_u32 s1, s1, 0
	s_cmpk_lg_i32 s0, 0x1fc0
	s_cbranch_scc1 .LBB0_1113
	s_waitcnt vmcnt(5)
	ds_write_b128 v158, v[112:115]
	s_waitcnt vmcnt(4)
	ds_write_b128 v158, v[116:119] offset:6144
	s_waitcnt vmcnt(3)
	ds_write_b128 v158, v[120:123] offset:12288
	s_waitcnt vmcnt(2)
	ds_write_b128 v158, v[124:127] offset:18432
	s_waitcnt vmcnt(1)
	ds_write_b128 v158, v[136:139] offset:24576
	s_waitcnt vmcnt(0)
	ds_write_b128 v158, v[140:143] offset:30720
	s_waitcnt lgkmcnt(0)
	s_barrier
	ds_read_b128 v[112:115], v168 offset:12288
	ds_read_b128 v[116:119], v168 offset:13824
	ds_read_b128 v[120:123], v167
	ds_read_b128 v[124:127], v167 offset:1536
	s_waitcnt lgkmcnt(1)
	v_mfma_f32_16x16x32_bf16 v[136:139], v[112:115], v[120:123], v[148:151]
	ds_read_b128 v[140:143], v168 offset:15360
	s_nop 1
	ds_read_b128 v[148:151], v168 offset:16896
	ds_read_b128 v[162:165], v167 offset:3072
	ds_read_b128 v[172:175], v167 offset:4608
	v_mfma_f32_16x16x32_bf16 v[144:147], v[116:119], v[120:123], v[144:147]
	s_waitcnt lgkmcnt(3)
	v_mfma_f32_16x16x32_bf16 v[132:135], v[140:143], v[120:123], v[132:135]
	s_waitcnt lgkmcnt(2)
	v_mfma_f32_16x16x32_bf16 v[128:131], v[148:151], v[120:123], v[128:131]
	v_mfma_f32_16x16x32_bf16 v[108:111], v[112:115], v[124:127], v[108:111]
	v_mfma_f32_16x16x32_bf16 v[104:107], v[116:119], v[124:127], v[104:107]
	v_mfma_f32_16x16x32_bf16 v[96:99], v[140:143], v[124:127], v[96:99]
	v_mfma_f32_16x16x32_bf16 v[88:91], v[148:151], v[124:127], v[88:91]
	s_waitcnt lgkmcnt(1)
	v_mfma_f32_16x16x32_bf16 v[76:79], v[112:115], v[162:165], v[76:79]
	v_mfma_f32_16x16x32_bf16 v[72:75], v[116:119], v[162:165], v[72:75]
	v_mfma_f32_16x16x32_bf16 v[64:67], v[140:143], v[162:165], v[64:67]
	v_mfma_f32_16x16x32_bf16 v[56:59], v[148:151], v[162:165], v[56:59]
	s_waitcnt lgkmcnt(0)
	v_mfma_f32_16x16x32_bf16 v[44:47], v[112:115], v[172:175], v[44:47]
	v_mfma_f32_16x16x32_bf16 v[40:43], v[116:119], v[172:175], v[40:43]
	v_mfma_f32_16x16x32_bf16 v[32:35], v[140:143], v[172:175], v[32:35]
	v_mfma_f32_16x16x32_bf16 v[24:27], v[148:151], v[172:175], v[24:27]
	ds_read_b128 v[112:115], v168 offset:18432
	ds_read_b128 v[116:119], v168 offset:19968
	ds_read_b128 v[140:143], v168 offset:21504
	ds_read_b128 v[148:151], v168 offset:23040
	s_waitcnt lgkmcnt(3)
	v_mfma_f32_16x16x32_bf16 v[100:103], v[112:115], v[120:123], v[100:103]
	s_waitcnt lgkmcnt(2)
	v_mfma_f32_16x16x32_bf16 v[92:95], v[116:119], v[120:123], v[92:95]
	s_waitcnt lgkmcnt(1)
	v_mfma_f32_16x16x32_bf16 v[84:87], v[140:143], v[120:123], v[84:87]
	s_waitcnt lgkmcnt(0)
	v_mfma_f32_16x16x32_bf16 v[80:83], v[148:151], v[120:123], v[80:83]
	v_mfma_f32_16x16x32_bf16 v[68:71], v[112:115], v[124:127], v[68:71]
	v_mfma_f32_16x16x32_bf16 v[60:63], v[116:119], v[124:127], v[60:63]
	v_mfma_f32_16x16x32_bf16 v[52:55], v[140:143], v[124:127], v[52:55]
	v_mfma_f32_16x16x32_bf16 v[48:51], v[148:151], v[124:127], v[48:51]
	v_mfma_f32_16x16x32_bf16 v[36:39], v[112:115], v[162:165], v[36:39]
	v_mfma_f32_16x16x32_bf16 v[28:31], v[116:119], v[162:165], v[28:31]
	v_mfma_f32_16x16x32_bf16 v[20:23], v[140:143], v[162:165], v[20:23]
	v_mfma_f32_16x16x32_bf16 v[16:19], v[148:151], v[162:165], v[16:19]
	v_mfma_f32_16x16x32_bf16 v[12:15], v[112:115], v[172:175], v[12:15]
	v_mfma_f32_16x16x32_bf16 v[8:11], v[116:119], v[172:175], v[8:11]
	v_mfma_f32_16x16x32_bf16 v[4:7], v[140:143], v[172:175], v[4:7]
	v_mfma_f32_16x16x32_bf16 v[0:3], v[148:151], v[172:175], v[0:3]
	v_or_b32_e32 v112, s3, v159
	v_add_u32_e32 v112, v112, v169
	v_ashrrev_i32_e32 v113, 31, v112
	v_or_b32_e32 v116, s4, v170
	v_lshlrev_b64 v[114:115], 13, v[112:113]
	v_lshl_add_u64 v[114:115], s[62:63], 0, v[114:115]
	v_lshlrev_b32_e32 v152, 2, v116
	v_lshl_add_u64 v[114:115], v[114:115], 0, v[152:153]
	s_barrier
	global_store_dwordx4 v[114:115], v[136:139], off
	global_store_dwordx4 v[114:115], v[144:147], off offset:64
	global_store_dwordx4 v[114:115], v[132:135], off offset:128
	global_store_dwordx4 v[114:115], v[128:131], off offset:192
	global_store_dwordx4 v[114:115], v[100:103], off offset:256
	global_store_dwordx4 v[114:115], v[92:95], off offset:320
	global_store_dwordx4 v[114:115], v[84:87], off offset:384
	global_store_dwordx4 v[114:115], v[80:83], off offset:448
	s_add_i32 s2, s2, s33
	s_cmpk_lt_i32 s2, 0x600
	v_or_b32_e32 v80, 16, v112
	v_ashrrev_i32_e32 v81, 31, v80
	v_lshlrev_b64 v[80:81], 13, v[80:81]
	v_lshl_add_u64 v[80:81], s[62:63], 0, v[80:81]
	v_lshl_add_u64 v[80:81], v[80:81], 0, v[152:153]
	global_store_dwordx4 v[80:81], v[108:111], off
	global_store_dwordx4 v[80:81], v[104:107], off offset:64
	global_store_dwordx4 v[80:81], v[96:99], off offset:128
	global_store_dwordx4 v[80:81], v[88:91], off offset:192
	global_store_dwordx4 v[80:81], v[68:71], off offset:256
	global_store_dwordx4 v[80:81], v[60:63], off offset:320
	global_store_dwordx4 v[80:81], v[52:55], off offset:384
	global_store_dwordx4 v[80:81], v[48:51], off offset:448
	s_nop 1
	v_or_b32_e32 v48, 32, v112
	v_ashrrev_i32_e32 v49, 31, v48
	v_lshlrev_b64 v[48:49], 13, v[48:49]
	v_lshl_add_u64 v[48:49], s[62:63], 0, v[48:49]
	v_lshl_add_u64 v[48:49], v[48:49], 0, v[152:153]
	global_store_dwordx4 v[48:49], v[76:79], off
	global_store_dwordx4 v[48:49], v[72:75], off offset:64
	global_store_dwordx4 v[48:49], v[64:67], off offset:128
	global_store_dwordx4 v[48:49], v[56:59], off offset:192
	global_store_dwordx4 v[48:49], v[36:39], off offset:256
	global_store_dwordx4 v[48:49], v[28:31], off offset:320
	global_store_dwordx4 v[48:49], v[20:23], off offset:384
	global_store_dwordx4 v[48:49], v[16:19], off offset:448
	s_nop 1
	v_or_b32_e32 v16, 48, v112
	v_ashrrev_i32_e32 v17, 31, v16
	v_lshlrev_b64 v[16:17], 13, v[16:17]
	v_lshl_add_u64 v[16:17], s[62:63], 0, v[16:17]
	v_lshl_add_u64 v[16:17], v[16:17], 0, v[152:153]
	global_store_dwordx4 v[16:17], v[44:47], off
	global_store_dwordx4 v[16:17], v[40:43], off offset:64
	global_store_dwordx4 v[16:17], v[32:35], off offset:128
	global_store_dwordx4 v[16:17], v[24:27], off offset:192
	global_store_dwordx4 v[16:17], v[12:15], off offset:256
	global_store_dwordx4 v[16:17], v[8:11], off offset:320
	global_store_dwordx4 v[16:17], v[4:7], off offset:384
	global_store_dwordx4 v[16:17], v[0:3], off offset:448
	s_cbranch_scc1 .LBB0_1108
